# v34 + remaining 8 LDS-DMA loads per iteration also SGPR-based (chained K-tile+1 addresses via two SALU adds into s[100:101]); no VALU address adds left in the K-loops
# speedup vs baseline: 1.0046x; 1.0002x over previous
.LBB0_394:
	s_add_u32 s0, s24, 0xfff80080
	s_addc_u32 s1, s25, -1
	s_add_i32 s33, 0, 0x10000
	s_cmp_eq_u32 s60, 28
	s_cselect_b32 s29, s7, s1
	s_cselect_b32 s28, s19, s0
	s_cselect_b32 s27, s17, s59
	s_cselect_b32 s26, s49, s58
	s_add_i32 s55, 0, 0x14000
	v_add_u32_e32 v158, s33, v151
	v_add_u32_e32 v174, s55, v151
	ds_read_b128 v[142:145], v158
	ds_read_b128 v[146:149], v158 offset:1024
	ds_read_b128 v[154:157], v158 offset:2048
	ds_read_b128 v[158:161], v158 offset:3072
	ds_read_b128 v[162:165], v174
	ds_read_b128 v[166:169], v174 offset:1024
	ds_read_b128 v[170:173], v174 offset:2048
	ds_read_b128 v[174:177], v174 offset:3072
	s_add_i32 m0, s9, 0xc000
	ds_read_b128 v[178:181], v153
	ds_read_b128 v[182:185], v153 offset:1024
	ds_read_b128 v[186:189], v153 offset:2048
	ds_read_b128 v[190:193], v153 offset:3072
	ds_read_b128 v[194:197], v153 offset:4096
	ds_read_b128 v[198:201], v153 offset:5120
	ds_read_b128 v[208:211], v153 offset:6144
	ds_read_b128 v[212:215], v153 offset:7168
	global_load_lds_dwordx4 v138, s[24:25]
	s_add_i32 m0, s9, 0xe000
	s_nop 0
	global_load_lds_dwordx4 v140, s[24:25]
	s_waitcnt vmcnt(8)
	s_waitcnt lgkmcnt(0)
	s_setprio 1
	s_barrier
	v_mfma_f32_16x16x32_bf16 v[126:129], v[142:145], v[178:181], v[126:129]
	v_mfma_f32_16x16x32_bf16 v[122:125], v[154:157], v[178:181], v[122:125]
	v_mfma_f32_16x16x32_bf16 v[110:113], v[142:145], v[186:189], v[110:113]
	v_mfma_f32_16x16x32_bf16 v[106:109], v[154:157], v[186:189], v[106:109]
	v_mfma_f32_16x16x32_bf16 v[94:97], v[142:145], v[194:197], v[94:97]
	v_mfma_f32_16x16x32_bf16 v[90:93], v[154:157], v[194:197], v[90:93]
	v_mfma_f32_16x16x32_bf16 v[78:81], v[142:145], v[208:211], v[78:81]
	v_mfma_f32_16x16x32_bf16 v[74:77], v[154:157], v[208:211], v[74:77]
	v_mfma_f32_16x16x32_bf16 v[126:129], v[146:149], v[182:185], v[126:129]
	v_mfma_f32_16x16x32_bf16 v[122:125], v[158:161], v[182:185], v[122:125]
	v_mfma_f32_16x16x32_bf16 v[110:113], v[146:149], v[190:193], v[110:113]
	v_mfma_f32_16x16x32_bf16 v[106:109], v[158:161], v[190:193], v[106:109]
	v_mfma_f32_16x16x32_bf16 v[94:97], v[146:149], v[198:201], v[94:97]
	v_mfma_f32_16x16x32_bf16 v[90:93], v[158:161], v[198:201], v[90:93]
	v_mfma_f32_16x16x32_bf16 v[78:81], v[146:149], v[212:215], v[78:81]
	v_mfma_f32_16x16x32_bf16 v[74:77], v[158:161], v[212:215], v[74:77]
	s_setprio 0
	s_setprio 1
	v_mfma_f32_16x16x32_bf16 v[118:121], v[162:165], v[178:181], v[118:121]
	v_mfma_f32_16x16x32_bf16 v[114:117], v[170:173], v[178:181], v[114:117]
	v_mfma_f32_16x16x32_bf16 v[102:105], v[162:165], v[186:189], v[102:105]
	v_mfma_f32_16x16x32_bf16 v[98:101], v[170:173], v[186:189], v[98:101]
	v_mfma_f32_16x16x32_bf16 v[86:89], v[162:165], v[194:197], v[86:89]
	v_mfma_f32_16x16x32_bf16 v[82:85], v[170:173], v[194:197], v[82:85]
	v_mfma_f32_16x16x32_bf16 v[70:73], v[162:165], v[208:211], v[70:73]
	v_mfma_f32_16x16x32_bf16 v[66:69], v[170:173], v[208:211], v[66:69]
	v_mfma_f32_16x16x32_bf16 v[118:121], v[166:169], v[182:185], v[118:121]
	v_mfma_f32_16x16x32_bf16 v[114:117], v[174:177], v[182:185], v[114:117]
	v_mfma_f32_16x16x32_bf16 v[102:105], v[166:169], v[190:193], v[102:105]
	v_mfma_f32_16x16x32_bf16 v[98:101], v[174:177], v[190:193], v[98:101]
	v_mfma_f32_16x16x32_bf16 v[86:89], v[166:169], v[198:201], v[86:89]
	v_mfma_f32_16x16x32_bf16 v[82:85], v[174:177], v[198:201], v[82:85]
	v_mfma_f32_16x16x32_bf16 v[70:73], v[166:169], v[212:215], v[70:73]
	v_mfma_f32_16x16x32_bf16 v[66:69], v[174:177], v[212:215], v[66:69]
	s_barrier
	s_setprio 0
	s_add_i32 s0, s33, s34
	s_mov_b32 m0, s0
	ds_read_b128 v[178:181], v153 offset:16384
	ds_read_b128 v[182:185], v153 offset:17408
	ds_read_b128 v[186:189], v153 offset:18432
	ds_read_b128 v[190:193], v153 offset:19456
	ds_read_b128 v[194:197], v153 offset:20480
	ds_read_b128 v[198:201], v153 offset:21504
	ds_read_b128 v[208:211], v153 offset:22528
	ds_read_b128 v[212:215], v153 offset:23552
	global_load_lds_dwordx4 v132, s[26:27]
	s_add_i32 m0, s0, 0x2000
	s_add_u32 s0, s26, 0x80000
	s_addc_u32 s1, s27, 0
	s_add_i32 s33, s55, s34
	global_load_lds_dwordx4 v136, s[26:27]
	s_mov_b32 m0, s33
	s_nop 0
	global_load_lds_dwordx4 v132, s[0:1]
	s_add_i32 m0, s33, 0x2000
	s_nop 0
	global_load_lds_dwordx4 v136, s[0:1]
	s_mov_b32 m0, s9
	s_nop 0
	global_load_lds_dwordx4 v130, s[28:29]
	s_mov_b32 m0, s35
	s_nop 0
	global_load_lds_dwordx4 v134, s[28:29]
	s_waitcnt vmcnt(8)
	s_waitcnt lgkmcnt(0)
	s_setprio 1
	s_barrier
	v_mfma_f32_16x16x32_bf16 v[62:65], v[142:145], v[178:181], v[62:65]
	v_mfma_f32_16x16x32_bf16 v[58:61], v[154:157], v[178:181], v[58:61]
	v_mfma_f32_16x16x32_bf16 v[46:49], v[142:145], v[186:189], v[46:49]
	v_mfma_f32_16x16x32_bf16 v[42:45], v[154:157], v[186:189], v[42:45]
	v_mfma_f32_16x16x32_bf16 v[30:33], v[142:145], v[194:197], v[30:33]
	v_mfma_f32_16x16x32_bf16 v[26:29], v[154:157], v[194:197], v[26:29]
	v_mfma_f32_16x16x32_bf16 v[14:17], v[142:145], v[208:211], v[14:17]
	v_mfma_f32_16x16x32_bf16 v[10:13], v[154:157], v[208:211], v[10:13]
	v_mfma_f32_16x16x32_bf16 v[62:65], v[146:149], v[182:185], v[62:65]
	v_mfma_f32_16x16x32_bf16 v[58:61], v[158:161], v[182:185], v[58:61]
	v_mfma_f32_16x16x32_bf16 v[46:49], v[146:149], v[190:193], v[46:49]
	v_mfma_f32_16x16x32_bf16 v[42:45], v[158:161], v[190:193], v[42:45]
	v_mfma_f32_16x16x32_bf16 v[30:33], v[146:149], v[198:201], v[30:33]
	v_mfma_f32_16x16x32_bf16 v[26:29], v[158:161], v[198:201], v[26:29]
	v_mfma_f32_16x16x32_bf16 v[14:17], v[146:149], v[212:215], v[14:17]
	v_mfma_f32_16x16x32_bf16 v[10:13], v[158:161], v[212:215], v[10:13]
	s_setprio 0
	s_setprio 1
	v_mfma_f32_16x16x32_bf16 v[54:57], v[162:165], v[178:181], v[54:57]
	v_mfma_f32_16x16x32_bf16 v[50:53], v[170:173], v[178:181], v[50:53]
	v_mfma_f32_16x16x32_bf16 v[38:41], v[162:165], v[186:189], v[38:41]
	v_mfma_f32_16x16x32_bf16 v[34:37], v[170:173], v[186:189], v[34:37]
	v_mfma_f32_16x16x32_bf16 v[22:25], v[162:165], v[194:197], v[22:25]
	v_mfma_f32_16x16x32_bf16 v[18:21], v[170:173], v[194:197], v[18:21]
	v_mfma_f32_16x16x32_bf16 v[6:9], v[162:165], v[208:211], v[6:9]
	v_mfma_f32_16x16x32_bf16 v[2:5], v[170:173], v[208:211], v[2:5]
	v_mfma_f32_16x16x32_bf16 v[54:57], v[166:169], v[182:185], v[54:57]
	v_mfma_f32_16x16x32_bf16 v[50:53], v[174:177], v[182:185], v[50:53]
	v_mfma_f32_16x16x32_bf16 v[38:41], v[166:169], v[190:193], v[38:41]
	v_mfma_f32_16x16x32_bf16 v[34:37], v[174:177], v[190:193], v[34:37]
	v_mfma_f32_16x16x32_bf16 v[22:25], v[166:169], v[198:201], v[22:25]
	v_mfma_f32_16x16x32_bf16 v[18:21], v[174:177], v[198:201], v[18:21]
	v_mfma_f32_16x16x32_bf16 v[6:9], v[166:169], v[212:215], v[6:9]
	v_mfma_f32_16x16x32_bf16 v[2:5], v[174:177], v[212:215], v[2:5]
	s_barrier
	s_setprio 0
	s_add_i32 s33, 0, 0x18000
	s_add_i32 s55, 0, 0x1c000
	v_add_u32_e32 v158, s33, v151
	v_add_u32_e32 v174, s55, v151
	ds_read_b128 v[142:145], v158
	ds_read_b128 v[146:149], v158 offset:1024
	ds_read_b128 v[154:157], v158 offset:2048
	ds_read_b128 v[158:161], v158 offset:3072
	ds_read_b128 v[162:165], v174
	ds_read_b128 v[166:169], v174 offset:1024
	ds_read_b128 v[170:173], v174 offset:2048
	ds_read_b128 v[174:177], v174 offset:3072
	s_add_u32 s0, s28, 0x80000
	s_addc_u32 s1, s29, 0
	s_mov_b32 m0, s36
	ds_read_b128 v[178:181], v153 offset:32768
	ds_read_b128 v[182:185], v153 offset:33792
	ds_read_b128 v[186:189], v153 offset:34816
	ds_read_b128 v[190:193], v153 offset:35840
	ds_read_b128 v[194:197], v153 offset:36864
	ds_read_b128 v[198:201], v153 offset:37888
	ds_read_b128 v[208:211], v153 offset:38912
	ds_read_b128 v[212:215], v153 offset:39936
	global_load_lds_dwordx4 v130, s[0:1]
	s_mov_b32 m0, s37
	s_nop 0
	global_load_lds_dwordx4 v134, s[0:1]
	s_waitcnt vmcnt(8)
	s_waitcnt lgkmcnt(0)
	s_setprio 1
	s_barrier
	v_mfma_f32_16x16x32_bf16 v[126:129], v[142:145], v[178:181], v[126:129]
	v_mfma_f32_16x16x32_bf16 v[122:125], v[154:157], v[178:181], v[122:125]
	v_mfma_f32_16x16x32_bf16 v[110:113], v[142:145], v[186:189], v[110:113]
	v_mfma_f32_16x16x32_bf16 v[106:109], v[154:157], v[186:189], v[106:109]
	v_mfma_f32_16x16x32_bf16 v[94:97], v[142:145], v[194:197], v[94:97]
	v_mfma_f32_16x16x32_bf16 v[90:93], v[154:157], v[194:197], v[90:93]
	v_mfma_f32_16x16x32_bf16 v[78:81], v[142:145], v[208:211], v[78:81]
	v_mfma_f32_16x16x32_bf16 v[74:77], v[154:157], v[208:211], v[74:77]
	v_mfma_f32_16x16x32_bf16 v[126:129], v[146:149], v[182:185], v[126:129]
	v_mfma_f32_16x16x32_bf16 v[122:125], v[158:161], v[182:185], v[122:125]
	v_mfma_f32_16x16x32_bf16 v[110:113], v[146:149], v[190:193], v[110:113]
	v_mfma_f32_16x16x32_bf16 v[106:109], v[158:161], v[190:193], v[106:109]
	v_mfma_f32_16x16x32_bf16 v[94:97], v[146:149], v[198:201], v[94:97]
	v_mfma_f32_16x16x32_bf16 v[90:93], v[158:161], v[198:201], v[90:93]
	v_mfma_f32_16x16x32_bf16 v[78:81], v[146:149], v[212:215], v[78:81]
	v_mfma_f32_16x16x32_bf16 v[74:77], v[158:161], v[212:215], v[74:77]
	s_setprio 0
	s_setprio 1
	v_mfma_f32_16x16x32_bf16 v[118:121], v[162:165], v[178:181], v[118:121]
	v_mfma_f32_16x16x32_bf16 v[114:117], v[170:173], v[178:181], v[114:117]
	v_mfma_f32_16x16x32_bf16 v[102:105], v[162:165], v[186:189], v[102:105]
	v_mfma_f32_16x16x32_bf16 v[98:101], v[170:173], v[186:189], v[98:101]
	v_mfma_f32_16x16x32_bf16 v[86:89], v[162:165], v[194:197], v[86:89]
	v_mfma_f32_16x16x32_bf16 v[82:85], v[170:173], v[194:197], v[82:85]
	v_mfma_f32_16x16x32_bf16 v[70:73], v[162:165], v[208:211], v[70:73]
	v_mfma_f32_16x16x32_bf16 v[66:69], v[170:173], v[208:211], v[66:69]
	v_mfma_f32_16x16x32_bf16 v[118:121], v[166:169], v[182:185], v[118:121]
	v_mfma_f32_16x16x32_bf16 v[114:117], v[174:177], v[182:185], v[114:117]
	v_mfma_f32_16x16x32_bf16 v[102:105], v[166:169], v[190:193], v[102:105]
	v_mfma_f32_16x16x32_bf16 v[98:101], v[174:177], v[190:193], v[98:101]
	v_mfma_f32_16x16x32_bf16 v[86:89], v[166:169], v[198:201], v[86:89]
	v_mfma_f32_16x16x32_bf16 v[82:85], v[174:177], v[198:201], v[82:85]
	v_mfma_f32_16x16x32_bf16 v[70:73], v[166:169], v[212:215], v[70:73]
	v_mfma_f32_16x16x32_bf16 v[66:69], v[174:177], v[212:215], v[66:69]
	s_barrier
	s_setprio 0
	s_add_i32 s0, s33, s34
	s_add_u32 s100, s26, 0x80
	s_addc_u32 s101, s27, 0
	s_mov_b32 m0, s0
	ds_read_b128 v[178:181], v153 offset:49152
	ds_read_b128 v[182:185], v153 offset:50176
	ds_read_b128 v[186:189], v153 offset:51200
	ds_read_b128 v[190:193], v153 offset:52224
	ds_read_b128 v[194:197], v153 offset:53248
	ds_read_b128 v[198:201], v153 offset:54272
	ds_read_b128 v[208:211], v153 offset:55296
	ds_read_b128 v[212:215], v153 offset:56320
	global_load_lds_dwordx4 v132, s[100:101]
	s_add_i32 m0, s0, 0x2000
	s_add_u32 s100, s26, 0x80
	s_addc_u32 s101, s27, 0
	s_add_u32 s0, s26, 0x80080
	s_addc_u32 s1, s27, 0
	s_add_i32 s26, s55, s34
	global_load_lds_dwordx4 v136, s[100:101]
	s_mov_b32 m0, s26
	s_nop 0
	global_load_lds_dwordx4 v132, s[0:1]
	s_add_i32 m0, s26, 0x2000
	s_nop 0
	global_load_lds_dwordx4 v136, s[0:1]
	s_add_u32 s100, s28, 0x80
	s_addc_u32 s101, s29, 0
	s_mov_b32 m0, s39
	s_nop 0
	global_load_lds_dwordx4 v130, s[100:101]
	s_add_u32 s100, s28, 0x80
	s_addc_u32 s101, s29, 0
	s_mov_b32 m0, s40
	s_nop 0
	global_load_lds_dwordx4 v134, s[100:101]
	s_waitcnt vmcnt(8)
	s_waitcnt lgkmcnt(0)
	s_setprio 1
	s_barrier
	v_mfma_f32_16x16x32_bf16 v[62:65], v[142:145], v[178:181], v[62:65]
	v_mfma_f32_16x16x32_bf16 v[58:61], v[154:157], v[178:181], v[58:61]
	v_mfma_f32_16x16x32_bf16 v[46:49], v[142:145], v[186:189], v[46:49]
	v_mfma_f32_16x16x32_bf16 v[42:45], v[154:157], v[186:189], v[42:45]
	v_mfma_f32_16x16x32_bf16 v[30:33], v[142:145], v[194:197], v[30:33]
	v_mfma_f32_16x16x32_bf16 v[26:29], v[154:157], v[194:197], v[26:29]
	v_mfma_f32_16x16x32_bf16 v[14:17], v[142:145], v[208:211], v[14:17]
	v_mfma_f32_16x16x32_bf16 v[10:13], v[154:157], v[208:211], v[10:13]
	v_mfma_f32_16x16x32_bf16 v[62:65], v[146:149], v[182:185], v[62:65]
	v_mfma_f32_16x16x32_bf16 v[58:61], v[158:161], v[182:185], v[58:61]
	v_mfma_f32_16x16x32_bf16 v[46:49], v[146:149], v[190:193], v[46:49]
	v_mfma_f32_16x16x32_bf16 v[42:45], v[158:161], v[190:193], v[42:45]
	v_mfma_f32_16x16x32_bf16 v[30:33], v[146:149], v[198:201], v[30:33]
	v_mfma_f32_16x16x32_bf16 v[26:29], v[158:161], v[198:201], v[26:29]
	v_mfma_f32_16x16x32_bf16 v[14:17], v[146:149], v[212:215], v[14:17]
	v_mfma_f32_16x16x32_bf16 v[10:13], v[158:161], v[212:215], v[10:13]
	s_setprio 0
	s_setprio 1
	v_mfma_f32_16x16x32_bf16 v[54:57], v[162:165], v[178:181], v[54:57]
	v_mfma_f32_16x16x32_bf16 v[50:53], v[170:173], v[178:181], v[50:53]
	v_mfma_f32_16x16x32_bf16 v[38:41], v[162:165], v[186:189], v[38:41]
	v_mfma_f32_16x16x32_bf16 v[34:37], v[170:173], v[186:189], v[34:37]
	v_mfma_f32_16x16x32_bf16 v[22:25], v[162:165], v[194:197], v[22:25]
	v_mfma_f32_16x16x32_bf16 v[18:21], v[170:173], v[194:197], v[18:21]
	v_mfma_f32_16x16x32_bf16 v[6:9], v[162:165], v[208:211], v[6:9]
	v_mfma_f32_16x16x32_bf16 v[2:5], v[170:173], v[208:211], v[2:5]
	v_mfma_f32_16x16x32_bf16 v[54:57], v[166:169], v[182:185], v[54:57]
	v_mfma_f32_16x16x32_bf16 v[50:53], v[174:177], v[182:185], v[50:53]
	v_mfma_f32_16x16x32_bf16 v[38:41], v[166:169], v[190:193], v[38:41]
	v_mfma_f32_16x16x32_bf16 v[34:37], v[174:177], v[190:193], v[34:37]
	v_mfma_f32_16x16x32_bf16 v[22:25], v[166:169], v[198:201], v[22:25]
	v_mfma_f32_16x16x32_bf16 v[18:21], v[174:177], v[198:201], v[18:21]
	v_mfma_f32_16x16x32_bf16 v[6:9], v[166:169], v[212:215], v[6:9]
	v_mfma_f32_16x16x32_bf16 v[2:5], v[174:177], v[212:215], v[2:5]
	s_barrier
	s_setprio 0
	s_add_i32 s60, s60, 2
	s_add_u32 s24, s24, 0x100
	s_addc_u32 s25, s25, 0
	s_add_u32 s58, s58, 0x100
	s_addc_u32 s59, s59, 0
	s_cmp_gt_u32 s60, 29
	s_cbranch_scc0 .LBB0_394
	s_and_b64 vcc, exec, s[14:15]
	s_cbranch_vccz .LBB0_397
	s_barrier

.LBB0_692:
	s_add_u32 s0, s18, 0xfff00080
	s_addc_u32 s1, s19, -1
	s_add_i32 s33, 0, 0x10000
	s_cmp_eq_u32 s61, 60
	s_cselect_b32 s23, s11, s1
	s_cselect_b32 s22, s49, s0
	s_cselect_b32 s21, s9, s60
	s_cselect_b32 s20, s58, s59
	s_add_i32 s55, 0, 0x14000
	v_add_u32_e32 v98, s33, v205
	v_add_u32_e32 v134, s55, v205
	ds_read_b128 v[78:81], v98
	ds_read_b128 v[86:89], v98 offset:1024
	ds_read_b128 v[94:97], v98 offset:2048
	ds_read_b128 v[98:101], v98 offset:3072
	ds_read_b128 v[106:109], v134
	ds_read_b128 v[110:113], v134 offset:1024
	ds_read_b128 v[126:129], v134 offset:2048
	ds_read_b128 v[134:137], v134 offset:3072
	s_add_i32 m0, s27, 0xc000
	ds_read_b128 v[146:149], v239
	ds_read_b128 v[158:161], v239 offset:1024
	ds_read_b128 v[166:169], v239 offset:2048
	ds_read_b128 v[174:177], v239 offset:3072
	ds_read_b128 v[178:181], v239 offset:4096
	ds_read_b128 v[182:185], v239 offset:5120
	ds_read_b128 v[186:189], v239 offset:6144
	ds_read_b128 v[190:193], v239 offset:7168
	global_load_lds_dwordx4 v214, s[18:19]
	s_add_i32 m0, s27, 0xe000
	s_nop 0
	global_load_lds_dwordx4 v216, s[18:19]
	s_waitcnt vmcnt(8)
	s_waitcnt lgkmcnt(0)
	s_setprio 1
	s_barrier
	v_mfma_f32_16x16x32_bf16 v[170:173], v[78:81], v[146:149], v[170:173]
	v_mfma_f32_16x16x32_bf16 v[162:165], v[94:97], v[146:149], v[162:165]
	v_mfma_f32_16x16x32_bf16 v[142:145], v[78:81], v[166:169], v[142:145]
	v_mfma_f32_16x16x32_bf16 v[138:141], v[94:97], v[166:169], v[138:141]
	v_mfma_f32_16x16x32_bf16 v[118:121], v[78:81], v[178:181], v[118:121]
	v_mfma_f32_16x16x32_bf16 v[114:117], v[94:97], v[178:181], v[114:117]
	v_mfma_f32_16x16x32_bf16 v[82:85], v[78:81], v[186:189], v[82:85]
	v_mfma_f32_16x16x32_bf16 v[74:77], v[94:97], v[186:189], v[74:77]
	v_mfma_f32_16x16x32_bf16 v[170:173], v[86:89], v[158:161], v[170:173]
	v_mfma_f32_16x16x32_bf16 v[162:165], v[98:101], v[158:161], v[162:165]
	v_mfma_f32_16x16x32_bf16 v[142:145], v[86:89], v[174:177], v[142:145]
	v_mfma_f32_16x16x32_bf16 v[138:141], v[98:101], v[174:177], v[138:141]
	v_mfma_f32_16x16x32_bf16 v[118:121], v[86:89], v[182:185], v[118:121]
	v_mfma_f32_16x16x32_bf16 v[114:117], v[98:101], v[182:185], v[114:117]
	v_mfma_f32_16x16x32_bf16 v[82:85], v[86:89], v[190:193], v[82:85]
	v_mfma_f32_16x16x32_bf16 v[74:77], v[98:101], v[190:193], v[74:77]
	s_setprio 0
	s_setprio 1
	v_mfma_f32_16x16x32_bf16 v[154:157], v[106:109], v[146:149], v[154:157]
	v_mfma_f32_16x16x32_bf16 v[130:133], v[106:109], v[166:169], v[130:133]
	v_mfma_f32_16x16x32_bf16 v[122:125], v[126:129], v[166:169], v[122:125]
	v_mfma_f32_16x16x32_bf16 v[102:105], v[106:109], v[178:181], v[102:105]
	v_mfma_f32_16x16x32_bf16 v[90:93], v[126:129], v[178:181], v[90:93]
	v_mfma_f32_16x16x32_bf16 v[70:73], v[106:109], v[186:189], v[70:73]
	v_mfma_f32_16x16x32_bf16 v[66:69], v[126:129], v[186:189], v[66:69]
	v_mfma_f32_16x16x32_bf16 v[154:157], v[110:113], v[158:161], v[154:157]
	v_mfma_f32_16x16x32_bf16 v[146:149], v[126:129], v[146:149], v[150:153]
	v_mfma_f32_16x16x32_bf16 v[130:133], v[110:113], v[174:177], v[130:133]
	v_mfma_f32_16x16x32_bf16 v[122:125], v[134:137], v[174:177], v[122:125]
	v_mfma_f32_16x16x32_bf16 v[102:105], v[110:113], v[182:185], v[102:105]
	v_mfma_f32_16x16x32_bf16 v[90:93], v[134:137], v[182:185], v[90:93]
	v_mfma_f32_16x16x32_bf16 v[70:73], v[110:113], v[190:193], v[70:73]
	v_mfma_f32_16x16x32_bf16 v[66:69], v[134:137], v[190:193], v[66:69]
	v_mfma_f32_16x16x32_bf16 v[146:149], v[134:137], v[158:161], v[146:149]
	s_barrier
	s_setprio 0
	s_add_i32 s0, s33, s26
	s_mov_b32 m0, s0
	ds_read_b128 v[150:153], v239 offset:16384
	ds_read_b128 v[158:161], v239 offset:17408
	ds_read_b128 v[166:169], v239 offset:18432
	ds_read_b128 v[174:177], v239 offset:19456
	ds_read_b128 v[178:181], v239 offset:20480
	ds_read_b128 v[182:185], v239 offset:21504
	ds_read_b128 v[186:189], v239 offset:22528
	ds_read_b128 v[190:193], v239 offset:23552
	global_load_lds_dwordx4 v202, s[20:21]
	s_add_i32 m0, s0, 0x2000
	s_add_u32 s0, s20, 0x100000
	s_addc_u32 s1, s21, 0
	s_add_i32 s33, s55, s26
	global_load_lds_dwordx4 v208, s[20:21]
	s_mov_b32 m0, s33
	s_nop 0
	global_load_lds_dwordx4 v202, s[0:1]
	s_add_i32 m0, s33, 0x2000
	s_nop 0
	global_load_lds_dwordx4 v208, s[0:1]
	s_mov_b32 m0, s27
	s_nop 0
	global_load_lds_dwordx4 v212, s[22:23]
	s_mov_b32 m0, s28
	s_nop 0
	global_load_lds_dwordx4 v210, s[22:23]
	s_waitcnt vmcnt(8)
	s_waitcnt lgkmcnt(0)
	s_setprio 1
	s_barrier
	v_mfma_f32_16x16x32_bf16 v[62:65], v[78:81], v[150:153], v[62:65]
	v_mfma_f32_16x16x32_bf16 v[58:61], v[94:97], v[150:153], v[58:61]
	v_mfma_f32_16x16x32_bf16 v[46:49], v[78:81], v[166:169], v[46:49]
	v_mfma_f32_16x16x32_bf16 v[42:45], v[94:97], v[166:169], v[42:45]
	v_mfma_f32_16x16x32_bf16 v[30:33], v[78:81], v[178:181], v[30:33]
	v_mfma_f32_16x16x32_bf16 v[26:29], v[94:97], v[178:181], v[26:29]
	v_mfma_f32_16x16x32_bf16 v[14:17], v[78:81], v[186:189], v[14:17]
	v_mfma_f32_16x16x32_bf16 v[10:13], v[94:97], v[186:189], v[10:13]
	v_mfma_f32_16x16x32_bf16 v[62:65], v[86:89], v[158:161], v[62:65]
	v_mfma_f32_16x16x32_bf16 v[58:61], v[98:101], v[158:161], v[58:61]
	v_mfma_f32_16x16x32_bf16 v[46:49], v[86:89], v[174:177], v[46:49]
	v_mfma_f32_16x16x32_bf16 v[42:45], v[98:101], v[174:177], v[42:45]
	v_mfma_f32_16x16x32_bf16 v[30:33], v[86:89], v[182:185], v[30:33]
	v_mfma_f32_16x16x32_bf16 v[26:29], v[98:101], v[182:185], v[26:29]
	v_mfma_f32_16x16x32_bf16 v[14:17], v[86:89], v[190:193], v[14:17]
	v_mfma_f32_16x16x32_bf16 v[10:13], v[98:101], v[190:193], v[10:13]
	s_setprio 0
	s_setprio 1
	v_mfma_f32_16x16x32_bf16 v[54:57], v[106:109], v[150:153], v[54:57]
	v_mfma_f32_16x16x32_bf16 v[50:53], v[126:129], v[150:153], v[50:53]
	v_mfma_f32_16x16x32_bf16 v[38:41], v[106:109], v[166:169], v[38:41]
	v_mfma_f32_16x16x32_bf16 v[34:37], v[126:129], v[166:169], v[34:37]
	v_mfma_f32_16x16x32_bf16 v[22:25], v[106:109], v[178:181], v[22:25]
	v_mfma_f32_16x16x32_bf16 v[18:21], v[126:129], v[178:181], v[18:21]
	v_mfma_f32_16x16x32_bf16 v[6:9], v[106:109], v[186:189], v[6:9]
	v_mfma_f32_16x16x32_bf16 v[2:5], v[126:129], v[186:189], v[2:5]
	v_mfma_f32_16x16x32_bf16 v[54:57], v[110:113], v[158:161], v[54:57]
	v_mfma_f32_16x16x32_bf16 v[50:53], v[134:137], v[158:161], v[50:53]
	v_mfma_f32_16x16x32_bf16 v[38:41], v[110:113], v[174:177], v[38:41]
	v_mfma_f32_16x16x32_bf16 v[34:37], v[134:137], v[174:177], v[34:37]
	v_mfma_f32_16x16x32_bf16 v[22:25], v[110:113], v[182:185], v[22:25]
	v_mfma_f32_16x16x32_bf16 v[18:21], v[134:137], v[182:185], v[18:21]
	v_mfma_f32_16x16x32_bf16 v[6:9], v[110:113], v[190:193], v[6:9]
	v_mfma_f32_16x16x32_bf16 v[2:5], v[134:137], v[190:193], v[2:5]
	s_barrier
	s_setprio 0
	s_add_i32 s33, 0, 0x18000
	s_add_i32 s55, 0, 0x1c000
	v_add_u32_e32 v98, s33, v205
	v_add_u32_e32 v134, s55, v205
	ds_read_b128 v[78:81], v98
	ds_read_b128 v[86:89], v98 offset:1024
	ds_read_b128 v[94:97], v98 offset:2048
	ds_read_b128 v[98:101], v98 offset:3072
	ds_read_b128 v[106:109], v134
	ds_read_b128 v[110:113], v134 offset:1024
	ds_read_b128 v[126:129], v134 offset:2048
	ds_read_b128 v[134:137], v134 offset:3072
	s_add_u32 s0, s22, 0x100000
	s_addc_u32 s1, s23, 0
	s_mov_b32 m0, s29
	ds_read_b128 v[150:153], v239 offset:32768
	ds_read_b128 v[158:161], v239 offset:33792
	ds_read_b128 v[166:169], v239 offset:34816
	ds_read_b128 v[174:177], v239 offset:35840
	ds_read_b128 v[178:181], v239 offset:36864
	ds_read_b128 v[182:185], v239 offset:37888
	ds_read_b128 v[186:189], v239 offset:38912
	ds_read_b128 v[190:193], v239 offset:39936
	global_load_lds_dwordx4 v212, s[0:1]
	s_mov_b32 m0, s30
	s_nop 0
	global_load_lds_dwordx4 v210, s[0:1]
	s_waitcnt vmcnt(8)
	s_waitcnt lgkmcnt(0)
	s_setprio 1
	s_barrier
	v_mfma_f32_16x16x32_bf16 v[170:173], v[78:81], v[150:153], v[170:173]
	v_mfma_f32_16x16x32_bf16 v[162:165], v[94:97], v[150:153], v[162:165]
	v_mfma_f32_16x16x32_bf16 v[142:145], v[78:81], v[166:169], v[142:145]
	v_mfma_f32_16x16x32_bf16 v[138:141], v[94:97], v[166:169], v[138:141]
	v_mfma_f32_16x16x32_bf16 v[118:121], v[78:81], v[178:181], v[118:121]
	v_mfma_f32_16x16x32_bf16 v[114:117], v[94:97], v[178:181], v[114:117]
	v_mfma_f32_16x16x32_bf16 v[82:85], v[78:81], v[186:189], v[82:85]
	v_mfma_f32_16x16x32_bf16 v[74:77], v[94:97], v[186:189], v[74:77]
	v_mfma_f32_16x16x32_bf16 v[170:173], v[86:89], v[158:161], v[170:173]
	v_mfma_f32_16x16x32_bf16 v[162:165], v[98:101], v[158:161], v[162:165]
	v_mfma_f32_16x16x32_bf16 v[142:145], v[86:89], v[174:177], v[142:145]
	v_mfma_f32_16x16x32_bf16 v[138:141], v[98:101], v[174:177], v[138:141]
	v_mfma_f32_16x16x32_bf16 v[118:121], v[86:89], v[182:185], v[118:121]
	v_mfma_f32_16x16x32_bf16 v[114:117], v[98:101], v[182:185], v[114:117]
	v_mfma_f32_16x16x32_bf16 v[82:85], v[86:89], v[190:193], v[82:85]
	v_mfma_f32_16x16x32_bf16 v[74:77], v[98:101], v[190:193], v[74:77]
	s_setprio 0
	s_setprio 1
	v_mfma_f32_16x16x32_bf16 v[154:157], v[106:109], v[150:153], v[154:157]
	v_mfma_f32_16x16x32_bf16 v[146:149], v[126:129], v[150:153], v[146:149]
	v_mfma_f32_16x16x32_bf16 v[130:133], v[106:109], v[166:169], v[130:133]
	v_mfma_f32_16x16x32_bf16 v[122:125], v[126:129], v[166:169], v[122:125]
	v_mfma_f32_16x16x32_bf16 v[102:105], v[106:109], v[178:181], v[102:105]
	v_mfma_f32_16x16x32_bf16 v[90:93], v[126:129], v[178:181], v[90:93]
	v_mfma_f32_16x16x32_bf16 v[70:73], v[106:109], v[186:189], v[70:73]
	v_mfma_f32_16x16x32_bf16 v[66:69], v[126:129], v[186:189], v[66:69]
	v_mfma_f32_16x16x32_bf16 v[154:157], v[110:113], v[158:161], v[154:157]
	v_mfma_f32_16x16x32_bf16 v[150:153], v[134:137], v[158:161], v[146:149]
	v_mfma_f32_16x16x32_bf16 v[130:133], v[110:113], v[174:177], v[130:133]
	v_mfma_f32_16x16x32_bf16 v[122:125], v[134:137], v[174:177], v[122:125]
	v_mfma_f32_16x16x32_bf16 v[102:105], v[110:113], v[182:185], v[102:105]
	v_mfma_f32_16x16x32_bf16 v[90:93], v[134:137], v[182:185], v[90:93]
	v_mfma_f32_16x16x32_bf16 v[70:73], v[110:113], v[190:193], v[70:73]
	v_mfma_f32_16x16x32_bf16 v[66:69], v[134:137], v[190:193], v[66:69]
	s_barrier
	s_setprio 0
	s_add_i32 s0, s33, s26
	s_add_u32 s100, s20, 0x80
	s_addc_u32 s101, s21, 0
	s_mov_b32 m0, s0
	ds_read_b128 v[146:149], v239 offset:49152
	ds_read_b128 v[158:161], v239 offset:50176
	ds_read_b128 v[166:169], v239 offset:51200
	ds_read_b128 v[174:177], v239 offset:52224
	ds_read_b128 v[178:181], v239 offset:53248
	ds_read_b128 v[182:185], v239 offset:54272
	ds_read_b128 v[186:189], v239 offset:55296
	ds_read_b128 v[190:193], v239 offset:56320
	global_load_lds_dwordx4 v202, s[100:101]
	s_add_i32 m0, s0, 0x2000
	s_add_u32 s100, s20, 0x80
	s_addc_u32 s101, s21, 0
	s_add_u32 s0, s20, 0x100080
	s_addc_u32 s1, s21, 0
	s_add_i32 s20, s55, s26
	global_load_lds_dwordx4 v208, s[100:101]
	s_mov_b32 m0, s20
	s_nop 0
	global_load_lds_dwordx4 v202, s[0:1]
	s_add_i32 m0, s20, 0x2000
	s_nop 0
	global_load_lds_dwordx4 v208, s[0:1]
	s_add_u32 s100, s22, 0x80
	s_addc_u32 s101, s23, 0
	s_mov_b32 m0, s35
	s_nop 0
	global_load_lds_dwordx4 v212, s[100:101]
	s_add_u32 s100, s22, 0x80
	s_addc_u32 s101, s23, 0
	s_mov_b32 m0, s36
	s_nop 0
	global_load_lds_dwordx4 v210, s[100:101]
	s_waitcnt vmcnt(8)
	s_waitcnt lgkmcnt(0)
	s_setprio 1
	s_barrier
	v_mfma_f32_16x16x32_bf16 v[62:65], v[78:81], v[146:149], v[62:65]
	v_mfma_f32_16x16x32_bf16 v[58:61], v[94:97], v[146:149], v[58:61]
	v_mfma_f32_16x16x32_bf16 v[46:49], v[78:81], v[166:169], v[46:49]
	v_mfma_f32_16x16x32_bf16 v[42:45], v[94:97], v[166:169], v[42:45]
	v_mfma_f32_16x16x32_bf16 v[30:33], v[78:81], v[178:181], v[30:33]
	v_mfma_f32_16x16x32_bf16 v[26:29], v[94:97], v[178:181], v[26:29]
	v_mfma_f32_16x16x32_bf16 v[14:17], v[78:81], v[186:189], v[14:17]
	v_mfma_f32_16x16x32_bf16 v[10:13], v[94:97], v[186:189], v[10:13]
	v_mfma_f32_16x16x32_bf16 v[62:65], v[86:89], v[158:161], v[62:65]
	v_mfma_f32_16x16x32_bf16 v[58:61], v[98:101], v[158:161], v[58:61]
	v_mfma_f32_16x16x32_bf16 v[46:49], v[86:89], v[174:177], v[46:49]
	v_mfma_f32_16x16x32_bf16 v[42:45], v[98:101], v[174:177], v[42:45]
	v_mfma_f32_16x16x32_bf16 v[30:33], v[86:89], v[182:185], v[30:33]
	v_mfma_f32_16x16x32_bf16 v[26:29], v[98:101], v[182:185], v[26:29]
	v_mfma_f32_16x16x32_bf16 v[14:17], v[86:89], v[190:193], v[14:17]
	v_mfma_f32_16x16x32_bf16 v[10:13], v[98:101], v[190:193], v[10:13]
	s_setprio 0
	s_setprio 1
	v_mfma_f32_16x16x32_bf16 v[54:57], v[106:109], v[146:149], v[54:57]
	v_mfma_f32_16x16x32_bf16 v[50:53], v[126:129], v[146:149], v[50:53]
	v_mfma_f32_16x16x32_bf16 v[38:41], v[106:109], v[166:169], v[38:41]
	v_mfma_f32_16x16x32_bf16 v[34:37], v[126:129], v[166:169], v[34:37]
	v_mfma_f32_16x16x32_bf16 v[22:25], v[106:109], v[178:181], v[22:25]
	v_mfma_f32_16x16x32_bf16 v[18:21], v[126:129], v[178:181], v[18:21]
	v_mfma_f32_16x16x32_bf16 v[6:9], v[106:109], v[186:189], v[6:9]
	v_mfma_f32_16x16x32_bf16 v[2:5], v[126:129], v[186:189], v[2:5]
	v_mfma_f32_16x16x32_bf16 v[54:57], v[110:113], v[158:161], v[54:57]
	v_mfma_f32_16x16x32_bf16 v[50:53], v[134:137], v[158:161], v[50:53]
	v_mfma_f32_16x16x32_bf16 v[38:41], v[110:113], v[174:177], v[38:41]
	v_mfma_f32_16x16x32_bf16 v[34:37], v[134:137], v[174:177], v[34:37]
	v_mfma_f32_16x16x32_bf16 v[22:25], v[110:113], v[182:185], v[22:25]
	v_mfma_f32_16x16x32_bf16 v[18:21], v[134:137], v[182:185], v[18:21]
	v_mfma_f32_16x16x32_bf16 v[6:9], v[110:113], v[190:193], v[6:9]
	v_mfma_f32_16x16x32_bf16 v[2:5], v[134:137], v[190:193], v[2:5]
	s_barrier
	s_setprio 0
	s_add_i32 s61, s61, 2
	s_add_u32 s18, s18, 0x100
	s_addc_u32 s19, s19, 0
	s_add_u32 s59, s59, 0x100
	s_addc_u32 s60, s60, 0
	s_cmp_gt_u32 s61, 61
	s_cbranch_scc0 .LBB0_692
	s_and_b64 vcc, exec, s[6:7]
	s_cbranch_vccz .LBB0_695
	s_barrier

.LBB0_712:
	s_add_u32 s0, s18, 0xfff00080
	s_addc_u32 s1, s19, -1
	s_add_i32 s33, 0, 0x10000
	s_cmp_eq_u32 s49, 4
	s_cselect_b32 s23, s15, s1
	s_cselect_b32 s22, s14, s0
	s_cselect_b32 s21, s17, s11
	s_cselect_b32 s20, s16, s9
	s_add_i32 s55, 0, 0x14000
	v_add_u32_e32 v152, s33, v136
	v_add_u32_e32 v168, s55, v136
	ds_read_b128 v[140:143], v152
	ds_read_b128 v[144:147], v152 offset:1024
	ds_read_b128 v[148:151], v152 offset:2048
	ds_read_b128 v[152:155], v152 offset:3072
	ds_read_b128 v[156:159], v168
	ds_read_b128 v[160:163], v168 offset:1024
	ds_read_b128 v[164:167], v168 offset:2048
	ds_read_b128 v[168:171], v168 offset:3072
	s_add_i32 m0, s27, 0xc000
	ds_read_b128 v[172:175], v139
	ds_read_b128 v[176:179], v139 offset:1024
	ds_read_b128 v[180:183], v139 offset:2048
	ds_read_b128 v[184:187], v139 offset:3072
	ds_read_b128 v[188:191], v139 offset:4096
	ds_read_b128 v[192:195], v139 offset:5120
	ds_read_b128 v[196:199], v139 offset:6144
	ds_read_b128 v[208:211], v139 offset:7168
	global_load_lds_dwordx4 v132, s[18:19]
	s_add_i32 m0, s27, 0xe000
	s_nop 0
	global_load_lds_dwordx4 v134, s[18:19]
	s_waitcnt vmcnt(8)
	s_waitcnt lgkmcnt(0)
	s_setprio 1
	s_barrier
	v_mfma_f32_16x16x32_bf16 v[126:129], v[140:143], v[172:175], v[126:129]
	v_mfma_f32_16x16x32_bf16 v[122:125], v[148:151], v[172:175], v[122:125]
	v_mfma_f32_16x16x32_bf16 v[118:121], v[140:143], v[180:183], v[118:121]
	v_mfma_f32_16x16x32_bf16 v[114:117], v[148:151], v[180:183], v[114:117]
	v_mfma_f32_16x16x32_bf16 v[106:109], v[140:143], v[188:191], v[106:109]
	v_mfma_f32_16x16x32_bf16 v[98:101], v[148:151], v[188:191], v[98:101]
	v_mfma_f32_16x16x32_bf16 v[90:93], v[140:143], v[196:199], v[90:93]
	v_mfma_f32_16x16x32_bf16 v[82:85], v[148:151], v[196:199], v[82:85]
	v_mfma_f32_16x16x32_bf16 v[126:129], v[144:147], v[176:179], v[126:129]
	v_mfma_f32_16x16x32_bf16 v[122:125], v[152:155], v[176:179], v[122:125]
	v_mfma_f32_16x16x32_bf16 v[118:121], v[144:147], v[184:187], v[118:121]
	v_mfma_f32_16x16x32_bf16 v[114:117], v[152:155], v[184:187], v[114:117]
	v_mfma_f32_16x16x32_bf16 v[106:109], v[144:147], v[192:195], v[106:109]
	v_mfma_f32_16x16x32_bf16 v[98:101], v[152:155], v[192:195], v[98:101]
	v_mfma_f32_16x16x32_bf16 v[90:93], v[144:147], v[208:211], v[90:93]
	v_mfma_f32_16x16x32_bf16 v[82:85], v[152:155], v[208:211], v[82:85]
	s_setprio 0
	s_setprio 1
	v_mfma_f32_16x16x32_bf16 v[110:113], v[156:159], v[172:175], v[110:113]
	v_mfma_f32_16x16x32_bf16 v[102:105], v[164:167], v[172:175], v[102:105]
	v_mfma_f32_16x16x32_bf16 v[94:97], v[156:159], v[180:183], v[94:97]
	v_mfma_f32_16x16x32_bf16 v[86:89], v[164:167], v[180:183], v[86:89]
	v_mfma_f32_16x16x32_bf16 v[78:81], v[156:159], v[188:191], v[78:81]
	v_mfma_f32_16x16x32_bf16 v[74:77], v[164:167], v[188:191], v[74:77]
	v_mfma_f32_16x16x32_bf16 v[70:73], v[156:159], v[196:199], v[70:73]
	v_mfma_f32_16x16x32_bf16 v[66:69], v[164:167], v[196:199], v[66:69]
	v_mfma_f32_16x16x32_bf16 v[110:113], v[160:163], v[176:179], v[110:113]
	v_mfma_f32_16x16x32_bf16 v[102:105], v[168:171], v[176:179], v[102:105]
	v_mfma_f32_16x16x32_bf16 v[94:97], v[160:163], v[184:187], v[94:97]
	v_mfma_f32_16x16x32_bf16 v[86:89], v[168:171], v[184:187], v[86:89]
	v_mfma_f32_16x16x32_bf16 v[78:81], v[160:163], v[192:195], v[78:81]
	v_mfma_f32_16x16x32_bf16 v[74:77], v[168:171], v[192:195], v[74:77]
	v_mfma_f32_16x16x32_bf16 v[70:73], v[160:163], v[208:211], v[70:73]
	v_mfma_f32_16x16x32_bf16 v[66:69], v[168:171], v[208:211], v[66:69]
	s_barrier
	s_setprio 0
	s_add_i32 s0, s33, s26
	s_mov_b32 m0, s0
	ds_read_b128 v[172:175], v139 offset:16384
	ds_read_b128 v[176:179], v139 offset:17408
	ds_read_b128 v[180:183], v139 offset:18432
	ds_read_b128 v[184:187], v139 offset:19456
	ds_read_b128 v[188:191], v139 offset:20480
	ds_read_b128 v[192:195], v139 offset:21504
	ds_read_b128 v[196:199], v139 offset:22528
	ds_read_b128 v[208:211], v139 offset:23552
	global_load_lds_dwordx4 v202, s[20:21]
	s_add_i32 m0, s0, 0x2000
	s_add_u32 s0, s20, 0x100000
	s_addc_u32 s1, s21, 0
	s_add_i32 s33, s55, s26
	global_load_lds_dwordx4 v130, s[20:21]
	s_mov_b32 m0, s33
	s_nop 0
	global_load_lds_dwordx4 v202, s[0:1]
	s_add_i32 m0, s33, 0x2000
	s_nop 0
	global_load_lds_dwordx4 v130, s[0:1]
	s_mov_b32 m0, s27
	s_nop 0
	global_load_lds_dwordx4 v202, s[22:23]
	s_mov_b32 m0, s28
	s_nop 0
	global_load_lds_dwordx4 v130, s[22:23]
	s_waitcnt vmcnt(8)
	s_waitcnt lgkmcnt(0)
	s_setprio 1
	s_barrier
	v_mfma_f32_16x16x32_bf16 v[62:65], v[140:143], v[172:175], v[62:65]
	v_mfma_f32_16x16x32_bf16 v[58:61], v[148:151], v[172:175], v[58:61]
	v_mfma_f32_16x16x32_bf16 v[54:57], v[140:143], v[180:183], v[54:57]
	v_mfma_f32_16x16x32_bf16 v[50:53], v[148:151], v[180:183], v[50:53]
	v_mfma_f32_16x16x32_bf16 v[38:41], v[140:143], v[188:191], v[38:41]
	v_mfma_f32_16x16x32_bf16 v[34:37], v[148:151], v[188:191], v[34:37]
	v_mfma_f32_16x16x32_bf16 v[22:25], v[140:143], v[196:199], v[22:25]
	v_mfma_f32_16x16x32_bf16 v[18:21], v[148:151], v[196:199], v[18:21]
	v_mfma_f32_16x16x32_bf16 v[62:65], v[144:147], v[176:179], v[62:65]
	v_mfma_f32_16x16x32_bf16 v[58:61], v[152:155], v[176:179], v[58:61]
	v_mfma_f32_16x16x32_bf16 v[54:57], v[144:147], v[184:187], v[54:57]
	v_mfma_f32_16x16x32_bf16 v[50:53], v[152:155], v[184:187], v[50:53]
	v_mfma_f32_16x16x32_bf16 v[38:41], v[144:147], v[192:195], v[38:41]
	v_mfma_f32_16x16x32_bf16 v[34:37], v[152:155], v[192:195], v[34:37]
	v_mfma_f32_16x16x32_bf16 v[22:25], v[144:147], v[208:211], v[22:25]
	v_mfma_f32_16x16x32_bf16 v[18:21], v[152:155], v[208:211], v[18:21]
	s_setprio 0
	s_setprio 1
	v_mfma_f32_16x16x32_bf16 v[46:49], v[156:159], v[172:175], v[46:49]
	v_mfma_f32_16x16x32_bf16 v[42:45], v[164:167], v[172:175], v[42:45]
	v_mfma_f32_16x16x32_bf16 v[30:33], v[156:159], v[180:183], v[30:33]
	v_mfma_f32_16x16x32_bf16 v[26:29], v[164:167], v[180:183], v[26:29]
	v_mfma_f32_16x16x32_bf16 v[14:17], v[156:159], v[188:191], v[14:17]
	v_mfma_f32_16x16x32_bf16 v[10:13], v[164:167], v[188:191], v[10:13]
	v_mfma_f32_16x16x32_bf16 v[6:9], v[156:159], v[196:199], v[6:9]
	v_mfma_f32_16x16x32_bf16 v[2:5], v[164:167], v[196:199], v[2:5]
	v_mfma_f32_16x16x32_bf16 v[46:49], v[160:163], v[176:179], v[46:49]
	v_mfma_f32_16x16x32_bf16 v[42:45], v[168:171], v[176:179], v[42:45]
	v_mfma_f32_16x16x32_bf16 v[30:33], v[160:163], v[184:187], v[30:33]
	v_mfma_f32_16x16x32_bf16 v[26:29], v[168:171], v[184:187], v[26:29]
	v_mfma_f32_16x16x32_bf16 v[14:17], v[160:163], v[192:195], v[14:17]
	v_mfma_f32_16x16x32_bf16 v[10:13], v[168:171], v[192:195], v[10:13]
	v_mfma_f32_16x16x32_bf16 v[6:9], v[160:163], v[208:211], v[6:9]
	v_mfma_f32_16x16x32_bf16 v[2:5], v[168:171], v[208:211], v[2:5]
	s_barrier
	s_setprio 0
	s_add_i32 s33, 0, 0x18000
	s_add_i32 s55, 0, 0x1c000
	v_add_u32_e32 v152, s33, v136
	v_add_u32_e32 v168, s55, v136
	ds_read_b128 v[140:143], v152
	ds_read_b128 v[144:147], v152 offset:1024
	ds_read_b128 v[148:151], v152 offset:2048
	ds_read_b128 v[152:155], v152 offset:3072
	ds_read_b128 v[156:159], v168
	ds_read_b128 v[160:163], v168 offset:1024
	ds_read_b128 v[164:167], v168 offset:2048
	ds_read_b128 v[168:171], v168 offset:3072
	s_add_u32 s0, s22, 0x100000
	s_addc_u32 s1, s23, 0
	s_mov_b32 m0, s29
	ds_read_b128 v[172:175], v139 offset:32768
	ds_read_b128 v[176:179], v139 offset:33792
	ds_read_b128 v[180:183], v139 offset:34816
	ds_read_b128 v[184:187], v139 offset:35840
	ds_read_b128 v[188:191], v139 offset:36864
	ds_read_b128 v[192:195], v139 offset:37888
	ds_read_b128 v[196:199], v139 offset:38912
	ds_read_b128 v[208:211], v139 offset:39936
	global_load_lds_dwordx4 v202, s[0:1]
	s_mov_b32 m0, s30
	s_nop 0
	global_load_lds_dwordx4 v130, s[0:1]
	s_waitcnt vmcnt(8)
	s_waitcnt lgkmcnt(0)
	s_setprio 1
	s_barrier
	v_mfma_f32_16x16x32_bf16 v[126:129], v[140:143], v[172:175], v[126:129]
	v_mfma_f32_16x16x32_bf16 v[122:125], v[148:151], v[172:175], v[122:125]
	v_mfma_f32_16x16x32_bf16 v[118:121], v[140:143], v[180:183], v[118:121]
	v_mfma_f32_16x16x32_bf16 v[114:117], v[148:151], v[180:183], v[114:117]
	v_mfma_f32_16x16x32_bf16 v[106:109], v[140:143], v[188:191], v[106:109]
	v_mfma_f32_16x16x32_bf16 v[98:101], v[148:151], v[188:191], v[98:101]
	v_mfma_f32_16x16x32_bf16 v[90:93], v[140:143], v[196:199], v[90:93]
	v_mfma_f32_16x16x32_bf16 v[82:85], v[148:151], v[196:199], v[82:85]
	v_mfma_f32_16x16x32_bf16 v[126:129], v[144:147], v[176:179], v[126:129]
	v_mfma_f32_16x16x32_bf16 v[122:125], v[152:155], v[176:179], v[122:125]
	v_mfma_f32_16x16x32_bf16 v[118:121], v[144:147], v[184:187], v[118:121]
	v_mfma_f32_16x16x32_bf16 v[114:117], v[152:155], v[184:187], v[114:117]
	v_mfma_f32_16x16x32_bf16 v[106:109], v[144:147], v[192:195], v[106:109]
	v_mfma_f32_16x16x32_bf16 v[98:101], v[152:155], v[192:195], v[98:101]
	v_mfma_f32_16x16x32_bf16 v[90:93], v[144:147], v[208:211], v[90:93]
	v_mfma_f32_16x16x32_bf16 v[82:85], v[152:155], v[208:211], v[82:85]
	s_setprio 0
	s_setprio 1
	v_mfma_f32_16x16x32_bf16 v[110:113], v[156:159], v[172:175], v[110:113]
	v_mfma_f32_16x16x32_bf16 v[102:105], v[164:167], v[172:175], v[102:105]
	v_mfma_f32_16x16x32_bf16 v[94:97], v[156:159], v[180:183], v[94:97]
	v_mfma_f32_16x16x32_bf16 v[86:89], v[164:167], v[180:183], v[86:89]
	v_mfma_f32_16x16x32_bf16 v[78:81], v[156:159], v[188:191], v[78:81]
	v_mfma_f32_16x16x32_bf16 v[74:77], v[164:167], v[188:191], v[74:77]
	v_mfma_f32_16x16x32_bf16 v[70:73], v[156:159], v[196:199], v[70:73]
	v_mfma_f32_16x16x32_bf16 v[66:69], v[164:167], v[196:199], v[66:69]
	v_mfma_f32_16x16x32_bf16 v[110:113], v[160:163], v[176:179], v[110:113]
	v_mfma_f32_16x16x32_bf16 v[102:105], v[168:171], v[176:179], v[102:105]
	v_mfma_f32_16x16x32_bf16 v[94:97], v[160:163], v[184:187], v[94:97]
	v_mfma_f32_16x16x32_bf16 v[86:89], v[168:171], v[184:187], v[86:89]
	v_mfma_f32_16x16x32_bf16 v[78:81], v[160:163], v[192:195], v[78:81]
	v_mfma_f32_16x16x32_bf16 v[74:77], v[168:171], v[192:195], v[74:77]
	v_mfma_f32_16x16x32_bf16 v[70:73], v[160:163], v[208:211], v[70:73]
	v_mfma_f32_16x16x32_bf16 v[66:69], v[168:171], v[208:211], v[66:69]
	s_barrier
	s_setprio 0
	s_add_i32 s0, s33, s26
	s_add_u32 s100, s20, 0x80
	s_addc_u32 s101, s21, 0
	s_mov_b32 m0, s0
	ds_read_b128 v[172:175], v139 offset:49152
	ds_read_b128 v[176:179], v139 offset:50176
	ds_read_b128 v[180:183], v139 offset:51200
	ds_read_b128 v[184:187], v139 offset:52224
	ds_read_b128 v[188:191], v139 offset:53248
	ds_read_b128 v[192:195], v139 offset:54272
	ds_read_b128 v[196:199], v139 offset:55296
	ds_read_b128 v[208:211], v139 offset:56320
	global_load_lds_dwordx4 v202, s[100:101]
	s_add_i32 m0, s0, 0x2000
	s_add_u32 s100, s20, 0x80
	s_addc_u32 s101, s21, 0
	s_add_u32 s0, s20, 0x100080
	s_addc_u32 s1, s21, 0
	s_add_i32 s20, s55, s26
	global_load_lds_dwordx4 v130, s[100:101]
	s_mov_b32 m0, s20
	s_nop 0
	global_load_lds_dwordx4 v202, s[0:1]
	s_add_i32 m0, s20, 0x2000
	s_nop 0
	global_load_lds_dwordx4 v130, s[0:1]
	s_add_u32 s100, s22, 0x80
	s_addc_u32 s101, s23, 0
	s_mov_b32 m0, s31
	s_nop 0
	global_load_lds_dwordx4 v202, s[100:101]
	s_add_u32 s100, s22, 0x80
	s_addc_u32 s101, s23, 0
	s_mov_b32 m0, s34
	s_nop 0
	global_load_lds_dwordx4 v130, s[100:101]
	s_waitcnt vmcnt(8)
	s_waitcnt lgkmcnt(0)
	s_setprio 1
	s_barrier
	v_mfma_f32_16x16x32_bf16 v[62:65], v[140:143], v[172:175], v[62:65]
	v_mfma_f32_16x16x32_bf16 v[58:61], v[148:151], v[172:175], v[58:61]
	v_mfma_f32_16x16x32_bf16 v[54:57], v[140:143], v[180:183], v[54:57]
	v_mfma_f32_16x16x32_bf16 v[50:53], v[148:151], v[180:183], v[50:53]
	v_mfma_f32_16x16x32_bf16 v[38:41], v[140:143], v[188:191], v[38:41]
	v_mfma_f32_16x16x32_bf16 v[34:37], v[148:151], v[188:191], v[34:37]
	v_mfma_f32_16x16x32_bf16 v[22:25], v[140:143], v[196:199], v[22:25]
	v_mfma_f32_16x16x32_bf16 v[18:21], v[148:151], v[196:199], v[18:21]
	v_mfma_f32_16x16x32_bf16 v[62:65], v[144:147], v[176:179], v[62:65]
	v_mfma_f32_16x16x32_bf16 v[58:61], v[152:155], v[176:179], v[58:61]
	v_mfma_f32_16x16x32_bf16 v[54:57], v[144:147], v[184:187], v[54:57]
	v_mfma_f32_16x16x32_bf16 v[50:53], v[152:155], v[184:187], v[50:53]
	v_mfma_f32_16x16x32_bf16 v[38:41], v[144:147], v[192:195], v[38:41]
	v_mfma_f32_16x16x32_bf16 v[34:37], v[152:155], v[192:195], v[34:37]
	v_mfma_f32_16x16x32_bf16 v[22:25], v[144:147], v[208:211], v[22:25]
	v_mfma_f32_16x16x32_bf16 v[18:21], v[152:155], v[208:211], v[18:21]
	s_setprio 0
	s_setprio 1
	v_mfma_f32_16x16x32_bf16 v[46:49], v[156:159], v[172:175], v[46:49]
	v_mfma_f32_16x16x32_bf16 v[42:45], v[164:167], v[172:175], v[42:45]
	v_mfma_f32_16x16x32_bf16 v[30:33], v[156:159], v[180:183], v[30:33]
	v_mfma_f32_16x16x32_bf16 v[26:29], v[164:167], v[180:183], v[26:29]
	v_mfma_f32_16x16x32_bf16 v[14:17], v[156:159], v[188:191], v[14:17]
	v_mfma_f32_16x16x32_bf16 v[10:13], v[164:167], v[188:191], v[10:13]
	v_mfma_f32_16x16x32_bf16 v[6:9], v[156:159], v[196:199], v[6:9]
	v_mfma_f32_16x16x32_bf16 v[2:5], v[164:167], v[196:199], v[2:5]
	v_mfma_f32_16x16x32_bf16 v[46:49], v[160:163], v[176:179], v[46:49]
	v_mfma_f32_16x16x32_bf16 v[42:45], v[168:171], v[176:179], v[42:45]
	v_mfma_f32_16x16x32_bf16 v[30:33], v[160:163], v[184:187], v[30:33]
	v_mfma_f32_16x16x32_bf16 v[26:29], v[168:171], v[184:187], v[26:29]
	v_mfma_f32_16x16x32_bf16 v[14:17], v[160:163], v[192:195], v[14:17]
	v_mfma_f32_16x16x32_bf16 v[10:13], v[168:171], v[192:195], v[10:13]
	v_mfma_f32_16x16x32_bf16 v[6:9], v[160:163], v[208:211], v[6:9]
	v_mfma_f32_16x16x32_bf16 v[2:5], v[168:171], v[208:211], v[2:5]
	s_barrier
	s_setprio 0
	s_add_i32 s49, s49, 2
	s_add_u32 s18, s18, 0x100
	s_addc_u32 s19, s19, 0
	s_add_u32 s9, s9, 0x100
	s_addc_u32 s11, s11, 0
	s_cmp_gt_u32 s49, 5
	s_cbranch_scc0 .LBB0_712
	s_and_b64 vcc, exec, s[6:7]
	s_cbranch_vccz .LBB0_715
	s_barrier

.LBB0_837:
	s_add_u32 s0, s18, 0xfff80080
	s_addc_u32 s1, s19, -1
	s_add_i32 s33, 0, 0x10000
	s_cmp_eq_u32 s59, 28
	s_cselect_b32 s23, s11, s1
	s_cselect_b32 s22, s38, s0
	v_add_u32_e32 v140, s33, v143
	s_cselect_b32 s21, s9, s58
	s_cselect_b32 s20, s39, s49
	s_add_i32 s55, 0, 0x14000
	ds_read_b128 v[146:149], v140
	ds_read_b128 v[150:153], v140 offset:1024
	ds_read_b128 v[154:157], v140 offset:2048
	ds_read_b128 v[158:161], v140 offset:3072
	v_add_u32_e32 v140, s55, v143
	ds_read_b128 v[162:165], v140
	ds_read_b128 v[166:169], v140 offset:1024
	ds_read_b128 v[170:173], v140 offset:2048
	ds_read_b128 v[174:177], v140 offset:3072
	s_add_i32 m0, s27, 0xc000
	ds_read_b128 v[178:181], v145
	ds_read_b128 v[182:185], v145 offset:1024
	ds_read_b128 v[186:189], v145 offset:2048
	ds_read_b128 v[190:193], v145 offset:3072
	ds_read_b128 v[194:197], v145 offset:4096
	ds_read_b128 v[198:201], v145 offset:5120
	ds_read_b128 v[208:211], v145 offset:6144
	ds_read_b128 v[212:215], v145 offset:7168
	global_load_lds_dwordx4 v136, s[18:19]
	s_add_i32 m0, s27, 0xe000
	s_nop 0
	global_load_lds_dwordx4 v138, s[18:19]
	s_waitcnt vmcnt(8)
	s_waitcnt lgkmcnt(0)
	s_setprio 1
	s_barrier
	v_mfma_f32_16x16x32_bf16 v[126:129], v[146:149], v[178:181], v[126:129]
	v_mfma_f32_16x16x32_bf16 v[118:121], v[154:157], v[178:181], v[118:121]
	v_mfma_f32_16x16x32_bf16 v[110:113], v[146:149], v[186:189], v[110:113]
	v_mfma_f32_16x16x32_bf16 v[102:105], v[154:157], v[186:189], v[102:105]
	v_mfma_f32_16x16x32_bf16 v[94:97], v[146:149], v[194:197], v[94:97]
	v_mfma_f32_16x16x32_bf16 v[86:89], v[154:157], v[194:197], v[86:89]
	v_mfma_f32_16x16x32_bf16 v[78:81], v[146:149], v[208:211], v[78:81]
	v_mfma_f32_16x16x32_bf16 v[70:73], v[154:157], v[208:211], v[70:73]
	v_mfma_f32_16x16x32_bf16 v[126:129], v[150:153], v[182:185], v[126:129]
	v_mfma_f32_16x16x32_bf16 v[118:121], v[158:161], v[182:185], v[118:121]
	v_mfma_f32_16x16x32_bf16 v[110:113], v[150:153], v[190:193], v[110:113]
	v_mfma_f32_16x16x32_bf16 v[102:105], v[158:161], v[190:193], v[102:105]
	v_mfma_f32_16x16x32_bf16 v[94:97], v[150:153], v[198:201], v[94:97]
	v_mfma_f32_16x16x32_bf16 v[86:89], v[158:161], v[198:201], v[86:89]
	v_mfma_f32_16x16x32_bf16 v[78:81], v[150:153], v[212:215], v[78:81]
	v_mfma_f32_16x16x32_bf16 v[70:73], v[158:161], v[212:215], v[70:73]
	s_setprio 0
	s_setprio 1
	v_mfma_f32_16x16x32_bf16 v[122:125], v[162:165], v[178:181], v[122:125]
	v_mfma_f32_16x16x32_bf16 v[114:117], v[170:173], v[178:181], v[114:117]
	v_mfma_f32_16x16x32_bf16 v[106:109], v[162:165], v[186:189], v[106:109]
	v_mfma_f32_16x16x32_bf16 v[98:101], v[170:173], v[186:189], v[98:101]
	v_mfma_f32_16x16x32_bf16 v[90:93], v[162:165], v[194:197], v[90:93]
	v_mfma_f32_16x16x32_bf16 v[82:85], v[170:173], v[194:197], v[82:85]
	v_mfma_f32_16x16x32_bf16 v[74:77], v[162:165], v[208:211], v[74:77]
	v_mfma_f32_16x16x32_bf16 v[66:69], v[170:173], v[208:211], v[66:69]
	v_mfma_f32_16x16x32_bf16 v[122:125], v[166:169], v[182:185], v[122:125]
	v_mfma_f32_16x16x32_bf16 v[114:117], v[174:177], v[182:185], v[114:117]
	v_mfma_f32_16x16x32_bf16 v[106:109], v[166:169], v[190:193], v[106:109]
	v_mfma_f32_16x16x32_bf16 v[98:101], v[174:177], v[190:193], v[98:101]
	v_mfma_f32_16x16x32_bf16 v[90:93], v[166:169], v[198:201], v[90:93]
	v_mfma_f32_16x16x32_bf16 v[82:85], v[174:177], v[198:201], v[82:85]
	v_mfma_f32_16x16x32_bf16 v[74:77], v[166:169], v[212:215], v[74:77]
	v_mfma_f32_16x16x32_bf16 v[66:69], v[174:177], v[212:215], v[66:69]
	s_barrier
	s_setprio 0
	s_add_i32 s0, s33, s26
	s_mov_b32 m0, s0
	ds_read_b128 v[178:181], v145 offset:16384
	ds_read_b128 v[182:185], v145 offset:17408
	ds_read_b128 v[186:189], v145 offset:18432
	ds_read_b128 v[190:193], v145 offset:19456
	ds_read_b128 v[194:197], v145 offset:20480
	ds_read_b128 v[198:201], v145 offset:21504
	ds_read_b128 v[208:211], v145 offset:22528
	ds_read_b128 v[212:215], v145 offset:23552
	global_load_lds_dwordx4 v202, s[20:21]
	s_add_i32 m0, s0, 0x2000
	s_add_u32 s0, s20, 0x80000
	s_addc_u32 s1, s21, 0
	s_add_i32 s33, s55, s26
	global_load_lds_dwordx4 v130, s[20:21]
	s_mov_b32 m0, s33
	s_nop 0
	global_load_lds_dwordx4 v202, s[0:1]
	s_add_i32 m0, s33, 0x2000
	s_nop 0
	global_load_lds_dwordx4 v130, s[0:1]
	s_mov_b32 m0, s27
	s_nop 0
	global_load_lds_dwordx4 v134, s[22:23]
	s_mov_b32 m0, s28
	s_nop 0
	global_load_lds_dwordx4 v132, s[22:23]
	s_waitcnt vmcnt(8)
	s_waitcnt lgkmcnt(0)
	s_setprio 1
	s_barrier
	v_mfma_f32_16x16x32_bf16 v[62:65], v[146:149], v[178:181], v[62:65]
	v_mfma_f32_16x16x32_bf16 v[54:57], v[154:157], v[178:181], v[54:57]
	v_mfma_f32_16x16x32_bf16 v[46:49], v[146:149], v[186:189], v[46:49]
	v_mfma_f32_16x16x32_bf16 v[38:41], v[154:157], v[186:189], v[38:41]
	v_mfma_f32_16x16x32_bf16 v[30:33], v[146:149], v[194:197], v[30:33]
	v_mfma_f32_16x16x32_bf16 v[22:25], v[154:157], v[194:197], v[22:25]
	v_mfma_f32_16x16x32_bf16 v[14:17], v[146:149], v[208:211], v[14:17]
	v_mfma_f32_16x16x32_bf16 v[6:9], v[154:157], v[208:211], v[6:9]
	v_mfma_f32_16x16x32_bf16 v[62:65], v[150:153], v[182:185], v[62:65]
	v_mfma_f32_16x16x32_bf16 v[54:57], v[158:161], v[182:185], v[54:57]
	v_mfma_f32_16x16x32_bf16 v[46:49], v[150:153], v[190:193], v[46:49]
	v_mfma_f32_16x16x32_bf16 v[38:41], v[158:161], v[190:193], v[38:41]
	v_mfma_f32_16x16x32_bf16 v[30:33], v[150:153], v[198:201], v[30:33]
	v_mfma_f32_16x16x32_bf16 v[22:25], v[158:161], v[198:201], v[22:25]
	v_mfma_f32_16x16x32_bf16 v[14:17], v[150:153], v[212:215], v[14:17]
	v_mfma_f32_16x16x32_bf16 v[6:9], v[158:161], v[212:215], v[6:9]
	s_setprio 0
	s_setprio 1
	v_mfma_f32_16x16x32_bf16 v[58:61], v[162:165], v[178:181], v[58:61]
	v_mfma_f32_16x16x32_bf16 v[50:53], v[170:173], v[178:181], v[50:53]
	v_mfma_f32_16x16x32_bf16 v[42:45], v[162:165], v[186:189], v[42:45]
	v_mfma_f32_16x16x32_bf16 v[34:37], v[170:173], v[186:189], v[34:37]
	v_mfma_f32_16x16x32_bf16 v[26:29], v[162:165], v[194:197], v[26:29]
	v_mfma_f32_16x16x32_bf16 v[18:21], v[170:173], v[194:197], v[18:21]
	v_mfma_f32_16x16x32_bf16 v[10:13], v[162:165], v[208:211], v[10:13]
	v_mfma_f32_16x16x32_bf16 v[2:5], v[170:173], v[208:211], v[2:5]
	v_mfma_f32_16x16x32_bf16 v[58:61], v[166:169], v[182:185], v[58:61]
	v_mfma_f32_16x16x32_bf16 v[50:53], v[174:177], v[182:185], v[50:53]
	v_mfma_f32_16x16x32_bf16 v[42:45], v[166:169], v[190:193], v[42:45]
	v_mfma_f32_16x16x32_bf16 v[34:37], v[174:177], v[190:193], v[34:37]
	v_mfma_f32_16x16x32_bf16 v[26:29], v[166:169], v[198:201], v[26:29]
	v_mfma_f32_16x16x32_bf16 v[18:21], v[174:177], v[198:201], v[18:21]
	v_mfma_f32_16x16x32_bf16 v[10:13], v[166:169], v[212:215], v[10:13]
	v_mfma_f32_16x16x32_bf16 v[2:5], v[174:177], v[212:215], v[2:5]
	s_barrier
	s_setprio 0
	s_add_i32 s33, 0, 0x18000
	s_add_i32 s55, 0, 0x1c000
	v_add_u32_e32 v158, s33, v143
	v_add_u32_e32 v174, s55, v143
	ds_read_b128 v[146:149], v158
	ds_read_b128 v[150:153], v158 offset:1024
	ds_read_b128 v[154:157], v158 offset:2048
	ds_read_b128 v[158:161], v158 offset:3072
	ds_read_b128 v[162:165], v174
	ds_read_b128 v[166:169], v174 offset:1024
	ds_read_b128 v[170:173], v174 offset:2048
	ds_read_b128 v[174:177], v174 offset:3072
	s_add_u32 s0, s22, 0x80000
	s_addc_u32 s1, s23, 0
	s_mov_b32 m0, s29
	ds_read_b128 v[178:181], v145 offset:32768
	ds_read_b128 v[182:185], v145 offset:33792
	ds_read_b128 v[186:189], v145 offset:34816
	ds_read_b128 v[190:193], v145 offset:35840
	ds_read_b128 v[194:197], v145 offset:36864
	ds_read_b128 v[198:201], v145 offset:37888
	ds_read_b128 v[208:211], v145 offset:38912
	ds_read_b128 v[212:215], v145 offset:39936
	global_load_lds_dwordx4 v134, s[0:1]
	s_mov_b32 m0, s30
	s_nop 0
	global_load_lds_dwordx4 v132, s[0:1]
	s_waitcnt vmcnt(8)
	s_waitcnt lgkmcnt(0)
	s_setprio 1
	s_barrier
	v_mfma_f32_16x16x32_bf16 v[126:129], v[146:149], v[178:181], v[126:129]
	v_mfma_f32_16x16x32_bf16 v[118:121], v[154:157], v[178:181], v[118:121]
	v_mfma_f32_16x16x32_bf16 v[110:113], v[146:149], v[186:189], v[110:113]
	v_mfma_f32_16x16x32_bf16 v[102:105], v[154:157], v[186:189], v[102:105]
	v_mfma_f32_16x16x32_bf16 v[94:97], v[146:149], v[194:197], v[94:97]
	v_mfma_f32_16x16x32_bf16 v[86:89], v[154:157], v[194:197], v[86:89]
	v_mfma_f32_16x16x32_bf16 v[78:81], v[146:149], v[208:211], v[78:81]
	v_mfma_f32_16x16x32_bf16 v[70:73], v[154:157], v[208:211], v[70:73]
	v_mfma_f32_16x16x32_bf16 v[126:129], v[150:153], v[182:185], v[126:129]
	v_mfma_f32_16x16x32_bf16 v[118:121], v[158:161], v[182:185], v[118:121]
	v_mfma_f32_16x16x32_bf16 v[110:113], v[150:153], v[190:193], v[110:113]
	v_mfma_f32_16x16x32_bf16 v[102:105], v[158:161], v[190:193], v[102:105]
	v_mfma_f32_16x16x32_bf16 v[94:97], v[150:153], v[198:201], v[94:97]
	v_mfma_f32_16x16x32_bf16 v[86:89], v[158:161], v[198:201], v[86:89]
	v_mfma_f32_16x16x32_bf16 v[78:81], v[150:153], v[212:215], v[78:81]
	v_mfma_f32_16x16x32_bf16 v[70:73], v[158:161], v[212:215], v[70:73]
	s_setprio 0
	s_setprio 1
	v_mfma_f32_16x16x32_bf16 v[122:125], v[162:165], v[178:181], v[122:125]
	v_mfma_f32_16x16x32_bf16 v[114:117], v[170:173], v[178:181], v[114:117]
	v_mfma_f32_16x16x32_bf16 v[106:109], v[162:165], v[186:189], v[106:109]
	v_mfma_f32_16x16x32_bf16 v[98:101], v[170:173], v[186:189], v[98:101]
	v_mfma_f32_16x16x32_bf16 v[90:93], v[162:165], v[194:197], v[90:93]
	v_mfma_f32_16x16x32_bf16 v[82:85], v[170:173], v[194:197], v[82:85]
	v_mfma_f32_16x16x32_bf16 v[74:77], v[162:165], v[208:211], v[74:77]
	v_mfma_f32_16x16x32_bf16 v[66:69], v[170:173], v[208:211], v[66:69]
	v_mfma_f32_16x16x32_bf16 v[122:125], v[166:169], v[182:185], v[122:125]
	v_mfma_f32_16x16x32_bf16 v[114:117], v[174:177], v[182:185], v[114:117]
	v_mfma_f32_16x16x32_bf16 v[106:109], v[166:169], v[190:193], v[106:109]
	v_mfma_f32_16x16x32_bf16 v[98:101], v[174:177], v[190:193], v[98:101]
	v_mfma_f32_16x16x32_bf16 v[90:93], v[166:169], v[198:201], v[90:93]
	v_mfma_f32_16x16x32_bf16 v[82:85], v[174:177], v[198:201], v[82:85]
	v_mfma_f32_16x16x32_bf16 v[74:77], v[166:169], v[212:215], v[74:77]
	v_mfma_f32_16x16x32_bf16 v[66:69], v[174:177], v[212:215], v[66:69]
	s_barrier
	s_setprio 0
	s_add_i32 s0, s33, s26
	s_add_u32 s100, s20, 0x80
	s_addc_u32 s101, s21, 0
	s_mov_b32 m0, s0
	ds_read_b128 v[178:181], v145 offset:49152
	ds_read_b128 v[182:185], v145 offset:50176
	ds_read_b128 v[186:189], v145 offset:51200
	ds_read_b128 v[190:193], v145 offset:52224
	ds_read_b128 v[194:197], v145 offset:53248
	ds_read_b128 v[198:201], v145 offset:54272
	ds_read_b128 v[208:211], v145 offset:55296
	ds_read_b128 v[212:215], v145 offset:56320
	global_load_lds_dwordx4 v202, s[100:101]
	s_add_i32 m0, s0, 0x2000
	s_add_u32 s100, s20, 0x80
	s_addc_u32 s101, s21, 0
	s_add_u32 s0, s20, 0x80080
	s_addc_u32 s1, s21, 0
	s_add_i32 s20, s55, s26
	global_load_lds_dwordx4 v130, s[100:101]
	s_mov_b32 m0, s20
	s_nop 0
	global_load_lds_dwordx4 v202, s[0:1]
	s_add_i32 m0, s20, 0x2000
	s_nop 0
	global_load_lds_dwordx4 v130, s[0:1]
	s_add_u32 s100, s22, 0x80
	s_addc_u32 s101, s23, 0
	s_mov_b32 m0, s31
	s_nop 0
	global_load_lds_dwordx4 v134, s[100:101]
	s_add_u32 s100, s22, 0x80
	s_addc_u32 s101, s23, 0
	s_mov_b32 m0, s34
	s_nop 0
	global_load_lds_dwordx4 v132, s[100:101]
	s_waitcnt vmcnt(8)
	s_waitcnt lgkmcnt(0)
	s_setprio 1
	s_barrier
	v_mfma_f32_16x16x32_bf16 v[62:65], v[146:149], v[178:181], v[62:65]
	v_mfma_f32_16x16x32_bf16 v[54:57], v[154:157], v[178:181], v[54:57]
	v_mfma_f32_16x16x32_bf16 v[46:49], v[146:149], v[186:189], v[46:49]
	v_mfma_f32_16x16x32_bf16 v[38:41], v[154:157], v[186:189], v[38:41]
	v_mfma_f32_16x16x32_bf16 v[30:33], v[146:149], v[194:197], v[30:33]
	v_mfma_f32_16x16x32_bf16 v[22:25], v[154:157], v[194:197], v[22:25]
	v_mfma_f32_16x16x32_bf16 v[14:17], v[146:149], v[208:211], v[14:17]
	v_mfma_f32_16x16x32_bf16 v[6:9], v[154:157], v[208:211], v[6:9]
	v_mfma_f32_16x16x32_bf16 v[62:65], v[150:153], v[182:185], v[62:65]
	v_mfma_f32_16x16x32_bf16 v[54:57], v[158:161], v[182:185], v[54:57]
	v_mfma_f32_16x16x32_bf16 v[46:49], v[150:153], v[190:193], v[46:49]
	v_mfma_f32_16x16x32_bf16 v[38:41], v[158:161], v[190:193], v[38:41]
	v_mfma_f32_16x16x32_bf16 v[30:33], v[150:153], v[198:201], v[30:33]
	v_mfma_f32_16x16x32_bf16 v[22:25], v[158:161], v[198:201], v[22:25]
	v_mfma_f32_16x16x32_bf16 v[14:17], v[150:153], v[212:215], v[14:17]
	v_mfma_f32_16x16x32_bf16 v[6:9], v[158:161], v[212:215], v[6:9]
	s_setprio 0
	s_setprio 1
	v_mfma_f32_16x16x32_bf16 v[58:61], v[162:165], v[178:181], v[58:61]
	v_mfma_f32_16x16x32_bf16 v[50:53], v[170:173], v[178:181], v[50:53]
	v_mfma_f32_16x16x32_bf16 v[42:45], v[162:165], v[186:189], v[42:45]
	v_mfma_f32_16x16x32_bf16 v[34:37], v[170:173], v[186:189], v[34:37]
	v_mfma_f32_16x16x32_bf16 v[26:29], v[162:165], v[194:197], v[26:29]
	v_mfma_f32_16x16x32_bf16 v[18:21], v[170:173], v[194:197], v[18:21]
	v_mfma_f32_16x16x32_bf16 v[10:13], v[162:165], v[208:211], v[10:13]
	v_mfma_f32_16x16x32_bf16 v[2:5], v[170:173], v[208:211], v[2:5]
	v_mfma_f32_16x16x32_bf16 v[58:61], v[166:169], v[182:185], v[58:61]
	v_mfma_f32_16x16x32_bf16 v[50:53], v[174:177], v[182:185], v[50:53]
	v_mfma_f32_16x16x32_bf16 v[42:45], v[166:169], v[190:193], v[42:45]
	v_mfma_f32_16x16x32_bf16 v[34:37], v[174:177], v[190:193], v[34:37]
	v_mfma_f32_16x16x32_bf16 v[26:29], v[166:169], v[198:201], v[26:29]
	v_mfma_f32_16x16x32_bf16 v[18:21], v[174:177], v[198:201], v[18:21]
	v_mfma_f32_16x16x32_bf16 v[10:13], v[166:169], v[212:215], v[10:13]
	v_mfma_f32_16x16x32_bf16 v[2:5], v[174:177], v[212:215], v[2:5]
	s_barrier
	s_setprio 0
	s_add_i32 s59, s59, 2
	s_add_u32 s18, s18, 0x100
	s_addc_u32 s19, s19, 0
	s_add_u32 s49, s49, 0x100
	s_addc_u32 s58, s58, 0
	s_cmp_gt_u32 s59, 29
	s_cbranch_scc0 .LBB0_837
	s_and_b64 vcc, exec, s[6:7]
	s_cbranch_vccz .LBB0_840
	s_barrier

.LBB0_970:
	s_add_u32 s16, s2, 0x100
	s_addc_u32 s17, s3, 0
	s_add_i32 s0, 0, 0x10000
	s_cmpk_eq_i32 s59, 0x54
	s_cselect_b32 s21, s7, s17
	s_cselect_b32 s20, s6, s16
	s_cselect_b32 s19, s15, s58
	s_cselect_b32 s18, s14, s49
	s_add_i32 s33, 0, 0x14000
	v_add_u32_e32 v98, s0, v205
	v_add_u32_e32 v134, s33, v205
	ds_read_b128 v[78:81], v98
	ds_read_b128 v[82:85], v98 offset:1024
	ds_read_b128 v[94:97], v98 offset:2048
	ds_read_b128 v[98:101], v98 offset:3072
	ds_read_b128 v[106:109], v134
	ds_read_b128 v[110:113], v134 offset:1024
	ds_read_b128 v[126:129], v134 offset:2048
	ds_read_b128 v[134:137], v134 offset:3072
	s_add_i32 m0, s25, 0xc000
	ds_read_b128 v[146:149], v239
	ds_read_b128 v[158:161], v239 offset:1024
	ds_read_b128 v[166:169], v239 offset:2048
	ds_read_b128 v[174:177], v239 offset:3072
	ds_read_b128 v[178:181], v239 offset:4096
	ds_read_b128 v[182:185], v239 offset:5120
	ds_read_b128 v[186:189], v239 offset:6144
	ds_read_b128 v[190:193], v239 offset:7168
	global_load_lds_dwordx4 v214, s[2:3]
	s_add_i32 m0, s25, 0xe000
	s_nop 0
	global_load_lds_dwordx4 v216, s[2:3]
	s_waitcnt vmcnt(8)
	s_waitcnt lgkmcnt(0)
	s_setprio 1
	s_barrier
	v_mfma_f32_16x16x32_bf16 v[170:173], v[78:81], v[146:149], v[170:173]
	v_mfma_f32_16x16x32_bf16 v[162:165], v[94:97], v[146:149], v[162:165]
	v_mfma_f32_16x16x32_bf16 v[142:145], v[78:81], v[166:169], v[142:145]
	v_mfma_f32_16x16x32_bf16 v[138:141], v[94:97], v[166:169], v[138:141]
	v_mfma_f32_16x16x32_bf16 v[118:121], v[78:81], v[178:181], v[118:121]
	v_mfma_f32_16x16x32_bf16 v[114:117], v[94:97], v[178:181], v[114:117]
	v_mfma_f32_16x16x32_bf16 v[86:89], v[78:81], v[186:189], v[86:89]
	v_mfma_f32_16x16x32_bf16 v[74:77], v[94:97], v[186:189], v[74:77]
	v_mfma_f32_16x16x32_bf16 v[170:173], v[82:85], v[158:161], v[170:173]
	v_mfma_f32_16x16x32_bf16 v[162:165], v[98:101], v[158:161], v[162:165]
	v_mfma_f32_16x16x32_bf16 v[142:145], v[82:85], v[174:177], v[142:145]
	v_mfma_f32_16x16x32_bf16 v[138:141], v[98:101], v[174:177], v[138:141]
	v_mfma_f32_16x16x32_bf16 v[118:121], v[82:85], v[182:185], v[118:121]
	v_mfma_f32_16x16x32_bf16 v[114:117], v[98:101], v[182:185], v[114:117]
	v_mfma_f32_16x16x32_bf16 v[86:89], v[82:85], v[190:193], v[86:89]
	v_mfma_f32_16x16x32_bf16 v[74:77], v[98:101], v[190:193], v[74:77]
	s_setprio 0
	s_setprio 1
	v_mfma_f32_16x16x32_bf16 v[154:157], v[106:109], v[146:149], v[154:157]
	v_mfma_f32_16x16x32_bf16 v[130:133], v[106:109], v[166:169], v[130:133]
	v_mfma_f32_16x16x32_bf16 v[122:125], v[126:129], v[166:169], v[122:125]
	v_mfma_f32_16x16x32_bf16 v[102:105], v[106:109], v[178:181], v[102:105]
	v_mfma_f32_16x16x32_bf16 v[90:93], v[126:129], v[178:181], v[90:93]
	v_mfma_f32_16x16x32_bf16 v[70:73], v[106:109], v[186:189], v[70:73]
	v_mfma_f32_16x16x32_bf16 v[66:69], v[126:129], v[186:189], v[66:69]
	v_mfma_f32_16x16x32_bf16 v[154:157], v[110:113], v[158:161], v[154:157]
	v_mfma_f32_16x16x32_bf16 v[146:149], v[126:129], v[146:149], v[150:153]
	v_mfma_f32_16x16x32_bf16 v[130:133], v[110:113], v[174:177], v[130:133]
	v_mfma_f32_16x16x32_bf16 v[122:125], v[134:137], v[174:177], v[122:125]
	v_mfma_f32_16x16x32_bf16 v[102:105], v[110:113], v[182:185], v[102:105]
	v_mfma_f32_16x16x32_bf16 v[90:93], v[134:137], v[182:185], v[90:93]
	v_mfma_f32_16x16x32_bf16 v[70:73], v[110:113], v[190:193], v[70:73]
	v_mfma_f32_16x16x32_bf16 v[66:69], v[134:137], v[190:193], v[66:69]
	v_mfma_f32_16x16x32_bf16 v[146:149], v[134:137], v[158:161], v[146:149]
	s_barrier
	s_setprio 0
	s_add_i32 s0, s0, s24
	s_mov_b32 m0, s0
	ds_read_b128 v[150:153], v239 offset:16384
	ds_read_b128 v[158:161], v239 offset:17408
	ds_read_b128 v[166:169], v239 offset:18432
	ds_read_b128 v[174:177], v239 offset:19456
	ds_read_b128 v[178:181], v239 offset:20480
	ds_read_b128 v[182:185], v239 offset:21504
	ds_read_b128 v[186:189], v239 offset:22528
	ds_read_b128 v[190:193], v239 offset:23552
	global_load_lds_dwordx4 v202, s[18:19]
	s_add_i32 m0, s0, 0x2000
	s_add_u32 s0, s18, 0x160000
	s_addc_u32 s1, s19, 0
	s_add_i32 s2, s33, s24
	global_load_lds_dwordx4 v208, s[18:19]
	s_mov_b32 m0, s2
	s_nop 0
	global_load_lds_dwordx4 v202, s[0:1]
	s_add_i32 m0, s2, 0x2000
	s_nop 0
	global_load_lds_dwordx4 v208, s[0:1]
	s_mov_b32 m0, s25
	s_nop 0
	global_load_lds_dwordx4 v212, s[20:21]
	s_mov_b32 m0, s26
	s_nop 0
	global_load_lds_dwordx4 v210, s[20:21]
	s_waitcnt vmcnt(8)
	s_waitcnt lgkmcnt(0)
	s_setprio 1
	s_barrier
	v_mfma_f32_16x16x32_bf16 v[62:65], v[78:81], v[150:153], v[62:65]
	v_mfma_f32_16x16x32_bf16 v[58:61], v[94:97], v[150:153], v[58:61]
	v_mfma_f32_16x16x32_bf16 v[46:49], v[78:81], v[166:169], v[46:49]
	v_mfma_f32_16x16x32_bf16 v[42:45], v[94:97], v[166:169], v[42:45]
	v_mfma_f32_16x16x32_bf16 v[30:33], v[78:81], v[178:181], v[30:33]
	v_mfma_f32_16x16x32_bf16 v[26:29], v[94:97], v[178:181], v[26:29]
	v_mfma_f32_16x16x32_bf16 v[14:17], v[78:81], v[186:189], v[14:17]
	v_mfma_f32_16x16x32_bf16 v[10:13], v[94:97], v[186:189], v[10:13]
	v_mfma_f32_16x16x32_bf16 v[62:65], v[82:85], v[158:161], v[62:65]
	v_mfma_f32_16x16x32_bf16 v[58:61], v[98:101], v[158:161], v[58:61]
	v_mfma_f32_16x16x32_bf16 v[46:49], v[82:85], v[174:177], v[46:49]
	v_mfma_f32_16x16x32_bf16 v[42:45], v[98:101], v[174:177], v[42:45]
	v_mfma_f32_16x16x32_bf16 v[30:33], v[82:85], v[182:185], v[30:33]
	v_mfma_f32_16x16x32_bf16 v[26:29], v[98:101], v[182:185], v[26:29]
	v_mfma_f32_16x16x32_bf16 v[14:17], v[82:85], v[190:193], v[14:17]
	v_mfma_f32_16x16x32_bf16 v[10:13], v[98:101], v[190:193], v[10:13]
	s_setprio 0
	s_setprio 1
	v_mfma_f32_16x16x32_bf16 v[54:57], v[106:109], v[150:153], v[54:57]
	v_mfma_f32_16x16x32_bf16 v[50:53], v[126:129], v[150:153], v[50:53]
	v_mfma_f32_16x16x32_bf16 v[38:41], v[106:109], v[166:169], v[38:41]
	v_mfma_f32_16x16x32_bf16 v[34:37], v[126:129], v[166:169], v[34:37]
	v_mfma_f32_16x16x32_bf16 v[22:25], v[106:109], v[178:181], v[22:25]
	v_mfma_f32_16x16x32_bf16 v[18:21], v[126:129], v[178:181], v[18:21]
	v_mfma_f32_16x16x32_bf16 v[6:9], v[106:109], v[186:189], v[6:9]
	v_mfma_f32_16x16x32_bf16 v[2:5], v[126:129], v[186:189], v[2:5]
	v_mfma_f32_16x16x32_bf16 v[54:57], v[110:113], v[158:161], v[54:57]
	v_mfma_f32_16x16x32_bf16 v[50:53], v[134:137], v[158:161], v[50:53]
	v_mfma_f32_16x16x32_bf16 v[38:41], v[110:113], v[174:177], v[38:41]
	v_mfma_f32_16x16x32_bf16 v[34:37], v[134:137], v[174:177], v[34:37]
	v_mfma_f32_16x16x32_bf16 v[22:25], v[110:113], v[182:185], v[22:25]
	v_mfma_f32_16x16x32_bf16 v[18:21], v[134:137], v[182:185], v[18:21]
	v_mfma_f32_16x16x32_bf16 v[6:9], v[110:113], v[190:193], v[6:9]
	v_mfma_f32_16x16x32_bf16 v[2:5], v[134:137], v[190:193], v[2:5]
	s_barrier
	s_setprio 0
	s_add_i32 s2, 0, 0x18000
	s_add_i32 s3, 0, 0x1c000
	v_add_u32_e32 v98, s2, v205
	v_add_u32_e32 v134, s3, v205
	ds_read_b128 v[78:81], v98
	ds_read_b128 v[82:85], v98 offset:1024
	ds_read_b128 v[94:97], v98 offset:2048
	ds_read_b128 v[98:101], v98 offset:3072
	ds_read_b128 v[106:109], v134
	ds_read_b128 v[110:113], v134 offset:1024
	ds_read_b128 v[126:129], v134 offset:2048
	ds_read_b128 v[134:137], v134 offset:3072
	s_add_u32 s0, s20, 0x160000
	s_addc_u32 s1, s21, 0
	s_mov_b32 m0, s27
	ds_read_b128 v[150:153], v239 offset:32768
	ds_read_b128 v[158:161], v239 offset:33792
	ds_read_b128 v[166:169], v239 offset:34816
	ds_read_b128 v[174:177], v239 offset:35840
	ds_read_b128 v[178:181], v239 offset:36864
	ds_read_b128 v[182:185], v239 offset:37888
	ds_read_b128 v[186:189], v239 offset:38912
	ds_read_b128 v[190:193], v239 offset:39936
	global_load_lds_dwordx4 v212, s[0:1]
	s_mov_b32 m0, s28
	s_nop 0
	global_load_lds_dwordx4 v210, s[0:1]
	s_waitcnt vmcnt(8)
	s_waitcnt lgkmcnt(0)
	s_setprio 1
	s_barrier
	v_mfma_f32_16x16x32_bf16 v[170:173], v[78:81], v[150:153], v[170:173]
	v_mfma_f32_16x16x32_bf16 v[162:165], v[94:97], v[150:153], v[162:165]
	v_mfma_f32_16x16x32_bf16 v[142:145], v[78:81], v[166:169], v[142:145]
	v_mfma_f32_16x16x32_bf16 v[138:141], v[94:97], v[166:169], v[138:141]
	v_mfma_f32_16x16x32_bf16 v[118:121], v[78:81], v[178:181], v[118:121]
	v_mfma_f32_16x16x32_bf16 v[114:117], v[94:97], v[178:181], v[114:117]
	v_mfma_f32_16x16x32_bf16 v[86:89], v[78:81], v[186:189], v[86:89]
	v_mfma_f32_16x16x32_bf16 v[74:77], v[94:97], v[186:189], v[74:77]
	v_mfma_f32_16x16x32_bf16 v[170:173], v[82:85], v[158:161], v[170:173]
	v_mfma_f32_16x16x32_bf16 v[162:165], v[98:101], v[158:161], v[162:165]
	v_mfma_f32_16x16x32_bf16 v[142:145], v[82:85], v[174:177], v[142:145]
	v_mfma_f32_16x16x32_bf16 v[138:141], v[98:101], v[174:177], v[138:141]
	v_mfma_f32_16x16x32_bf16 v[118:121], v[82:85], v[182:185], v[118:121]
	v_mfma_f32_16x16x32_bf16 v[114:117], v[98:101], v[182:185], v[114:117]
	v_mfma_f32_16x16x32_bf16 v[86:89], v[82:85], v[190:193], v[86:89]
	v_mfma_f32_16x16x32_bf16 v[74:77], v[98:101], v[190:193], v[74:77]
	s_setprio 0
	s_setprio 1
	v_mfma_f32_16x16x32_bf16 v[154:157], v[106:109], v[150:153], v[154:157]
	v_mfma_f32_16x16x32_bf16 v[146:149], v[126:129], v[150:153], v[146:149]
	v_mfma_f32_16x16x32_bf16 v[130:133], v[106:109], v[166:169], v[130:133]
	v_mfma_f32_16x16x32_bf16 v[122:125], v[126:129], v[166:169], v[122:125]
	v_mfma_f32_16x16x32_bf16 v[102:105], v[106:109], v[178:181], v[102:105]
	v_mfma_f32_16x16x32_bf16 v[90:93], v[126:129], v[178:181], v[90:93]
	v_mfma_f32_16x16x32_bf16 v[70:73], v[106:109], v[186:189], v[70:73]
	v_mfma_f32_16x16x32_bf16 v[66:69], v[126:129], v[186:189], v[66:69]
	v_mfma_f32_16x16x32_bf16 v[154:157], v[110:113], v[158:161], v[154:157]
	v_mfma_f32_16x16x32_bf16 v[150:153], v[134:137], v[158:161], v[146:149]
	v_mfma_f32_16x16x32_bf16 v[130:133], v[110:113], v[174:177], v[130:133]
	v_mfma_f32_16x16x32_bf16 v[122:125], v[134:137], v[174:177], v[122:125]
	v_mfma_f32_16x16x32_bf16 v[102:105], v[110:113], v[182:185], v[102:105]
	v_mfma_f32_16x16x32_bf16 v[90:93], v[134:137], v[182:185], v[90:93]
	v_mfma_f32_16x16x32_bf16 v[70:73], v[110:113], v[190:193], v[70:73]
	v_mfma_f32_16x16x32_bf16 v[66:69], v[134:137], v[190:193], v[66:69]
	s_barrier
	s_setprio 0
	s_add_i32 s0, s2, s24
	s_add_u32 s100, s18, 0x80
	s_addc_u32 s101, s19, 0
	s_mov_b32 m0, s0
	ds_read_b128 v[146:149], v239 offset:49152
	ds_read_b128 v[158:161], v239 offset:50176
	ds_read_b128 v[166:169], v239 offset:51200
	ds_read_b128 v[174:177], v239 offset:52224
	ds_read_b128 v[178:181], v239 offset:53248
	ds_read_b128 v[182:185], v239 offset:54272
	ds_read_b128 v[186:189], v239 offset:55296
	ds_read_b128 v[190:193], v239 offset:56320
	global_load_lds_dwordx4 v202, s[100:101]
	s_add_i32 m0, s0, 0x2000
	s_add_u32 s100, s18, 0x80
	s_addc_u32 s101, s19, 0
	s_add_u32 s0, s18, 0x160080
	s_addc_u32 s1, s19, 0
	s_add_i32 s2, s3, s24
	global_load_lds_dwordx4 v208, s[100:101]
	s_mov_b32 m0, s2
	s_nop 0
	global_load_lds_dwordx4 v202, s[0:1]
	s_add_i32 m0, s2, 0x2000
	s_nop 0
	global_load_lds_dwordx4 v208, s[0:1]
	s_add_u32 s100, s20, 0x80
	s_addc_u32 s101, s21, 0
	s_mov_b32 m0, s31
	s_nop 0
	global_load_lds_dwordx4 v212, s[100:101]
	s_add_u32 s100, s20, 0x80
	s_addc_u32 s101, s21, 0
	s_mov_b32 m0, s34
	s_nop 0
	global_load_lds_dwordx4 v210, s[100:101]
	s_waitcnt vmcnt(8)
	s_waitcnt lgkmcnt(0)
	s_setprio 1
	s_barrier
	v_mfma_f32_16x16x32_bf16 v[62:65], v[78:81], v[146:149], v[62:65]
	v_mfma_f32_16x16x32_bf16 v[58:61], v[94:97], v[146:149], v[58:61]
	v_mfma_f32_16x16x32_bf16 v[46:49], v[78:81], v[166:169], v[46:49]
	v_mfma_f32_16x16x32_bf16 v[42:45], v[94:97], v[166:169], v[42:45]
	v_mfma_f32_16x16x32_bf16 v[30:33], v[78:81], v[178:181], v[30:33]
	v_mfma_f32_16x16x32_bf16 v[26:29], v[94:97], v[178:181], v[26:29]
	v_mfma_f32_16x16x32_bf16 v[14:17], v[78:81], v[186:189], v[14:17]
	v_mfma_f32_16x16x32_bf16 v[10:13], v[94:97], v[186:189], v[10:13]
	v_mfma_f32_16x16x32_bf16 v[62:65], v[82:85], v[158:161], v[62:65]
	v_mfma_f32_16x16x32_bf16 v[58:61], v[98:101], v[158:161], v[58:61]
	v_mfma_f32_16x16x32_bf16 v[46:49], v[82:85], v[174:177], v[46:49]
	v_mfma_f32_16x16x32_bf16 v[42:45], v[98:101], v[174:177], v[42:45]
	v_mfma_f32_16x16x32_bf16 v[30:33], v[82:85], v[182:185], v[30:33]
	v_mfma_f32_16x16x32_bf16 v[26:29], v[98:101], v[182:185], v[26:29]
	v_mfma_f32_16x16x32_bf16 v[14:17], v[82:85], v[190:193], v[14:17]
	v_mfma_f32_16x16x32_bf16 v[10:13], v[98:101], v[190:193], v[10:13]
	s_setprio 0
	s_setprio 1
	v_mfma_f32_16x16x32_bf16 v[54:57], v[106:109], v[146:149], v[54:57]
	v_mfma_f32_16x16x32_bf16 v[50:53], v[126:129], v[146:149], v[50:53]
	v_mfma_f32_16x16x32_bf16 v[38:41], v[106:109], v[166:169], v[38:41]
	v_mfma_f32_16x16x32_bf16 v[34:37], v[126:129], v[166:169], v[34:37]
	v_mfma_f32_16x16x32_bf16 v[22:25], v[106:109], v[178:181], v[22:25]
	v_mfma_f32_16x16x32_bf16 v[18:21], v[126:129], v[178:181], v[18:21]
	v_mfma_f32_16x16x32_bf16 v[6:9], v[106:109], v[186:189], v[6:9]
	v_mfma_f32_16x16x32_bf16 v[2:5], v[126:129], v[186:189], v[2:5]
	v_mfma_f32_16x16x32_bf16 v[54:57], v[110:113], v[158:161], v[54:57]
	v_mfma_f32_16x16x32_bf16 v[50:53], v[134:137], v[158:161], v[50:53]
	v_mfma_f32_16x16x32_bf16 v[38:41], v[110:113], v[174:177], v[38:41]
	v_mfma_f32_16x16x32_bf16 v[34:37], v[134:137], v[174:177], v[34:37]
	v_mfma_f32_16x16x32_bf16 v[22:25], v[110:113], v[182:185], v[22:25]
	v_mfma_f32_16x16x32_bf16 v[18:21], v[134:137], v[182:185], v[18:21]
	v_mfma_f32_16x16x32_bf16 v[6:9], v[110:113], v[190:193], v[6:9]
	v_mfma_f32_16x16x32_bf16 v[2:5], v[134:137], v[190:193], v[2:5]
	s_barrier
	s_setprio 0
	s_add_i32 s59, s59, 2
	s_add_u32 s49, s49, 0x100
	s_addc_u32 s58, s58, 0
	s_cmpk_gt_u32 s59, 0x55
	s_mov_b64 s[2:3], s[16:17]
	s_cbranch_scc0 .LBB0_970
	s_and_b64 vcc, exec, s[10:11]
	s_cbranch_vccz .LBB0_973
	s_barrier

.LBB0_990:
	s_add_u32 s4, s2, 0x100
	s_addc_u32 s5, s3, 0
	s_add_i32 s0, 0, 0x10000
	s_cmp_eq_u32 s59, 4
	s_cselect_b32 s21, s15, s5
	s_cselect_b32 s20, s14, s4
	s_cselect_b32 s19, s17, s58
	s_cselect_b32 s18, s16, s49
	s_add_i32 s33, 0, 0x14000
	v_add_u32_e32 v152, s0, v136
	v_add_u32_e32 v168, s33, v136
	ds_read_b128 v[140:143], v152
	ds_read_b128 v[144:147], v152 offset:1024
	ds_read_b128 v[148:151], v152 offset:2048
	ds_read_b128 v[152:155], v152 offset:3072
	ds_read_b128 v[156:159], v168
	ds_read_b128 v[160:163], v168 offset:1024
	ds_read_b128 v[164:167], v168 offset:2048
	ds_read_b128 v[168:171], v168 offset:3072
	s_add_i32 m0, s25, 0xc000
	ds_read_b128 v[172:175], v139
	ds_read_b128 v[176:179], v139 offset:1024
	ds_read_b128 v[180:183], v139 offset:2048
	ds_read_b128 v[184:187], v139 offset:3072
	ds_read_b128 v[188:191], v139 offset:4096
	ds_read_b128 v[192:195], v139 offset:5120
	ds_read_b128 v[196:199], v139 offset:6144
	ds_read_b128 v[208:211], v139 offset:7168
	global_load_lds_dwordx4 v132, s[2:3]
	s_add_i32 m0, s25, 0xe000
	s_nop 0
	global_load_lds_dwordx4 v134, s[2:3]
	s_waitcnt vmcnt(8)
	s_waitcnt lgkmcnt(0)
	s_setprio 1
	s_barrier
	v_mfma_f32_16x16x32_bf16 v[126:129], v[140:143], v[172:175], v[126:129]
	v_mfma_f32_16x16x32_bf16 v[122:125], v[148:151], v[172:175], v[122:125]
	v_mfma_f32_16x16x32_bf16 v[118:121], v[140:143], v[180:183], v[118:121]
	v_mfma_f32_16x16x32_bf16 v[114:117], v[148:151], v[180:183], v[114:117]
	v_mfma_f32_16x16x32_bf16 v[106:109], v[140:143], v[188:191], v[106:109]
	v_mfma_f32_16x16x32_bf16 v[98:101], v[148:151], v[188:191], v[98:101]
	v_mfma_f32_16x16x32_bf16 v[90:93], v[140:143], v[196:199], v[90:93]
	v_mfma_f32_16x16x32_bf16 v[82:85], v[148:151], v[196:199], v[82:85]
	v_mfma_f32_16x16x32_bf16 v[126:129], v[144:147], v[176:179], v[126:129]
	v_mfma_f32_16x16x32_bf16 v[122:125], v[152:155], v[176:179], v[122:125]
	v_mfma_f32_16x16x32_bf16 v[118:121], v[144:147], v[184:187], v[118:121]
	v_mfma_f32_16x16x32_bf16 v[114:117], v[152:155], v[184:187], v[114:117]
	v_mfma_f32_16x16x32_bf16 v[106:109], v[144:147], v[192:195], v[106:109]
	v_mfma_f32_16x16x32_bf16 v[98:101], v[152:155], v[192:195], v[98:101]
	v_mfma_f32_16x16x32_bf16 v[90:93], v[144:147], v[208:211], v[90:93]
	v_mfma_f32_16x16x32_bf16 v[82:85], v[152:155], v[208:211], v[82:85]
	s_setprio 0
	s_setprio 1
	v_mfma_f32_16x16x32_bf16 v[110:113], v[156:159], v[172:175], v[110:113]
	v_mfma_f32_16x16x32_bf16 v[102:105], v[164:167], v[172:175], v[102:105]
	v_mfma_f32_16x16x32_bf16 v[94:97], v[156:159], v[180:183], v[94:97]
	v_mfma_f32_16x16x32_bf16 v[86:89], v[164:167], v[180:183], v[86:89]
	v_mfma_f32_16x16x32_bf16 v[78:81], v[156:159], v[188:191], v[78:81]
	v_mfma_f32_16x16x32_bf16 v[74:77], v[164:167], v[188:191], v[74:77]
	v_mfma_f32_16x16x32_bf16 v[70:73], v[156:159], v[196:199], v[70:73]
	v_mfma_f32_16x16x32_bf16 v[66:69], v[164:167], v[196:199], v[66:69]
	v_mfma_f32_16x16x32_bf16 v[110:113], v[160:163], v[176:179], v[110:113]
	v_mfma_f32_16x16x32_bf16 v[102:105], v[168:171], v[176:179], v[102:105]
	v_mfma_f32_16x16x32_bf16 v[94:97], v[160:163], v[184:187], v[94:97]
	v_mfma_f32_16x16x32_bf16 v[86:89], v[168:171], v[184:187], v[86:89]
	v_mfma_f32_16x16x32_bf16 v[78:81], v[160:163], v[192:195], v[78:81]
	v_mfma_f32_16x16x32_bf16 v[74:77], v[168:171], v[192:195], v[74:77]
	v_mfma_f32_16x16x32_bf16 v[70:73], v[160:163], v[208:211], v[70:73]
	v_mfma_f32_16x16x32_bf16 v[66:69], v[168:171], v[208:211], v[66:69]
	s_barrier
	s_setprio 0
	s_add_i32 s0, s0, s24
	s_mov_b32 m0, s0
	ds_read_b128 v[172:175], v139 offset:16384
	ds_read_b128 v[176:179], v139 offset:17408
	ds_read_b128 v[180:183], v139 offset:18432
	ds_read_b128 v[184:187], v139 offset:19456
	ds_read_b128 v[188:191], v139 offset:20480
	ds_read_b128 v[192:195], v139 offset:21504
	ds_read_b128 v[196:199], v139 offset:22528
	ds_read_b128 v[208:211], v139 offset:23552
	global_load_lds_dwordx4 v202, s[18:19]
	s_add_i32 m0, s0, 0x2000
	s_add_u32 s0, s18, 0x160000
	s_addc_u32 s1, s19, 0
	s_add_i32 s2, s33, s24
	global_load_lds_dwordx4 v130, s[18:19]
	s_mov_b32 m0, s2
	s_nop 0
	global_load_lds_dwordx4 v202, s[0:1]
	s_add_i32 m0, s2, 0x2000
	s_nop 0
	global_load_lds_dwordx4 v130, s[0:1]
	s_mov_b32 m0, s25
	s_nop 0
	global_load_lds_dwordx4 v202, s[20:21]
	s_mov_b32 m0, s26
	s_nop 0
	global_load_lds_dwordx4 v130, s[20:21]
	s_waitcnt vmcnt(8)
	s_waitcnt lgkmcnt(0)
	s_setprio 1
	s_barrier
	v_mfma_f32_16x16x32_bf16 v[62:65], v[140:143], v[172:175], v[62:65]
	v_mfma_f32_16x16x32_bf16 v[58:61], v[148:151], v[172:175], v[58:61]
	v_mfma_f32_16x16x32_bf16 v[54:57], v[140:143], v[180:183], v[54:57]
	v_mfma_f32_16x16x32_bf16 v[50:53], v[148:151], v[180:183], v[50:53]
	v_mfma_f32_16x16x32_bf16 v[38:41], v[140:143], v[188:191], v[38:41]
	v_mfma_f32_16x16x32_bf16 v[34:37], v[148:151], v[188:191], v[34:37]
	v_mfma_f32_16x16x32_bf16 v[22:25], v[140:143], v[196:199], v[22:25]
	v_mfma_f32_16x16x32_bf16 v[18:21], v[148:151], v[196:199], v[18:21]
	v_mfma_f32_16x16x32_bf16 v[62:65], v[144:147], v[176:179], v[62:65]
	v_mfma_f32_16x16x32_bf16 v[58:61], v[152:155], v[176:179], v[58:61]
	v_mfma_f32_16x16x32_bf16 v[54:57], v[144:147], v[184:187], v[54:57]
	v_mfma_f32_16x16x32_bf16 v[50:53], v[152:155], v[184:187], v[50:53]
	v_mfma_f32_16x16x32_bf16 v[38:41], v[144:147], v[192:195], v[38:41]
	v_mfma_f32_16x16x32_bf16 v[34:37], v[152:155], v[192:195], v[34:37]
	v_mfma_f32_16x16x32_bf16 v[22:25], v[144:147], v[208:211], v[22:25]
	v_mfma_f32_16x16x32_bf16 v[18:21], v[152:155], v[208:211], v[18:21]
	s_setprio 0
	s_setprio 1
	v_mfma_f32_16x16x32_bf16 v[46:49], v[156:159], v[172:175], v[46:49]
	v_mfma_f32_16x16x32_bf16 v[42:45], v[164:167], v[172:175], v[42:45]
	v_mfma_f32_16x16x32_bf16 v[30:33], v[156:159], v[180:183], v[30:33]
	v_mfma_f32_16x16x32_bf16 v[26:29], v[164:167], v[180:183], v[26:29]
	v_mfma_f32_16x16x32_bf16 v[14:17], v[156:159], v[188:191], v[14:17]
	v_mfma_f32_16x16x32_bf16 v[10:13], v[164:167], v[188:191], v[10:13]
	v_mfma_f32_16x16x32_bf16 v[6:9], v[156:159], v[196:199], v[6:9]
	v_mfma_f32_16x16x32_bf16 v[2:5], v[164:167], v[196:199], v[2:5]
	v_mfma_f32_16x16x32_bf16 v[46:49], v[160:163], v[176:179], v[46:49]
	v_mfma_f32_16x16x32_bf16 v[42:45], v[168:171], v[176:179], v[42:45]
	v_mfma_f32_16x16x32_bf16 v[30:33], v[160:163], v[184:187], v[30:33]
	v_mfma_f32_16x16x32_bf16 v[26:29], v[168:171], v[184:187], v[26:29]
	v_mfma_f32_16x16x32_bf16 v[14:17], v[160:163], v[192:195], v[14:17]
	v_mfma_f32_16x16x32_bf16 v[10:13], v[168:171], v[192:195], v[10:13]
	v_mfma_f32_16x16x32_bf16 v[6:9], v[160:163], v[208:211], v[6:9]
	v_mfma_f32_16x16x32_bf16 v[2:5], v[168:171], v[208:211], v[2:5]
	s_barrier
	s_setprio 0
	s_add_i32 s2, 0, 0x18000
	s_add_i32 s3, 0, 0x1c000
	v_add_u32_e32 v152, s2, v136
	v_add_u32_e32 v168, s3, v136
	ds_read_b128 v[140:143], v152
	ds_read_b128 v[144:147], v152 offset:1024
	ds_read_b128 v[148:151], v152 offset:2048
	ds_read_b128 v[152:155], v152 offset:3072
	ds_read_b128 v[156:159], v168
	ds_read_b128 v[160:163], v168 offset:1024
	ds_read_b128 v[164:167], v168 offset:2048
	ds_read_b128 v[168:171], v168 offset:3072
	s_add_u32 s0, s20, 0x160000
	s_addc_u32 s1, s21, 0
	s_mov_b32 m0, s27
	ds_read_b128 v[172:175], v139 offset:32768
	ds_read_b128 v[176:179], v139 offset:33792
	ds_read_b128 v[180:183], v139 offset:34816
	ds_read_b128 v[184:187], v139 offset:35840
	ds_read_b128 v[188:191], v139 offset:36864
	ds_read_b128 v[192:195], v139 offset:37888
	ds_read_b128 v[196:199], v139 offset:38912
	ds_read_b128 v[208:211], v139 offset:39936
	global_load_lds_dwordx4 v202, s[0:1]
	s_mov_b32 m0, s28
	s_nop 0
	global_load_lds_dwordx4 v130, s[0:1]
	s_waitcnt vmcnt(8)
	s_waitcnt lgkmcnt(0)
	s_setprio 1
	s_barrier
	v_mfma_f32_16x16x32_bf16 v[126:129], v[140:143], v[172:175], v[126:129]
	v_mfma_f32_16x16x32_bf16 v[122:125], v[148:151], v[172:175], v[122:125]
	v_mfma_f32_16x16x32_bf16 v[118:121], v[140:143], v[180:183], v[118:121]
	v_mfma_f32_16x16x32_bf16 v[114:117], v[148:151], v[180:183], v[114:117]
	v_mfma_f32_16x16x32_bf16 v[106:109], v[140:143], v[188:191], v[106:109]
	v_mfma_f32_16x16x32_bf16 v[98:101], v[148:151], v[188:191], v[98:101]
	v_mfma_f32_16x16x32_bf16 v[90:93], v[140:143], v[196:199], v[90:93]
	v_mfma_f32_16x16x32_bf16 v[82:85], v[148:151], v[196:199], v[82:85]
	v_mfma_f32_16x16x32_bf16 v[126:129], v[144:147], v[176:179], v[126:129]
	v_mfma_f32_16x16x32_bf16 v[122:125], v[152:155], v[176:179], v[122:125]
	v_mfma_f32_16x16x32_bf16 v[118:121], v[144:147], v[184:187], v[118:121]
	v_mfma_f32_16x16x32_bf16 v[114:117], v[152:155], v[184:187], v[114:117]
	v_mfma_f32_16x16x32_bf16 v[106:109], v[144:147], v[192:195], v[106:109]
	v_mfma_f32_16x16x32_bf16 v[98:101], v[152:155], v[192:195], v[98:101]
	v_mfma_f32_16x16x32_bf16 v[90:93], v[144:147], v[208:211], v[90:93]
	v_mfma_f32_16x16x32_bf16 v[82:85], v[152:155], v[208:211], v[82:85]
	s_setprio 0
	s_setprio 1
	v_mfma_f32_16x16x32_bf16 v[110:113], v[156:159], v[172:175], v[110:113]
	v_mfma_f32_16x16x32_bf16 v[102:105], v[164:167], v[172:175], v[102:105]
	v_mfma_f32_16x16x32_bf16 v[94:97], v[156:159], v[180:183], v[94:97]
	v_mfma_f32_16x16x32_bf16 v[86:89], v[164:167], v[180:183], v[86:89]
	v_mfma_f32_16x16x32_bf16 v[78:81], v[156:159], v[188:191], v[78:81]
	v_mfma_f32_16x16x32_bf16 v[74:77], v[164:167], v[188:191], v[74:77]
	v_mfma_f32_16x16x32_bf16 v[70:73], v[156:159], v[196:199], v[70:73]
	v_mfma_f32_16x16x32_bf16 v[66:69], v[164:167], v[196:199], v[66:69]
	v_mfma_f32_16x16x32_bf16 v[110:113], v[160:163], v[176:179], v[110:113]
	v_mfma_f32_16x16x32_bf16 v[102:105], v[168:171], v[176:179], v[102:105]
	v_mfma_f32_16x16x32_bf16 v[94:97], v[160:163], v[184:187], v[94:97]
	v_mfma_f32_16x16x32_bf16 v[86:89], v[168:171], v[184:187], v[86:89]
	v_mfma_f32_16x16x32_bf16 v[78:81], v[160:163], v[192:195], v[78:81]
	v_mfma_f32_16x16x32_bf16 v[74:77], v[168:171], v[192:195], v[74:77]
	v_mfma_f32_16x16x32_bf16 v[70:73], v[160:163], v[208:211], v[70:73]
	v_mfma_f32_16x16x32_bf16 v[66:69], v[168:171], v[208:211], v[66:69]
	s_barrier
	s_setprio 0
	s_add_i32 s0, s2, s24
	s_add_u32 s100, s18, 0x80
	s_addc_u32 s101, s19, 0
	s_mov_b32 m0, s0
	ds_read_b128 v[172:175], v139 offset:49152
	ds_read_b128 v[176:179], v139 offset:50176
	ds_read_b128 v[180:183], v139 offset:51200
	ds_read_b128 v[184:187], v139 offset:52224
	ds_read_b128 v[188:191], v139 offset:53248
	ds_read_b128 v[192:195], v139 offset:54272
	ds_read_b128 v[196:199], v139 offset:55296
	ds_read_b128 v[208:211], v139 offset:56320
	global_load_lds_dwordx4 v202, s[100:101]
	s_add_i32 m0, s0, 0x2000
	s_add_u32 s100, s18, 0x80
	s_addc_u32 s101, s19, 0
	s_add_u32 s0, s18, 0x160080
	s_addc_u32 s1, s19, 0
	s_add_i32 s2, s3, s24
	global_load_lds_dwordx4 v130, s[100:101]
	s_mov_b32 m0, s2
	s_nop 0
	global_load_lds_dwordx4 v202, s[0:1]
	s_add_i32 m0, s2, 0x2000
	s_nop 0
	global_load_lds_dwordx4 v130, s[0:1]
	s_add_u32 s100, s20, 0x80
	s_addc_u32 s101, s21, 0
	s_mov_b32 m0, s29
	s_nop 0
	global_load_lds_dwordx4 v202, s[100:101]
	s_add_u32 s100, s20, 0x80
	s_addc_u32 s101, s21, 0
	s_mov_b32 m0, s30
	s_nop 0
	global_load_lds_dwordx4 v130, s[100:101]
	s_waitcnt vmcnt(8)
	s_waitcnt lgkmcnt(0)
	s_setprio 1
	s_barrier
	v_mfma_f32_16x16x32_bf16 v[62:65], v[140:143], v[172:175], v[62:65]
	v_mfma_f32_16x16x32_bf16 v[58:61], v[148:151], v[172:175], v[58:61]
	v_mfma_f32_16x16x32_bf16 v[54:57], v[140:143], v[180:183], v[54:57]
	v_mfma_f32_16x16x32_bf16 v[50:53], v[148:151], v[180:183], v[50:53]
	v_mfma_f32_16x16x32_bf16 v[38:41], v[140:143], v[188:191], v[38:41]
	v_mfma_f32_16x16x32_bf16 v[34:37], v[148:151], v[188:191], v[34:37]
	v_mfma_f32_16x16x32_bf16 v[22:25], v[140:143], v[196:199], v[22:25]
	v_mfma_f32_16x16x32_bf16 v[18:21], v[148:151], v[196:199], v[18:21]
	v_mfma_f32_16x16x32_bf16 v[62:65], v[144:147], v[176:179], v[62:65]
	v_mfma_f32_16x16x32_bf16 v[58:61], v[152:155], v[176:179], v[58:61]
	v_mfma_f32_16x16x32_bf16 v[54:57], v[144:147], v[184:187], v[54:57]
	v_mfma_f32_16x16x32_bf16 v[50:53], v[152:155], v[184:187], v[50:53]
	v_mfma_f32_16x16x32_bf16 v[38:41], v[144:147], v[192:195], v[38:41]
	v_mfma_f32_16x16x32_bf16 v[34:37], v[152:155], v[192:195], v[34:37]
	v_mfma_f32_16x16x32_bf16 v[22:25], v[144:147], v[208:211], v[22:25]
	v_mfma_f32_16x16x32_bf16 v[18:21], v[152:155], v[208:211], v[18:21]
	s_setprio 0
	s_setprio 1
	v_mfma_f32_16x16x32_bf16 v[46:49], v[156:159], v[172:175], v[46:49]
	v_mfma_f32_16x16x32_bf16 v[42:45], v[164:167], v[172:175], v[42:45]
	v_mfma_f32_16x16x32_bf16 v[30:33], v[156:159], v[180:183], v[30:33]
	v_mfma_f32_16x16x32_bf16 v[26:29], v[164:167], v[180:183], v[26:29]
	v_mfma_f32_16x16x32_bf16 v[14:17], v[156:159], v[188:191], v[14:17]
	v_mfma_f32_16x16x32_bf16 v[10:13], v[164:167], v[188:191], v[10:13]
	v_mfma_f32_16x16x32_bf16 v[6:9], v[156:159], v[196:199], v[6:9]
	v_mfma_f32_16x16x32_bf16 v[2:5], v[164:167], v[196:199], v[2:5]
	v_mfma_f32_16x16x32_bf16 v[46:49], v[160:163], v[176:179], v[46:49]
	v_mfma_f32_16x16x32_bf16 v[42:45], v[168:171], v[176:179], v[42:45]
	v_mfma_f32_16x16x32_bf16 v[30:33], v[160:163], v[184:187], v[30:33]
	v_mfma_f32_16x16x32_bf16 v[26:29], v[168:171], v[184:187], v[26:29]
	v_mfma_f32_16x16x32_bf16 v[14:17], v[160:163], v[192:195], v[14:17]
	v_mfma_f32_16x16x32_bf16 v[10:13], v[168:171], v[192:195], v[10:13]
	v_mfma_f32_16x16x32_bf16 v[6:9], v[160:163], v[208:211], v[6:9]
	v_mfma_f32_16x16x32_bf16 v[2:5], v[168:171], v[208:211], v[2:5]
	s_barrier
	s_setprio 0
	s_add_i32 s59, s59, 2
	s_add_u32 s49, s49, 0x100
	s_addc_u32 s58, s58, 0
	s_cmp_gt_u32 s59, 5
	s_mov_b64 s[2:3], s[4:5]
	s_cbranch_scc0 .LBB0_990
	s_and_b64 vcc, exec, s[10:11]
	s_cbranch_vccz .LBB0_993
	s_barrier

.LBB0_1115:
	s_add_u32 s0, s22, 0xfff80080
	s_addc_u32 s1, s23, -1
	s_add_i32 s33, 0, 0x10000
	s_cmp_eq_u32 s58, 28
	s_cselect_b32 s5, s17, s1
	s_cselect_b32 s4, s39, s0
	v_add_u32_e32 v143, s33, v145
	s_cselect_b32 s3, s15, s49
	s_cselect_b32 s2, s40, s41
	s_add_i32 s55, 0, 0x14000
	ds_read_b128 v[148:151], v143
	ds_read_b128 v[152:155], v143 offset:1024
	ds_read_b128 v[156:159], v143 offset:2048
	ds_read_b128 v[160:163], v143 offset:3072
	v_add_u32_e32 v143, s55, v145
	ds_read_b128 v[164:167], v143
	ds_read_b128 v[168:171], v143 offset:1024
	ds_read_b128 v[172:175], v143 offset:2048
	ds_read_b128 v[176:179], v143 offset:3072
	s_add_i32 m0, s27, 0xc000
	ds_read_b128 v[180:183], v147
	ds_read_b128 v[184:187], v147 offset:1024
	ds_read_b128 v[188:191], v147 offset:2048
	ds_read_b128 v[192:195], v147 offset:3072
	ds_read_b128 v[196:199], v147 offset:4096
	ds_read_b128 v[208:211], v147 offset:5120
	ds_read_b128 v[212:215], v147 offset:6144
	ds_read_b128 v[216:219], v147 offset:7168
	global_load_lds_dwordx4 v138, s[22:23]
	s_add_i32 m0, s27, 0xe000
	s_nop 0
	global_load_lds_dwordx4 v140, s[22:23]
	s_waitcnt vmcnt(8)
	s_waitcnt lgkmcnt(0)
	s_setprio 1
	s_barrier
	v_mfma_f32_16x16x32_bf16 v[126:129], v[148:151], v[180:183], v[126:129]
	v_mfma_f32_16x16x32_bf16 v[122:125], v[156:159], v[180:183], v[122:125]
	v_mfma_f32_16x16x32_bf16 v[110:113], v[148:151], v[188:191], v[110:113]
	v_mfma_f32_16x16x32_bf16 v[106:109], v[156:159], v[188:191], v[106:109]
	v_mfma_f32_16x16x32_bf16 v[94:97], v[148:151], v[196:199], v[94:97]
	v_mfma_f32_16x16x32_bf16 v[90:93], v[156:159], v[196:199], v[90:93]
	v_mfma_f32_16x16x32_bf16 v[78:81], v[148:151], v[212:215], v[78:81]
	v_mfma_f32_16x16x32_bf16 v[74:77], v[156:159], v[212:215], v[74:77]
	v_mfma_f32_16x16x32_bf16 v[126:129], v[152:155], v[184:187], v[126:129]
	v_mfma_f32_16x16x32_bf16 v[122:125], v[160:163], v[184:187], v[122:125]
	v_mfma_f32_16x16x32_bf16 v[110:113], v[152:155], v[192:195], v[110:113]
	v_mfma_f32_16x16x32_bf16 v[106:109], v[160:163], v[192:195], v[106:109]
	v_mfma_f32_16x16x32_bf16 v[94:97], v[152:155], v[208:211], v[94:97]
	v_mfma_f32_16x16x32_bf16 v[90:93], v[160:163], v[208:211], v[90:93]
	v_mfma_f32_16x16x32_bf16 v[78:81], v[152:155], v[216:219], v[78:81]
	v_mfma_f32_16x16x32_bf16 v[74:77], v[160:163], v[216:219], v[74:77]
	s_setprio 0
	s_setprio 1
	v_mfma_f32_16x16x32_bf16 v[118:121], v[164:167], v[180:183], v[118:121]
	v_mfma_f32_16x16x32_bf16 v[114:117], v[172:175], v[180:183], v[114:117]
	v_mfma_f32_16x16x32_bf16 v[102:105], v[164:167], v[188:191], v[102:105]
	v_mfma_f32_16x16x32_bf16 v[98:101], v[172:175], v[188:191], v[98:101]
	v_mfma_f32_16x16x32_bf16 v[86:89], v[164:167], v[196:199], v[86:89]
	v_mfma_f32_16x16x32_bf16 v[82:85], v[172:175], v[196:199], v[82:85]
	v_mfma_f32_16x16x32_bf16 v[70:73], v[164:167], v[212:215], v[70:73]
	v_mfma_f32_16x16x32_bf16 v[66:69], v[172:175], v[212:215], v[66:69]
	v_mfma_f32_16x16x32_bf16 v[118:121], v[168:171], v[184:187], v[118:121]
	v_mfma_f32_16x16x32_bf16 v[114:117], v[176:179], v[184:187], v[114:117]
	v_mfma_f32_16x16x32_bf16 v[102:105], v[168:171], v[192:195], v[102:105]
	v_mfma_f32_16x16x32_bf16 v[98:101], v[176:179], v[192:195], v[98:101]
	v_mfma_f32_16x16x32_bf16 v[86:89], v[168:171], v[208:211], v[86:89]
	v_mfma_f32_16x16x32_bf16 v[82:85], v[176:179], v[208:211], v[82:85]
	v_mfma_f32_16x16x32_bf16 v[70:73], v[168:171], v[216:219], v[70:73]
	v_mfma_f32_16x16x32_bf16 v[66:69], v[176:179], v[216:219], v[66:69]
	s_barrier
	s_setprio 0
	s_add_i32 s0, s33, s26
	s_mov_b32 m0, s0
	ds_read_b128 v[180:183], v147 offset:16384
	ds_read_b128 v[184:187], v147 offset:17408
	ds_read_b128 v[188:191], v147 offset:18432
	ds_read_b128 v[192:195], v147 offset:19456
	ds_read_b128 v[196:199], v147 offset:20480
	ds_read_b128 v[208:211], v147 offset:21504
	ds_read_b128 v[212:215], v147 offset:22528
	ds_read_b128 v[216:219], v147 offset:23552
	global_load_lds_dwordx4 v134, s[2:3]
	s_add_i32 m0, s0, 0x2000
	s_add_u32 s0, s2, 0x80000
	s_addc_u32 s1, s3, 0
	s_add_i32 s33, s55, s26
	global_load_lds_dwordx4 v130, s[2:3]
	s_mov_b32 m0, s33
	s_nop 0
	global_load_lds_dwordx4 v134, s[0:1]
	s_add_i32 m0, s33, 0x2000
	s_nop 0
	global_load_lds_dwordx4 v130, s[0:1]
	s_mov_b32 m0, s27
	s_nop 0
	global_load_lds_dwordx4 v136, s[4:5]
	s_mov_b32 m0, s28
	s_nop 0
	global_load_lds_dwordx4 v132, s[4:5]
	s_waitcnt vmcnt(8)
	s_waitcnt lgkmcnt(0)
	s_setprio 1
	s_barrier
	v_mfma_f32_16x16x32_bf16 v[62:65], v[148:151], v[180:183], v[62:65]
	v_mfma_f32_16x16x32_bf16 v[58:61], v[156:159], v[180:183], v[58:61]
	v_mfma_f32_16x16x32_bf16 v[46:49], v[148:151], v[188:191], v[46:49]
	v_mfma_f32_16x16x32_bf16 v[42:45], v[156:159], v[188:191], v[42:45]
	v_mfma_f32_16x16x32_bf16 v[30:33], v[148:151], v[196:199], v[30:33]
	v_mfma_f32_16x16x32_bf16 v[26:29], v[156:159], v[196:199], v[26:29]
	v_mfma_f32_16x16x32_bf16 v[14:17], v[148:151], v[212:215], v[14:17]
	v_mfma_f32_16x16x32_bf16 v[10:13], v[156:159], v[212:215], v[10:13]
	v_mfma_f32_16x16x32_bf16 v[62:65], v[152:155], v[184:187], v[62:65]
	v_mfma_f32_16x16x32_bf16 v[58:61], v[160:163], v[184:187], v[58:61]
	v_mfma_f32_16x16x32_bf16 v[46:49], v[152:155], v[192:195], v[46:49]
	v_mfma_f32_16x16x32_bf16 v[42:45], v[160:163], v[192:195], v[42:45]
	v_mfma_f32_16x16x32_bf16 v[30:33], v[152:155], v[208:211], v[30:33]
	v_mfma_f32_16x16x32_bf16 v[26:29], v[160:163], v[208:211], v[26:29]
	v_mfma_f32_16x16x32_bf16 v[14:17], v[152:155], v[216:219], v[14:17]
	v_mfma_f32_16x16x32_bf16 v[10:13], v[160:163], v[216:219], v[10:13]
	s_setprio 0
	s_setprio 1
	v_mfma_f32_16x16x32_bf16 v[54:57], v[164:167], v[180:183], v[54:57]
	v_mfma_f32_16x16x32_bf16 v[50:53], v[172:175], v[180:183], v[50:53]
	v_mfma_f32_16x16x32_bf16 v[38:41], v[164:167], v[188:191], v[38:41]
	v_mfma_f32_16x16x32_bf16 v[34:37], v[172:175], v[188:191], v[34:37]
	v_mfma_f32_16x16x32_bf16 v[22:25], v[164:167], v[196:199], v[22:25]
	v_mfma_f32_16x16x32_bf16 v[18:21], v[172:175], v[196:199], v[18:21]
	v_mfma_f32_16x16x32_bf16 v[6:9], v[164:167], v[212:215], v[6:9]
	v_mfma_f32_16x16x32_bf16 v[2:5], v[172:175], v[212:215], v[2:5]
	v_mfma_f32_16x16x32_bf16 v[54:57], v[168:171], v[184:187], v[54:57]
	v_mfma_f32_16x16x32_bf16 v[50:53], v[176:179], v[184:187], v[50:53]
	v_mfma_f32_16x16x32_bf16 v[38:41], v[168:171], v[192:195], v[38:41]
	v_mfma_f32_16x16x32_bf16 v[34:37], v[176:179], v[192:195], v[34:37]
	v_mfma_f32_16x16x32_bf16 v[22:25], v[168:171], v[208:211], v[22:25]
	v_mfma_f32_16x16x32_bf16 v[18:21], v[176:179], v[208:211], v[18:21]
	v_mfma_f32_16x16x32_bf16 v[6:9], v[168:171], v[216:219], v[6:9]
	v_mfma_f32_16x16x32_bf16 v[2:5], v[176:179], v[216:219], v[2:5]
	s_barrier
	s_setprio 0
	s_add_i32 s33, 0, 0x18000
	v_add_u32_e32 v143, s33, v145
	s_add_i32 s55, 0, 0x1c000
	ds_read_b128 v[148:151], v143
	ds_read_b128 v[152:155], v143 offset:1024
	ds_read_b128 v[156:159], v143 offset:2048
	ds_read_b128 v[160:163], v143 offset:3072
	v_add_u32_e32 v143, s55, v145
	ds_read_b128 v[164:167], v143
	ds_read_b128 v[168:171], v143 offset:1024
	ds_read_b128 v[172:175], v143 offset:2048
	ds_read_b128 v[176:179], v143 offset:3072
	s_add_u32 s0, s4, 0x80000
	s_addc_u32 s1, s5, 0
	s_mov_b32 m0, s29
	ds_read_b128 v[180:183], v147 offset:32768
	ds_read_b128 v[184:187], v147 offset:33792
	ds_read_b128 v[188:191], v147 offset:34816
	ds_read_b128 v[192:195], v147 offset:35840
	ds_read_b128 v[196:199], v147 offset:36864
	ds_read_b128 v[208:211], v147 offset:37888
	ds_read_b128 v[212:215], v147 offset:38912
	ds_read_b128 v[216:219], v147 offset:39936
	global_load_lds_dwordx4 v136, s[0:1]
	s_mov_b32 m0, s30
	s_nop 0
	global_load_lds_dwordx4 v132, s[0:1]
	s_waitcnt vmcnt(8)
	s_waitcnt lgkmcnt(0)
	s_setprio 1
	s_barrier
	v_mfma_f32_16x16x32_bf16 v[126:129], v[148:151], v[180:183], v[126:129]
	v_mfma_f32_16x16x32_bf16 v[122:125], v[156:159], v[180:183], v[122:125]
	v_mfma_f32_16x16x32_bf16 v[110:113], v[148:151], v[188:191], v[110:113]
	v_mfma_f32_16x16x32_bf16 v[106:109], v[156:159], v[188:191], v[106:109]
	v_mfma_f32_16x16x32_bf16 v[94:97], v[148:151], v[196:199], v[94:97]
	v_mfma_f32_16x16x32_bf16 v[90:93], v[156:159], v[196:199], v[90:93]
	v_mfma_f32_16x16x32_bf16 v[78:81], v[148:151], v[212:215], v[78:81]
	v_mfma_f32_16x16x32_bf16 v[74:77], v[156:159], v[212:215], v[74:77]
	v_mfma_f32_16x16x32_bf16 v[126:129], v[152:155], v[184:187], v[126:129]
	v_mfma_f32_16x16x32_bf16 v[122:125], v[160:163], v[184:187], v[122:125]
	v_mfma_f32_16x16x32_bf16 v[110:113], v[152:155], v[192:195], v[110:113]
	v_mfma_f32_16x16x32_bf16 v[106:109], v[160:163], v[192:195], v[106:109]
	v_mfma_f32_16x16x32_bf16 v[94:97], v[152:155], v[208:211], v[94:97]
	v_mfma_f32_16x16x32_bf16 v[90:93], v[160:163], v[208:211], v[90:93]
	v_mfma_f32_16x16x32_bf16 v[78:81], v[152:155], v[216:219], v[78:81]
	v_mfma_f32_16x16x32_bf16 v[74:77], v[160:163], v[216:219], v[74:77]
	s_setprio 0
	s_setprio 1
	v_mfma_f32_16x16x32_bf16 v[118:121], v[164:167], v[180:183], v[118:121]
	v_mfma_f32_16x16x32_bf16 v[114:117], v[172:175], v[180:183], v[114:117]
	v_mfma_f32_16x16x32_bf16 v[102:105], v[164:167], v[188:191], v[102:105]
	v_mfma_f32_16x16x32_bf16 v[98:101], v[172:175], v[188:191], v[98:101]
	v_mfma_f32_16x16x32_bf16 v[86:89], v[164:167], v[196:199], v[86:89]
	v_mfma_f32_16x16x32_bf16 v[82:85], v[172:175], v[196:199], v[82:85]
	v_mfma_f32_16x16x32_bf16 v[70:73], v[164:167], v[212:215], v[70:73]
	v_mfma_f32_16x16x32_bf16 v[66:69], v[172:175], v[212:215], v[66:69]
	v_mfma_f32_16x16x32_bf16 v[118:121], v[168:171], v[184:187], v[118:121]
	v_mfma_f32_16x16x32_bf16 v[114:117], v[176:179], v[184:187], v[114:117]
	v_mfma_f32_16x16x32_bf16 v[102:105], v[168:171], v[192:195], v[102:105]
	v_mfma_f32_16x16x32_bf16 v[98:101], v[176:179], v[192:195], v[98:101]
	v_mfma_f32_16x16x32_bf16 v[86:89], v[168:171], v[208:211], v[86:89]
	v_mfma_f32_16x16x32_bf16 v[82:85], v[176:179], v[208:211], v[82:85]
	v_mfma_f32_16x16x32_bf16 v[70:73], v[168:171], v[216:219], v[70:73]
	v_mfma_f32_16x16x32_bf16 v[66:69], v[176:179], v[216:219], v[66:69]
	s_barrier
	s_setprio 0
	s_add_i32 s0, s33, s26
	s_add_u32 s100, s2, 0x80
	s_addc_u32 s101, s3, 0
	s_mov_b32 m0, s0
	ds_read_b128 v[180:183], v147 offset:49152
	ds_read_b128 v[184:187], v147 offset:50176
	ds_read_b128 v[188:191], v147 offset:51200
	ds_read_b128 v[192:195], v147 offset:52224
	ds_read_b128 v[196:199], v147 offset:53248
	ds_read_b128 v[208:211], v147 offset:54272
	ds_read_b128 v[212:215], v147 offset:55296
	ds_read_b128 v[216:219], v147 offset:56320
	global_load_lds_dwordx4 v134, s[100:101]
	s_add_i32 m0, s0, 0x2000
	s_add_u32 s100, s2, 0x80
	s_addc_u32 s101, s3, 0
	s_add_u32 s0, s2, 0x80080
	s_addc_u32 s1, s3, 0
	s_add_i32 s2, s55, s26
	global_load_lds_dwordx4 v130, s[100:101]
	s_mov_b32 m0, s2
	s_nop 0
	global_load_lds_dwordx4 v134, s[0:1]
	s_add_i32 m0, s2, 0x2000
	s_nop 0
	global_load_lds_dwordx4 v130, s[0:1]
	s_add_u32 s100, s4, 0x80
	s_addc_u32 s101, s5, 0
	s_mov_b32 m0, s34
	s_nop 0
	global_load_lds_dwordx4 v136, s[100:101]
	s_add_u32 s100, s4, 0x80
	s_addc_u32 s101, s5, 0
	s_mov_b32 m0, s35
	s_nop 0
	global_load_lds_dwordx4 v132, s[100:101]
	s_waitcnt vmcnt(8)
	s_waitcnt lgkmcnt(0)
	s_setprio 1
	s_barrier
	v_mfma_f32_16x16x32_bf16 v[62:65], v[148:151], v[180:183], v[62:65]
	v_mfma_f32_16x16x32_bf16 v[58:61], v[156:159], v[180:183], v[58:61]
	v_mfma_f32_16x16x32_bf16 v[46:49], v[148:151], v[188:191], v[46:49]
	v_mfma_f32_16x16x32_bf16 v[42:45], v[156:159], v[188:191], v[42:45]
	v_mfma_f32_16x16x32_bf16 v[30:33], v[148:151], v[196:199], v[30:33]
	v_mfma_f32_16x16x32_bf16 v[26:29], v[156:159], v[196:199], v[26:29]
	v_mfma_f32_16x16x32_bf16 v[14:17], v[148:151], v[212:215], v[14:17]
	v_mfma_f32_16x16x32_bf16 v[10:13], v[156:159], v[212:215], v[10:13]
	v_mfma_f32_16x16x32_bf16 v[62:65], v[152:155], v[184:187], v[62:65]
	v_mfma_f32_16x16x32_bf16 v[58:61], v[160:163], v[184:187], v[58:61]
	v_mfma_f32_16x16x32_bf16 v[46:49], v[152:155], v[192:195], v[46:49]
	v_mfma_f32_16x16x32_bf16 v[42:45], v[160:163], v[192:195], v[42:45]
	v_mfma_f32_16x16x32_bf16 v[30:33], v[152:155], v[208:211], v[30:33]
	v_mfma_f32_16x16x32_bf16 v[26:29], v[160:163], v[208:211], v[26:29]
	v_mfma_f32_16x16x32_bf16 v[14:17], v[152:155], v[216:219], v[14:17]
	v_mfma_f32_16x16x32_bf16 v[10:13], v[160:163], v[216:219], v[10:13]
	s_setprio 0
	s_setprio 1
	v_mfma_f32_16x16x32_bf16 v[54:57], v[164:167], v[180:183], v[54:57]
	v_mfma_f32_16x16x32_bf16 v[50:53], v[172:175], v[180:183], v[50:53]
	v_mfma_f32_16x16x32_bf16 v[38:41], v[164:167], v[188:191], v[38:41]
	v_mfma_f32_16x16x32_bf16 v[34:37], v[172:175], v[188:191], v[34:37]
	v_mfma_f32_16x16x32_bf16 v[22:25], v[164:167], v[196:199], v[22:25]
	v_mfma_f32_16x16x32_bf16 v[18:21], v[172:175], v[196:199], v[18:21]
	v_mfma_f32_16x16x32_bf16 v[6:9], v[164:167], v[212:215], v[6:9]
	v_mfma_f32_16x16x32_bf16 v[2:5], v[172:175], v[212:215], v[2:5]
	v_mfma_f32_16x16x32_bf16 v[54:57], v[168:171], v[184:187], v[54:57]
	v_mfma_f32_16x16x32_bf16 v[50:53], v[176:179], v[184:187], v[50:53]
	v_mfma_f32_16x16x32_bf16 v[38:41], v[168:171], v[192:195], v[38:41]
	v_mfma_f32_16x16x32_bf16 v[34:37], v[176:179], v[192:195], v[34:37]
	v_mfma_f32_16x16x32_bf16 v[22:25], v[168:171], v[208:211], v[22:25]
	v_mfma_f32_16x16x32_bf16 v[18:21], v[176:179], v[208:211], v[18:21]
	v_mfma_f32_16x16x32_bf16 v[6:9], v[168:171], v[216:219], v[6:9]
	v_mfma_f32_16x16x32_bf16 v[2:5], v[176:179], v[216:219], v[2:5]
	s_barrier
	s_setprio 0
	s_add_i32 s58, s58, 2
	s_add_u32 s22, s22, 0x100
	s_addc_u32 s23, s23, 0
	s_add_u32 s41, s41, 0x100
	s_addc_u32 s49, s49, 0
	s_cmp_gt_u32 s58, 29
	s_cbranch_scc0 .LBB0_1115
	s_and_b64 vcc, exec, s[10:11]
	s_cbranch_vccz .LBB0_1118
	s_barrier

.LBB0_1242:
	s_add_u32 s28, s18, s4
	s_addc_u32 s29, s19, s5
	s_add_u32 s24, s28, 0x100
	s_addc_u32 s25, s29, 0
	s_and_b64 s[0:1], s[2:3], exec
	s_cselect_b32 s25, s49, s25
	s_cselect_b32 s24, s58, s24
	s_add_u32 s0, s20, s4
	s_addc_u32 s1, s21, s5
	s_add_u32 s4, s0, 0x100
	s_addc_u32 s5, s1, 0
	s_add_i32 s55, 0, 0x10000
	s_and_b64 s[0:1], s[2:3], exec
	s_cselect_b32 s27, s59, s5
	s_cselect_b32 s26, s60, s4
	s_add_i32 s0, 0, 0x14000
	s_add_u32 s30, s28, 0x20080
	s_addc_u32 s31, s29, 0
	s_add_i32 s57, s55, s36
	s_add_i32 m0, s37, 0xc000
	s_add_i32 s1, s37, 0xe000
	s_add_i32 s63, s57, 0x2000
	v_add_u32_e32 v138, s55, v141
	s_add_u32 s28, s26, 0x10000
	ds_read_b128 v[144:147], v138
	ds_read_b128 v[148:151], v138 offset:1024
	ds_read_b128 v[152:155], v138 offset:2048
	ds_read_b128 v[156:159], v138 offset:3072
	v_add_u32_e32 v138, s0, v141
	s_addc_u32 s29, s27, 0
	s_add_i32 s33, s0, s36
	ds_read_b128 v[160:163], v138
	ds_read_b128 v[164:167], v138 offset:1024
	ds_read_b128 v[168:171], v138 offset:2048
	ds_read_b128 v[172:175], v138 offset:3072
	s_add_i32 s56, s33, 0x2000
	s_add_i32 vcc_lo, 0, 0x18000
	s_add_i32 vcc_hi, 0, 0x1c000
	s_add_u32 s4, s24, 0x20000
	s_addc_u32 s5, s25, 0
	s_add_i32 s61, vcc_lo, s36
	s_add_i32 s62, s61, 0x2000
	s_add_u32 s2, s26, 0x10080
	s_addc_u32 s3, s27, 0
	s_add_i32 s55, vcc_hi, s36
	s_add_i32 s0, s55, 0x2000
	ds_read_b128 v[176:179], v142
	ds_read_b128 v[180:183], v142 offset:1024
	ds_read_b128 v[184:187], v142 offset:2048
	ds_read_b128 v[188:191], v142 offset:3072
	ds_read_b128 v[192:195], v142 offset:4096
	ds_read_b128 v[196:199], v142 offset:5120
	ds_read_b128 v[208:211], v142 offset:6144
	ds_read_b128 v[212:215], v142 offset:7168
	global_load_lds_dwordx4 v134, s[30:31]
	s_mov_b32 m0, s1
	s_nop 0
	global_load_lds_dwordx4 v132, s[30:31]
	s_waitcnt vmcnt(8)
	s_waitcnt lgkmcnt(0)
	s_setprio 1
	s_barrier
	v_mfma_f32_16x16x32_bf16 v[126:129], v[144:147], v[176:179], v[126:129]
	v_mfma_f32_16x16x32_bf16 v[122:125], v[152:155], v[176:179], v[122:125]
	v_mfma_f32_16x16x32_bf16 v[118:121], v[144:147], v[184:187], v[118:121]
	v_mfma_f32_16x16x32_bf16 v[110:113], v[152:155], v[184:187], v[110:113]
	v_mfma_f32_16x16x32_bf16 v[102:105], v[144:147], v[192:195], v[102:105]
	v_mfma_f32_16x16x32_bf16 v[94:97], v[152:155], v[192:195], v[94:97]
	v_mfma_f32_16x16x32_bf16 v[86:89], v[144:147], v[208:211], v[86:89]
	v_mfma_f32_16x16x32_bf16 v[78:81], v[152:155], v[208:211], v[78:81]
	v_mfma_f32_16x16x32_bf16 v[126:129], v[148:151], v[180:183], v[126:129]
	v_mfma_f32_16x16x32_bf16 v[122:125], v[156:159], v[180:183], v[122:125]
	v_mfma_f32_16x16x32_bf16 v[118:121], v[148:151], v[188:191], v[118:121]
	v_mfma_f32_16x16x32_bf16 v[110:113], v[156:159], v[188:191], v[110:113]
	v_mfma_f32_16x16x32_bf16 v[102:105], v[148:151], v[196:199], v[102:105]
	v_mfma_f32_16x16x32_bf16 v[94:97], v[156:159], v[196:199], v[94:97]
	v_mfma_f32_16x16x32_bf16 v[86:89], v[148:151], v[212:215], v[86:89]
	v_mfma_f32_16x16x32_bf16 v[78:81], v[156:159], v[212:215], v[78:81]
	s_setprio 0
	s_setprio 1
	v_mfma_f32_16x16x32_bf16 v[114:117], v[160:163], v[176:179], v[114:117]
	v_mfma_f32_16x16x32_bf16 v[106:109], v[168:171], v[176:179], v[106:109]
	v_mfma_f32_16x16x32_bf16 v[98:101], v[160:163], v[184:187], v[98:101]
	v_mfma_f32_16x16x32_bf16 v[90:93], v[168:171], v[184:187], v[90:93]
	v_mfma_f32_16x16x32_bf16 v[82:85], v[160:163], v[192:195], v[82:85]
	v_mfma_f32_16x16x32_bf16 v[74:77], v[168:171], v[192:195], v[74:77]
	v_mfma_f32_16x16x32_bf16 v[70:73], v[160:163], v[208:211], v[70:73]
	v_mfma_f32_16x16x32_bf16 v[66:69], v[168:171], v[208:211], v[66:69]
	v_mfma_f32_16x16x32_bf16 v[114:117], v[164:167], v[180:183], v[114:117]
	v_mfma_f32_16x16x32_bf16 v[106:109], v[172:175], v[180:183], v[106:109]
	v_mfma_f32_16x16x32_bf16 v[98:101], v[164:167], v[188:191], v[98:101]
	v_mfma_f32_16x16x32_bf16 v[90:93], v[172:175], v[188:191], v[90:93]
	v_mfma_f32_16x16x32_bf16 v[82:85], v[164:167], v[196:199], v[82:85]
	v_mfma_f32_16x16x32_bf16 v[74:77], v[172:175], v[196:199], v[74:77]
	v_mfma_f32_16x16x32_bf16 v[70:73], v[164:167], v[212:215], v[70:73]
	v_mfma_f32_16x16x32_bf16 v[66:69], v[172:175], v[212:215], v[66:69]
	s_barrier
	s_setprio 0
	s_mov_b32 m0, s57
	ds_read_b128 v[176:179], v142 offset:16384
	ds_read_b128 v[180:183], v142 offset:17408
	ds_read_b128 v[184:187], v142 offset:18432
	ds_read_b128 v[188:191], v142 offset:19456
	ds_read_b128 v[192:195], v142 offset:20480
	ds_read_b128 v[196:199], v142 offset:21504
	ds_read_b128 v[208:211], v142 offset:22528
	ds_read_b128 v[212:215], v142 offset:23552
	global_load_lds_dwordx4 v202, s[26:27]
	s_mov_b32 m0, s63
	s_nop 0
	global_load_lds_dwordx4 v130, s[26:27]
	s_mov_b32 m0, s33
	s_nop 0
	global_load_lds_dwordx4 v202, s[28:29]
	s_mov_b32 m0, s56
	s_nop 0
	global_load_lds_dwordx4 v130, s[28:29]
	s_mov_b32 m0, s37
	s_nop 0
	global_load_lds_dwordx4 v134, s[24:25]
	s_mov_b32 m0, s38
	s_nop 0
	global_load_lds_dwordx4 v132, s[24:25]
	s_waitcnt vmcnt(8)
	s_waitcnt lgkmcnt(0)
	s_setprio 1
	s_barrier
	v_mfma_f32_16x16x32_bf16 v[62:65], v[144:147], v[176:179], v[62:65]
	v_mfma_f32_16x16x32_bf16 v[58:61], v[152:155], v[176:179], v[58:61]
	v_mfma_f32_16x16x32_bf16 v[54:57], v[144:147], v[184:187], v[54:57]
	v_mfma_f32_16x16x32_bf16 v[46:49], v[152:155], v[184:187], v[46:49]
	v_mfma_f32_16x16x32_bf16 v[38:41], v[144:147], v[192:195], v[38:41]
	v_mfma_f32_16x16x32_bf16 v[30:33], v[152:155], v[192:195], v[30:33]
	v_mfma_f32_16x16x32_bf16 v[22:25], v[144:147], v[208:211], v[22:25]
	v_mfma_f32_16x16x32_bf16 v[14:17], v[152:155], v[208:211], v[14:17]
	v_mfma_f32_16x16x32_bf16 v[62:65], v[148:151], v[180:183], v[62:65]
	v_mfma_f32_16x16x32_bf16 v[58:61], v[156:159], v[180:183], v[58:61]
	v_mfma_f32_16x16x32_bf16 v[54:57], v[148:151], v[188:191], v[54:57]
	v_mfma_f32_16x16x32_bf16 v[46:49], v[156:159], v[188:191], v[46:49]
	v_mfma_f32_16x16x32_bf16 v[38:41], v[148:151], v[196:199], v[38:41]
	v_mfma_f32_16x16x32_bf16 v[30:33], v[156:159], v[196:199], v[30:33]
	v_mfma_f32_16x16x32_bf16 v[22:25], v[148:151], v[212:215], v[22:25]
	v_mfma_f32_16x16x32_bf16 v[14:17], v[156:159], v[212:215], v[14:17]
	s_setprio 0
	s_setprio 1
	v_mfma_f32_16x16x32_bf16 v[50:53], v[160:163], v[176:179], v[50:53]
	v_mfma_f32_16x16x32_bf16 v[42:45], v[168:171], v[176:179], v[42:45]
	v_mfma_f32_16x16x32_bf16 v[34:37], v[160:163], v[184:187], v[34:37]
	v_mfma_f32_16x16x32_bf16 v[26:29], v[168:171], v[184:187], v[26:29]
	v_mfma_f32_16x16x32_bf16 v[18:21], v[160:163], v[192:195], v[18:21]
	v_mfma_f32_16x16x32_bf16 v[10:13], v[168:171], v[192:195], v[10:13]
	v_mfma_f32_16x16x32_bf16 v[6:9], v[160:163], v[208:211], v[6:9]
	v_mfma_f32_16x16x32_bf16 v[2:5], v[168:171], v[208:211], v[2:5]
	v_mfma_f32_16x16x32_bf16 v[50:53], v[164:167], v[180:183], v[50:53]
	v_mfma_f32_16x16x32_bf16 v[42:45], v[172:175], v[180:183], v[42:45]
	v_mfma_f32_16x16x32_bf16 v[34:37], v[164:167], v[188:191], v[34:37]
	v_mfma_f32_16x16x32_bf16 v[26:29], v[172:175], v[188:191], v[26:29]
	v_mfma_f32_16x16x32_bf16 v[18:21], v[164:167], v[196:199], v[18:21]
	v_mfma_f32_16x16x32_bf16 v[10:13], v[172:175], v[196:199], v[10:13]
	v_mfma_f32_16x16x32_bf16 v[6:9], v[164:167], v[212:215], v[6:9]
	v_mfma_f32_16x16x32_bf16 v[2:5], v[172:175], v[212:215], v[2:5]
	s_barrier
	s_setprio 0
	v_add_u32_e32 v143, vcc_lo, v141
	ds_read_b128 v[144:147], v143
	ds_read_b128 v[148:151], v143 offset:1024
	ds_read_b128 v[152:155], v143 offset:2048
	ds_read_b128 v[156:159], v143 offset:3072
	v_add_u32_e32 v143, vcc_hi, v141
	ds_read_b128 v[160:163], v143
	ds_read_b128 v[164:167], v143 offset:1024
	ds_read_b128 v[168:171], v143 offset:2048
	ds_read_b128 v[172:175], v143 offset:3072
	s_mov_b32 m0, s39
	ds_read_b128 v[176:179], v142 offset:32768
	ds_read_b128 v[180:183], v142 offset:33792
	ds_read_b128 v[184:187], v142 offset:34816
	ds_read_b128 v[188:191], v142 offset:35840
	ds_read_b128 v[192:195], v142 offset:36864
	ds_read_b128 v[196:199], v142 offset:37888
	ds_read_b128 v[208:211], v142 offset:38912
	ds_read_b128 v[212:215], v142 offset:39936
	global_load_lds_dwordx4 v134, s[4:5]
	s_mov_b32 m0, s40
	s_nop 0
	global_load_lds_dwordx4 v132, s[4:5]
	s_waitcnt vmcnt(8)
	s_waitcnt lgkmcnt(0)
	s_setprio 1
	s_barrier
	v_mfma_f32_16x16x32_bf16 v[126:129], v[144:147], v[176:179], v[126:129]
	v_mfma_f32_16x16x32_bf16 v[122:125], v[152:155], v[176:179], v[122:125]
	v_mfma_f32_16x16x32_bf16 v[118:121], v[144:147], v[184:187], v[118:121]
	v_mfma_f32_16x16x32_bf16 v[110:113], v[152:155], v[184:187], v[110:113]
	v_mfma_f32_16x16x32_bf16 v[102:105], v[144:147], v[192:195], v[102:105]
	v_mfma_f32_16x16x32_bf16 v[94:97], v[152:155], v[192:195], v[94:97]
	v_mfma_f32_16x16x32_bf16 v[86:89], v[144:147], v[208:211], v[86:89]
	v_mfma_f32_16x16x32_bf16 v[78:81], v[152:155], v[208:211], v[78:81]
	v_mfma_f32_16x16x32_bf16 v[126:129], v[148:151], v[180:183], v[126:129]
	v_mfma_f32_16x16x32_bf16 v[122:125], v[156:159], v[180:183], v[122:125]
	v_mfma_f32_16x16x32_bf16 v[118:121], v[148:151], v[188:191], v[118:121]
	v_mfma_f32_16x16x32_bf16 v[110:113], v[156:159], v[188:191], v[110:113]
	v_mfma_f32_16x16x32_bf16 v[102:105], v[148:151], v[196:199], v[102:105]
	v_mfma_f32_16x16x32_bf16 v[94:97], v[156:159], v[196:199], v[94:97]
	v_mfma_f32_16x16x32_bf16 v[86:89], v[148:151], v[212:215], v[86:89]
	v_mfma_f32_16x16x32_bf16 v[78:81], v[156:159], v[212:215], v[78:81]
	s_setprio 0
	s_setprio 1
	v_mfma_f32_16x16x32_bf16 v[114:117], v[160:163], v[176:179], v[114:117]
	v_mfma_f32_16x16x32_bf16 v[106:109], v[168:171], v[176:179], v[106:109]
	v_mfma_f32_16x16x32_bf16 v[98:101], v[160:163], v[184:187], v[98:101]
	v_mfma_f32_16x16x32_bf16 v[90:93], v[168:171], v[184:187], v[90:93]
	v_mfma_f32_16x16x32_bf16 v[82:85], v[160:163], v[192:195], v[82:85]
	v_mfma_f32_16x16x32_bf16 v[74:77], v[168:171], v[192:195], v[74:77]
	v_mfma_f32_16x16x32_bf16 v[70:73], v[160:163], v[208:211], v[70:73]
	v_mfma_f32_16x16x32_bf16 v[66:69], v[168:171], v[208:211], v[66:69]
	v_mfma_f32_16x16x32_bf16 v[114:117], v[164:167], v[180:183], v[114:117]
	v_mfma_f32_16x16x32_bf16 v[106:109], v[172:175], v[180:183], v[106:109]
	v_mfma_f32_16x16x32_bf16 v[98:101], v[164:167], v[188:191], v[98:101]
	v_mfma_f32_16x16x32_bf16 v[90:93], v[172:175], v[188:191], v[90:93]
	v_mfma_f32_16x16x32_bf16 v[82:85], v[164:167], v[196:199], v[82:85]
	v_mfma_f32_16x16x32_bf16 v[74:77], v[172:175], v[196:199], v[74:77]
	v_mfma_f32_16x16x32_bf16 v[70:73], v[164:167], v[212:215], v[70:73]
	v_mfma_f32_16x16x32_bf16 v[66:69], v[172:175], v[212:215], v[66:69]
	s_barrier
	s_setprio 0
	s_mov_b32 m0, s61
	s_add_u32 s100, s26, 0x80
	s_addc_u32 s101, s27, 0
	ds_read_b128 v[176:179], v142 offset:49152
	ds_read_b128 v[180:183], v142 offset:50176
	ds_read_b128 v[184:187], v142 offset:51200
	ds_read_b128 v[188:191], v142 offset:52224
	ds_read_b128 v[192:195], v142 offset:53248
	ds_read_b128 v[196:199], v142 offset:54272
	ds_read_b128 v[208:211], v142 offset:55296
	ds_read_b128 v[212:215], v142 offset:56320
	global_load_lds_dwordx4 v202, s[100:101]
	s_add_u32 s100, s26, 0x80
	s_addc_u32 s101, s27, 0
	s_mov_b32 m0, s62
	s_nop 0
	global_load_lds_dwordx4 v130, s[100:101]
	s_mov_b32 m0, s55
	s_nop 0
	global_load_lds_dwordx4 v202, s[2:3]
	s_mov_b32 m0, s0
	s_nop 0
	global_load_lds_dwordx4 v130, s[2:3]
	s_add_u32 s100, s24, 0x80
	s_addc_u32 s101, s25, 0
	s_mov_b32 m0, s41
	s_nop 0
	global_load_lds_dwordx4 v134, s[100:101]
	s_add_u32 s100, s24, 0x80
	s_addc_u32 s101, s25, 0
	s_mov_b32 m0, s86
	s_nop 0
	global_load_lds_dwordx4 v132, s[100:101]
	s_waitcnt vmcnt(8)
	s_waitcnt lgkmcnt(0)
	s_setprio 1
	s_barrier
	v_mfma_f32_16x16x32_bf16 v[62:65], v[144:147], v[176:179], v[62:65]
	v_mfma_f32_16x16x32_bf16 v[58:61], v[152:155], v[176:179], v[58:61]
	v_mfma_f32_16x16x32_bf16 v[54:57], v[144:147], v[184:187], v[54:57]
	v_mfma_f32_16x16x32_bf16 v[46:49], v[152:155], v[184:187], v[46:49]
	v_mfma_f32_16x16x32_bf16 v[38:41], v[144:147], v[192:195], v[38:41]
	v_mfma_f32_16x16x32_bf16 v[30:33], v[152:155], v[192:195], v[30:33]
	v_mfma_f32_16x16x32_bf16 v[22:25], v[144:147], v[208:211], v[22:25]
	v_mfma_f32_16x16x32_bf16 v[14:17], v[152:155], v[208:211], v[14:17]
	v_mfma_f32_16x16x32_bf16 v[62:65], v[148:151], v[180:183], v[62:65]
	v_mfma_f32_16x16x32_bf16 v[58:61], v[156:159], v[180:183], v[58:61]
	v_mfma_f32_16x16x32_bf16 v[54:57], v[148:151], v[188:191], v[54:57]
	v_mfma_f32_16x16x32_bf16 v[46:49], v[156:159], v[188:191], v[46:49]
	v_mfma_f32_16x16x32_bf16 v[38:41], v[148:151], v[196:199], v[38:41]
	v_mfma_f32_16x16x32_bf16 v[30:33], v[156:159], v[196:199], v[30:33]
	v_mfma_f32_16x16x32_bf16 v[22:25], v[148:151], v[212:215], v[22:25]
	v_mfma_f32_16x16x32_bf16 v[14:17], v[156:159], v[212:215], v[14:17]
	s_setprio 0
	s_setprio 1
	v_mfma_f32_16x16x32_bf16 v[50:53], v[160:163], v[176:179], v[50:53]
	v_mfma_f32_16x16x32_bf16 v[42:45], v[168:171], v[176:179], v[42:45]
	v_mfma_f32_16x16x32_bf16 v[34:37], v[160:163], v[184:187], v[34:37]
	v_mfma_f32_16x16x32_bf16 v[26:29], v[168:171], v[184:187], v[26:29]
	v_mfma_f32_16x16x32_bf16 v[18:21], v[160:163], v[192:195], v[18:21]
	v_mfma_f32_16x16x32_bf16 v[10:13], v[168:171], v[192:195], v[10:13]
	v_mfma_f32_16x16x32_bf16 v[6:9], v[160:163], v[208:211], v[6:9]
	v_mfma_f32_16x16x32_bf16 v[2:5], v[168:171], v[208:211], v[2:5]
	v_mfma_f32_16x16x32_bf16 v[50:53], v[164:167], v[180:183], v[50:53]
	v_mfma_f32_16x16x32_bf16 v[42:45], v[172:175], v[180:183], v[42:45]
	v_mfma_f32_16x16x32_bf16 v[34:37], v[164:167], v[188:191], v[34:37]
	v_mfma_f32_16x16x32_bf16 v[26:29], v[172:175], v[188:191], v[26:29]
	v_mfma_f32_16x16x32_bf16 v[18:21], v[164:167], v[196:199], v[18:21]
	v_mfma_f32_16x16x32_bf16 v[10:13], v[172:175], v[196:199], v[10:13]
	v_mfma_f32_16x16x32_bf16 v[6:9], v[164:167], v[212:215], v[6:9]
	v_mfma_f32_16x16x32_bf16 v[2:5], v[172:175], v[212:215], v[2:5]
	s_barrier
	s_setprio 0
	s_andn2_b64 vcc, exec, s[22:23]
	s_mov_b64 s[2:3], -1
	s_mov_b64 s[22:23], 0
	s_mov_b64 s[4:5], 0x100
	s_cbranch_vccz .LBB0_1242
	s_and_b64 vcc, exec, s[10:11]
	s_cbranch_vccz .LBB0_1245
	s_barrier

.LBB0_1363:
	s_add_u32 s0, s20, 0xfffe0080
	s_addc_u32 s1, s21, -1
	s_add_i32 s33, 0, 0x10000
	s_cmp_eq_u32 s59, 4
	s_cselect_b32 s5, s38, s1
	s_cselect_b32 s4, s39, s0
	v_add_u32_e32 v147, s33, v143
	s_cselect_b32 s3, s40, s58
	s_cselect_b32 s2, s41, s49
	s_add_i32 s55, 0, 0x14000
	ds_read_b128 v[148:151], v147
	ds_read_b128 v[152:155], v147 offset:1024
	ds_read_b128 v[156:159], v147 offset:2048
	ds_read_b128 v[160:163], v147 offset:3072
	v_add_u32_e32 v147, s55, v143
	ds_read_b128 v[164:167], v147
	ds_read_b128 v[168:171], v147 offset:1024
	ds_read_b128 v[172:175], v147 offset:2048
	ds_read_b128 v[176:179], v147 offset:3072
	s_add_i32 m0, s25, 0xc000
	ds_read_b128 v[180:183], v146
	ds_read_b128 v[184:187], v146 offset:1024
	ds_read_b128 v[188:191], v146 offset:2048
	ds_read_b128 v[192:195], v146 offset:3072
	ds_read_b128 v[196:199], v146 offset:4096
	ds_read_b128 v[208:211], v146 offset:5120
	ds_read_b128 v[212:215], v146 offset:6144
	ds_read_b128 v[216:219], v146 offset:7168
	global_load_lds_dwordx4 v138, s[20:21]
	s_add_i32 m0, s25, 0xe000
	s_nop 0
	global_load_lds_dwordx4 v140, s[20:21]
	s_waitcnt vmcnt(8)
	s_waitcnt lgkmcnt(0)
	s_setprio 1
	s_barrier
	v_mfma_f32_16x16x32_bf16 v[126:129], v[148:151], v[180:183], v[126:129]
	v_mfma_f32_16x16x32_bf16 v[122:125], v[156:159], v[180:183], v[122:125]
	v_mfma_f32_16x16x32_bf16 v[110:113], v[148:151], v[188:191], v[110:113]
	v_mfma_f32_16x16x32_bf16 v[106:109], v[156:159], v[188:191], v[106:109]
	v_mfma_f32_16x16x32_bf16 v[94:97], v[148:151], v[196:199], v[94:97]
	v_mfma_f32_16x16x32_bf16 v[90:93], v[156:159], v[196:199], v[90:93]
	v_mfma_f32_16x16x32_bf16 v[78:81], v[148:151], v[212:215], v[78:81]
	v_mfma_f32_16x16x32_bf16 v[74:77], v[156:159], v[212:215], v[74:77]
	v_mfma_f32_16x16x32_bf16 v[126:129], v[152:155], v[184:187], v[126:129]
	v_mfma_f32_16x16x32_bf16 v[122:125], v[160:163], v[184:187], v[122:125]
	v_mfma_f32_16x16x32_bf16 v[110:113], v[152:155], v[192:195], v[110:113]
	v_mfma_f32_16x16x32_bf16 v[106:109], v[160:163], v[192:195], v[106:109]
	v_mfma_f32_16x16x32_bf16 v[94:97], v[152:155], v[208:211], v[94:97]
	v_mfma_f32_16x16x32_bf16 v[90:93], v[160:163], v[208:211], v[90:93]
	v_mfma_f32_16x16x32_bf16 v[78:81], v[152:155], v[216:219], v[78:81]
	v_mfma_f32_16x16x32_bf16 v[74:77], v[160:163], v[216:219], v[74:77]
	s_setprio 0
	s_setprio 1
	v_mfma_f32_16x16x32_bf16 v[118:121], v[164:167], v[180:183], v[118:121]
	v_mfma_f32_16x16x32_bf16 v[114:117], v[172:175], v[180:183], v[114:117]
	v_mfma_f32_16x16x32_bf16 v[102:105], v[164:167], v[188:191], v[102:105]
	v_mfma_f32_16x16x32_bf16 v[98:101], v[172:175], v[188:191], v[98:101]
	v_mfma_f32_16x16x32_bf16 v[86:89], v[164:167], v[196:199], v[86:89]
	v_mfma_f32_16x16x32_bf16 v[82:85], v[172:175], v[196:199], v[82:85]
	v_mfma_f32_16x16x32_bf16 v[70:73], v[164:167], v[212:215], v[70:73]
	v_mfma_f32_16x16x32_bf16 v[66:69], v[172:175], v[212:215], v[66:69]
	v_mfma_f32_16x16x32_bf16 v[118:121], v[168:171], v[184:187], v[118:121]
	v_mfma_f32_16x16x32_bf16 v[114:117], v[176:179], v[184:187], v[114:117]
	v_mfma_f32_16x16x32_bf16 v[102:105], v[168:171], v[192:195], v[102:105]
	v_mfma_f32_16x16x32_bf16 v[98:101], v[176:179], v[192:195], v[98:101]
	v_mfma_f32_16x16x32_bf16 v[86:89], v[168:171], v[208:211], v[86:89]
	v_mfma_f32_16x16x32_bf16 v[82:85], v[176:179], v[208:211], v[82:85]
	v_mfma_f32_16x16x32_bf16 v[70:73], v[168:171], v[216:219], v[70:73]
	v_mfma_f32_16x16x32_bf16 v[66:69], v[176:179], v[216:219], v[66:69]
	s_barrier
	s_setprio 0
	s_add_i32 s0, s33, s24
	s_mov_b32 m0, s0
	ds_read_b128 v[180:183], v146 offset:16384
	ds_read_b128 v[184:187], v146 offset:17408
	ds_read_b128 v[188:191], v146 offset:18432
	ds_read_b128 v[192:195], v146 offset:19456
	ds_read_b128 v[196:199], v146 offset:20480
	ds_read_b128 v[208:211], v146 offset:21504
	ds_read_b128 v[212:215], v146 offset:22528
	ds_read_b128 v[216:219], v146 offset:23552
	global_load_lds_dwordx4 v134, s[2:3]
	s_add_i32 m0, s0, 0x2000
	s_add_u32 s0, s2, 0x20000
	s_addc_u32 s1, s3, 0
	s_add_i32 s33, s55, s24
	global_load_lds_dwordx4 v130, s[2:3]
	s_mov_b32 m0, s33
	s_nop 0
	global_load_lds_dwordx4 v134, s[0:1]
	s_add_i32 m0, s33, 0x2000
	s_nop 0
	global_load_lds_dwordx4 v130, s[0:1]
	s_mov_b32 m0, s25
	s_nop 0
	global_load_lds_dwordx4 v136, s[4:5]
	s_mov_b32 m0, s26
	s_nop 0
	global_load_lds_dwordx4 v132, s[4:5]
	s_waitcnt vmcnt(8)
	s_waitcnt lgkmcnt(0)
	s_setprio 1
	s_barrier
	v_mfma_f32_16x16x32_bf16 v[62:65], v[148:151], v[180:183], v[62:65]
	v_mfma_f32_16x16x32_bf16 v[58:61], v[156:159], v[180:183], v[58:61]
	v_mfma_f32_16x16x32_bf16 v[46:49], v[148:151], v[188:191], v[46:49]
	v_mfma_f32_16x16x32_bf16 v[42:45], v[156:159], v[188:191], v[42:45]
	v_mfma_f32_16x16x32_bf16 v[30:33], v[148:151], v[196:199], v[30:33]
	v_mfma_f32_16x16x32_bf16 v[26:29], v[156:159], v[196:199], v[26:29]
	v_mfma_f32_16x16x32_bf16 v[14:17], v[148:151], v[212:215], v[14:17]
	v_mfma_f32_16x16x32_bf16 v[10:13], v[156:159], v[212:215], v[10:13]
	v_mfma_f32_16x16x32_bf16 v[62:65], v[152:155], v[184:187], v[62:65]
	v_mfma_f32_16x16x32_bf16 v[58:61], v[160:163], v[184:187], v[58:61]
	v_mfma_f32_16x16x32_bf16 v[46:49], v[152:155], v[192:195], v[46:49]
	v_mfma_f32_16x16x32_bf16 v[42:45], v[160:163], v[192:195], v[42:45]
	v_mfma_f32_16x16x32_bf16 v[30:33], v[152:155], v[208:211], v[30:33]
	v_mfma_f32_16x16x32_bf16 v[26:29], v[160:163], v[208:211], v[26:29]
	v_mfma_f32_16x16x32_bf16 v[14:17], v[152:155], v[216:219], v[14:17]
	v_mfma_f32_16x16x32_bf16 v[10:13], v[160:163], v[216:219], v[10:13]
	s_setprio 0
	s_setprio 1
	v_mfma_f32_16x16x32_bf16 v[54:57], v[164:167], v[180:183], v[54:57]
	v_mfma_f32_16x16x32_bf16 v[50:53], v[172:175], v[180:183], v[50:53]
	v_mfma_f32_16x16x32_bf16 v[38:41], v[164:167], v[188:191], v[38:41]
	v_mfma_f32_16x16x32_bf16 v[34:37], v[172:175], v[188:191], v[34:37]
	v_mfma_f32_16x16x32_bf16 v[22:25], v[164:167], v[196:199], v[22:25]
	v_mfma_f32_16x16x32_bf16 v[18:21], v[172:175], v[196:199], v[18:21]
	v_mfma_f32_16x16x32_bf16 v[6:9], v[164:167], v[212:215], v[6:9]
	v_mfma_f32_16x16x32_bf16 v[2:5], v[172:175], v[212:215], v[2:5]
	v_mfma_f32_16x16x32_bf16 v[54:57], v[168:171], v[184:187], v[54:57]
	v_mfma_f32_16x16x32_bf16 v[50:53], v[176:179], v[184:187], v[50:53]
	v_mfma_f32_16x16x32_bf16 v[38:41], v[168:171], v[192:195], v[38:41]
	v_mfma_f32_16x16x32_bf16 v[34:37], v[176:179], v[192:195], v[34:37]
	v_mfma_f32_16x16x32_bf16 v[22:25], v[168:171], v[208:211], v[22:25]
	v_mfma_f32_16x16x32_bf16 v[18:21], v[176:179], v[208:211], v[18:21]
	v_mfma_f32_16x16x32_bf16 v[6:9], v[168:171], v[216:219], v[6:9]
	v_mfma_f32_16x16x32_bf16 v[2:5], v[176:179], v[216:219], v[2:5]
	s_barrier
	s_setprio 0
	s_add_i32 s33, 0, 0x18000
	v_add_u32_e32 v147, s33, v143
	s_add_i32 s55, 0, 0x1c000
	ds_read_b128 v[148:151], v147
	ds_read_b128 v[152:155], v147 offset:1024
	ds_read_b128 v[156:159], v147 offset:2048
	ds_read_b128 v[160:163], v147 offset:3072
	v_add_u32_e32 v147, s55, v143
	ds_read_b128 v[164:167], v147
	ds_read_b128 v[168:171], v147 offset:1024
	ds_read_b128 v[172:175], v147 offset:2048
	ds_read_b128 v[176:179], v147 offset:3072
	s_add_u32 s0, s4, 0x20000
	s_addc_u32 s1, s5, 0
	s_mov_b32 m0, s27
	ds_read_b128 v[180:183], v146 offset:32768
	ds_read_b128 v[184:187], v146 offset:33792
	ds_read_b128 v[188:191], v146 offset:34816
	ds_read_b128 v[192:195], v146 offset:35840
	ds_read_b128 v[196:199], v146 offset:36864
	ds_read_b128 v[208:211], v146 offset:37888
	ds_read_b128 v[212:215], v146 offset:38912
	ds_read_b128 v[216:219], v146 offset:39936
	global_load_lds_dwordx4 v136, s[0:1]
	s_mov_b32 m0, s28
	s_nop 0
	global_load_lds_dwordx4 v132, s[0:1]
	s_waitcnt vmcnt(8)
	s_waitcnt lgkmcnt(0)
	s_setprio 1
	s_barrier
	v_mfma_f32_16x16x32_bf16 v[126:129], v[148:151], v[180:183], v[126:129]
	v_mfma_f32_16x16x32_bf16 v[122:125], v[156:159], v[180:183], v[122:125]
	v_mfma_f32_16x16x32_bf16 v[110:113], v[148:151], v[188:191], v[110:113]
	v_mfma_f32_16x16x32_bf16 v[106:109], v[156:159], v[188:191], v[106:109]
	v_mfma_f32_16x16x32_bf16 v[94:97], v[148:151], v[196:199], v[94:97]
	v_mfma_f32_16x16x32_bf16 v[90:93], v[156:159], v[196:199], v[90:93]
	v_mfma_f32_16x16x32_bf16 v[78:81], v[148:151], v[212:215], v[78:81]
	v_mfma_f32_16x16x32_bf16 v[74:77], v[156:159], v[212:215], v[74:77]
	v_mfma_f32_16x16x32_bf16 v[126:129], v[152:155], v[184:187], v[126:129]
	v_mfma_f32_16x16x32_bf16 v[122:125], v[160:163], v[184:187], v[122:125]
	v_mfma_f32_16x16x32_bf16 v[110:113], v[152:155], v[192:195], v[110:113]
	v_mfma_f32_16x16x32_bf16 v[106:109], v[160:163], v[192:195], v[106:109]
	v_mfma_f32_16x16x32_bf16 v[94:97], v[152:155], v[208:211], v[94:97]
	v_mfma_f32_16x16x32_bf16 v[90:93], v[160:163], v[208:211], v[90:93]
	v_mfma_f32_16x16x32_bf16 v[78:81], v[152:155], v[216:219], v[78:81]
	v_mfma_f32_16x16x32_bf16 v[74:77], v[160:163], v[216:219], v[74:77]
	s_setprio 0
	s_setprio 1
	v_mfma_f32_16x16x32_bf16 v[118:121], v[164:167], v[180:183], v[118:121]
	v_mfma_f32_16x16x32_bf16 v[114:117], v[172:175], v[180:183], v[114:117]
	v_mfma_f32_16x16x32_bf16 v[102:105], v[164:167], v[188:191], v[102:105]
	v_mfma_f32_16x16x32_bf16 v[98:101], v[172:175], v[188:191], v[98:101]
	v_mfma_f32_16x16x32_bf16 v[86:89], v[164:167], v[196:199], v[86:89]
	v_mfma_f32_16x16x32_bf16 v[82:85], v[172:175], v[196:199], v[82:85]
	v_mfma_f32_16x16x32_bf16 v[70:73], v[164:167], v[212:215], v[70:73]
	v_mfma_f32_16x16x32_bf16 v[66:69], v[172:175], v[212:215], v[66:69]
	v_mfma_f32_16x16x32_bf16 v[118:121], v[168:171], v[184:187], v[118:121]
	v_mfma_f32_16x16x32_bf16 v[114:117], v[176:179], v[184:187], v[114:117]
	v_mfma_f32_16x16x32_bf16 v[102:105], v[168:171], v[192:195], v[102:105]
	v_mfma_f32_16x16x32_bf16 v[98:101], v[176:179], v[192:195], v[98:101]
	v_mfma_f32_16x16x32_bf16 v[86:89], v[168:171], v[208:211], v[86:89]
	v_mfma_f32_16x16x32_bf16 v[82:85], v[176:179], v[208:211], v[82:85]
	v_mfma_f32_16x16x32_bf16 v[70:73], v[168:171], v[216:219], v[70:73]
	v_mfma_f32_16x16x32_bf16 v[66:69], v[176:179], v[216:219], v[66:69]
	s_barrier
	s_setprio 0
	s_add_i32 s0, s33, s24
	s_add_u32 s100, s2, 0x80
	s_addc_u32 s101, s3, 0
	s_mov_b32 m0, s0
	ds_read_b128 v[180:183], v146 offset:49152
	ds_read_b128 v[184:187], v146 offset:50176
	ds_read_b128 v[188:191], v146 offset:51200
	ds_read_b128 v[192:195], v146 offset:52224
	ds_read_b128 v[196:199], v146 offset:53248
	ds_read_b128 v[208:211], v146 offset:54272
	ds_read_b128 v[212:215], v146 offset:55296
	ds_read_b128 v[216:219], v146 offset:56320
	global_load_lds_dwordx4 v134, s[100:101]
	s_add_i32 m0, s0, 0x2000
	s_add_u32 s100, s2, 0x80
	s_addc_u32 s101, s3, 0
	s_add_u32 s0, s2, 0x20080
	s_addc_u32 s1, s3, 0
	s_add_i32 s2, s55, s24
	global_load_lds_dwordx4 v130, s[100:101]
	s_mov_b32 m0, s2
	s_nop 0
	global_load_lds_dwordx4 v134, s[0:1]
	s_add_i32 m0, s2, 0x2000
	s_nop 0
	global_load_lds_dwordx4 v130, s[0:1]
	s_add_u32 s100, s4, 0x80
	s_addc_u32 s101, s5, 0
	s_mov_b32 m0, s29
	s_nop 0
	global_load_lds_dwordx4 v136, s[100:101]
	s_add_u32 s100, s4, 0x80
	s_addc_u32 s101, s5, 0
	s_mov_b32 m0, s30
	s_nop 0
	global_load_lds_dwordx4 v132, s[100:101]
	s_waitcnt vmcnt(8)
	s_waitcnt lgkmcnt(0)
	s_setprio 1
	s_barrier
	v_mfma_f32_16x16x32_bf16 v[62:65], v[148:151], v[180:183], v[62:65]
	v_mfma_f32_16x16x32_bf16 v[58:61], v[156:159], v[180:183], v[58:61]
	v_mfma_f32_16x16x32_bf16 v[46:49], v[148:151], v[188:191], v[46:49]
	v_mfma_f32_16x16x32_bf16 v[42:45], v[156:159], v[188:191], v[42:45]
	v_mfma_f32_16x16x32_bf16 v[30:33], v[148:151], v[196:199], v[30:33]
	v_mfma_f32_16x16x32_bf16 v[26:29], v[156:159], v[196:199], v[26:29]
	v_mfma_f32_16x16x32_bf16 v[14:17], v[148:151], v[212:215], v[14:17]
	v_mfma_f32_16x16x32_bf16 v[10:13], v[156:159], v[212:215], v[10:13]
	v_mfma_f32_16x16x32_bf16 v[62:65], v[152:155], v[184:187], v[62:65]
	v_mfma_f32_16x16x32_bf16 v[58:61], v[160:163], v[184:187], v[58:61]
	v_mfma_f32_16x16x32_bf16 v[46:49], v[152:155], v[192:195], v[46:49]
	v_mfma_f32_16x16x32_bf16 v[42:45], v[160:163], v[192:195], v[42:45]
	v_mfma_f32_16x16x32_bf16 v[30:33], v[152:155], v[208:211], v[30:33]
	v_mfma_f32_16x16x32_bf16 v[26:29], v[160:163], v[208:211], v[26:29]
	v_mfma_f32_16x16x32_bf16 v[14:17], v[152:155], v[216:219], v[14:17]
	v_mfma_f32_16x16x32_bf16 v[10:13], v[160:163], v[216:219], v[10:13]
	s_setprio 0
	s_setprio 1
	v_mfma_f32_16x16x32_bf16 v[54:57], v[164:167], v[180:183], v[54:57]
	v_mfma_f32_16x16x32_bf16 v[50:53], v[172:175], v[180:183], v[50:53]
	v_mfma_f32_16x16x32_bf16 v[38:41], v[164:167], v[188:191], v[38:41]
	v_mfma_f32_16x16x32_bf16 v[34:37], v[172:175], v[188:191], v[34:37]
	v_mfma_f32_16x16x32_bf16 v[22:25], v[164:167], v[196:199], v[22:25]
	v_mfma_f32_16x16x32_bf16 v[18:21], v[172:175], v[196:199], v[18:21]
	v_mfma_f32_16x16x32_bf16 v[6:9], v[164:167], v[212:215], v[6:9]
	v_mfma_f32_16x16x32_bf16 v[2:5], v[172:175], v[212:215], v[2:5]
	v_mfma_f32_16x16x32_bf16 v[54:57], v[168:171], v[184:187], v[54:57]
	v_mfma_f32_16x16x32_bf16 v[50:53], v[176:179], v[184:187], v[50:53]
	v_mfma_f32_16x16x32_bf16 v[38:41], v[168:171], v[192:195], v[38:41]
	v_mfma_f32_16x16x32_bf16 v[34:37], v[176:179], v[192:195], v[34:37]
	v_mfma_f32_16x16x32_bf16 v[22:25], v[168:171], v[208:211], v[22:25]
	v_mfma_f32_16x16x32_bf16 v[18:21], v[176:179], v[208:211], v[18:21]
	v_mfma_f32_16x16x32_bf16 v[6:9], v[168:171], v[216:219], v[6:9]
	v_mfma_f32_16x16x32_bf16 v[2:5], v[176:179], v[216:219], v[2:5]
	s_barrier
	s_setprio 0
	s_add_i32 s59, s59, 2
	s_add_u32 s20, s20, 0x100
	s_addc_u32 s21, s21, 0
	s_add_u32 s49, s49, 0x100
	s_addc_u32 s58, s58, 0
	s_cmp_gt_u32 s59, 5
	s_cbranch_scc0 .LBB0_1363
	s_and_b64 vcc, exec, s[14:15]
	s_cbranch_vccz .LBB0_1366
	s_barrier

.LBB0_1428:
	s_add_u32 s0, s26, 0xfff80080
	s_addc_u32 s1, s27, -1
	s_add_i32 s33, 0, 0x10000
	s_cmp_eq_u32 s61, 28
	s_cselect_b32 s5, s17, s1
	s_cselect_b32 s4, s49, s0
	s_cselect_b32 s3, s15, s60
	s_cselect_b32 s2, s58, s59
	s_add_i32 s55, 0, 0x14000
	v_add_u32_e32 v142, s33, v187
	v_add_u32_e32 v158, s55, v187
	ds_read_b128 v[126:129], v142
	ds_read_b128 v[134:137], v142 offset:1024
	ds_read_b128 v[138:141], v142 offset:2048
	ds_read_b128 v[142:145], v142 offset:3072
	ds_read_b128 v[146:149], v158
	ds_read_b128 v[150:153], v158 offset:1024
	ds_read_b128 v[154:157], v158 offset:2048
	ds_read_b128 v[158:161], v158 offset:3072
	s_add_i32 m0, s23, 0xc000
	ds_read_b128 v[172:175], v189
	ds_read_b128 v[176:179], v189 offset:1024
	ds_read_b128 v[180:183], v189 offset:2048
	ds_read_b128 v[190:193], v189 offset:3072
	ds_read_b128 v[194:197], v189 offset:4096
	ds_read_b128 v[198:201], v189 offset:5120
	ds_read_b128 v[208:211], v189 offset:6144
	ds_read_b128 v[212:215], v189 offset:7168
	global_load_lds_dwordx4 v168, s[26:27]
	s_add_i32 m0, s23, 0xe000
	s_nop 0
	global_load_lds_dwordx4 v170, s[26:27]
	s_waitcnt vmcnt(8)
	s_waitcnt lgkmcnt(0)
	s_setprio 1
	s_barrier
	v_mfma_f32_16x16x32_bf16 v[130:133], v[126:129], v[172:175], v[130:133]
	v_mfma_f32_16x16x32_bf16 v[118:121], v[138:141], v[172:175], v[118:121]
	v_mfma_f32_16x16x32_bf16 v[110:113], v[126:129], v[180:183], v[110:113]
	v_mfma_f32_16x16x32_bf16 v[102:105], v[138:141], v[180:183], v[102:105]
	v_mfma_f32_16x16x32_bf16 v[94:97], v[126:129], v[194:197], v[94:97]
	v_mfma_f32_16x16x32_bf16 v[86:89], v[138:141], v[194:197], v[86:89]
	v_mfma_f32_16x16x32_bf16 v[78:81], v[126:129], v[208:211], v[78:81]
	v_mfma_f32_16x16x32_bf16 v[70:73], v[138:141], v[208:211], v[70:73]
	v_mfma_f32_16x16x32_bf16 v[130:133], v[134:137], v[176:179], v[130:133]
	v_mfma_f32_16x16x32_bf16 v[118:121], v[142:145], v[176:179], v[118:121]
	v_mfma_f32_16x16x32_bf16 v[110:113], v[134:137], v[190:193], v[110:113]
	v_mfma_f32_16x16x32_bf16 v[102:105], v[142:145], v[190:193], v[102:105]
	v_mfma_f32_16x16x32_bf16 v[94:97], v[134:137], v[198:201], v[94:97]
	v_mfma_f32_16x16x32_bf16 v[86:89], v[142:145], v[198:201], v[86:89]
	v_mfma_f32_16x16x32_bf16 v[78:81], v[134:137], v[212:215], v[78:81]
	v_mfma_f32_16x16x32_bf16 v[70:73], v[142:145], v[212:215], v[70:73]
	s_setprio 0
	s_setprio 1
	v_mfma_f32_16x16x32_bf16 v[122:125], v[146:149], v[172:175], v[122:125]
	v_mfma_f32_16x16x32_bf16 v[114:117], v[154:157], v[172:175], v[114:117]
	v_mfma_f32_16x16x32_bf16 v[106:109], v[146:149], v[180:183], v[106:109]
	v_mfma_f32_16x16x32_bf16 v[98:101], v[154:157], v[180:183], v[98:101]
	v_mfma_f32_16x16x32_bf16 v[90:93], v[146:149], v[194:197], v[90:93]
	v_mfma_f32_16x16x32_bf16 v[82:85], v[154:157], v[194:197], v[82:85]
	v_mfma_f32_16x16x32_bf16 v[74:77], v[146:149], v[208:211], v[74:77]
	v_mfma_f32_16x16x32_bf16 v[66:69], v[154:157], v[208:211], v[66:69]
	v_mfma_f32_16x16x32_bf16 v[122:125], v[150:153], v[176:179], v[122:125]
	v_mfma_f32_16x16x32_bf16 v[114:117], v[158:161], v[176:179], v[114:117]
	v_mfma_f32_16x16x32_bf16 v[106:109], v[150:153], v[190:193], v[106:109]
	v_mfma_f32_16x16x32_bf16 v[98:101], v[158:161], v[190:193], v[98:101]
	v_mfma_f32_16x16x32_bf16 v[90:93], v[150:153], v[198:201], v[90:93]
	v_mfma_f32_16x16x32_bf16 v[82:85], v[158:161], v[198:201], v[82:85]
	v_mfma_f32_16x16x32_bf16 v[74:77], v[150:153], v[212:215], v[74:77]
	v_mfma_f32_16x16x32_bf16 v[66:69], v[158:161], v[212:215], v[66:69]
	s_barrier
	s_setprio 0
	s_add_i32 s0, s33, s34
	s_mov_b32 m0, s0
	ds_read_b128 v[172:175], v189 offset:16384
	ds_read_b128 v[176:179], v189 offset:17408
	ds_read_b128 v[180:183], v189 offset:18432
	ds_read_b128 v[190:193], v189 offset:19456
	ds_read_b128 v[194:197], v189 offset:20480
	ds_read_b128 v[198:201], v189 offset:21504
	ds_read_b128 v[208:211], v189 offset:22528
	ds_read_b128 v[212:215], v189 offset:23552
	global_load_lds_dwordx4 v202, s[2:3]
	s_add_i32 m0, s0, 0x2000
	s_add_u32 s0, s2, 0x80000
	s_addc_u32 s1, s3, 0
	s_add_i32 s33, s55, s34
	global_load_lds_dwordx4 v162, s[2:3]
	s_mov_b32 m0, s33
	s_nop 0
	global_load_lds_dwordx4 v202, s[0:1]
	s_add_i32 m0, s33, 0x2000
	s_nop 0
	global_load_lds_dwordx4 v162, s[0:1]
	s_mov_b32 m0, s23
	s_nop 0
	global_load_lds_dwordx4 v166, s[4:5]
	s_mov_b32 m0, s25
	s_nop 0
	global_load_lds_dwordx4 v164, s[4:5]
	s_waitcnt vmcnt(8)
	s_waitcnt lgkmcnt(0)
	s_setprio 1
	s_barrier
	v_mfma_f32_16x16x32_bf16 v[62:65], v[126:129], v[172:175], v[62:65]
	v_mfma_f32_16x16x32_bf16 v[54:57], v[138:141], v[172:175], v[54:57]
	v_mfma_f32_16x16x32_bf16 v[46:49], v[126:129], v[180:183], v[46:49]
	v_mfma_f32_16x16x32_bf16 v[38:41], v[138:141], v[180:183], v[38:41]
	v_mfma_f32_16x16x32_bf16 v[30:33], v[126:129], v[194:197], v[30:33]
	v_mfma_f32_16x16x32_bf16 v[22:25], v[138:141], v[194:197], v[22:25]
	v_mfma_f32_16x16x32_bf16 v[14:17], v[126:129], v[208:211], v[14:17]
	v_mfma_f32_16x16x32_bf16 v[6:9], v[138:141], v[208:211], v[6:9]
	v_mfma_f32_16x16x32_bf16 v[62:65], v[134:137], v[176:179], v[62:65]
	v_mfma_f32_16x16x32_bf16 v[54:57], v[142:145], v[176:179], v[54:57]
	v_mfma_f32_16x16x32_bf16 v[46:49], v[134:137], v[190:193], v[46:49]
	v_mfma_f32_16x16x32_bf16 v[38:41], v[142:145], v[190:193], v[38:41]
	v_mfma_f32_16x16x32_bf16 v[30:33], v[134:137], v[198:201], v[30:33]
	v_mfma_f32_16x16x32_bf16 v[22:25], v[142:145], v[198:201], v[22:25]
	v_mfma_f32_16x16x32_bf16 v[14:17], v[134:137], v[212:215], v[14:17]
	v_mfma_f32_16x16x32_bf16 v[6:9], v[142:145], v[212:215], v[6:9]
	s_setprio 0
	s_setprio 1
	v_mfma_f32_16x16x32_bf16 v[58:61], v[146:149], v[172:175], v[58:61]
	v_mfma_f32_16x16x32_bf16 v[50:53], v[154:157], v[172:175], v[50:53]
	v_mfma_f32_16x16x32_bf16 v[42:45], v[146:149], v[180:183], v[42:45]
	v_mfma_f32_16x16x32_bf16 v[34:37], v[154:157], v[180:183], v[34:37]
	v_mfma_f32_16x16x32_bf16 v[26:29], v[146:149], v[194:197], v[26:29]
	v_mfma_f32_16x16x32_bf16 v[18:21], v[154:157], v[194:197], v[18:21]
	v_mfma_f32_16x16x32_bf16 v[10:13], v[146:149], v[208:211], v[10:13]
	v_mfma_f32_16x16x32_bf16 v[2:5], v[154:157], v[208:211], v[2:5]
	v_mfma_f32_16x16x32_bf16 v[58:61], v[150:153], v[176:179], v[58:61]
	v_mfma_f32_16x16x32_bf16 v[50:53], v[158:161], v[176:179], v[50:53]
	v_mfma_f32_16x16x32_bf16 v[42:45], v[150:153], v[190:193], v[42:45]
	v_mfma_f32_16x16x32_bf16 v[34:37], v[158:161], v[190:193], v[34:37]
	v_mfma_f32_16x16x32_bf16 v[26:29], v[150:153], v[198:201], v[26:29]
	v_mfma_f32_16x16x32_bf16 v[18:21], v[158:161], v[198:201], v[18:21]
	v_mfma_f32_16x16x32_bf16 v[10:13], v[150:153], v[212:215], v[10:13]
	v_mfma_f32_16x16x32_bf16 v[2:5], v[158:161], v[212:215], v[2:5]
	s_barrier
	s_setprio 0
	s_add_i32 s33, 0, 0x18000
	s_add_i32 s55, 0, 0x1c000
	v_add_u32_e32 v142, s33, v187
	v_add_u32_e32 v158, s55, v187
	ds_read_b128 v[126:129], v142
	ds_read_b128 v[134:137], v142 offset:1024
	ds_read_b128 v[138:141], v142 offset:2048
	ds_read_b128 v[142:145], v142 offset:3072
	ds_read_b128 v[146:149], v158
	ds_read_b128 v[150:153], v158 offset:1024
	ds_read_b128 v[154:157], v158 offset:2048
	ds_read_b128 v[158:161], v158 offset:3072
	s_add_u32 s0, s4, 0x80000
	s_addc_u32 s1, s5, 0
	s_mov_b32 m0, s35
	ds_read_b128 v[172:175], v189 offset:32768
	ds_read_b128 v[176:179], v189 offset:33792
	ds_read_b128 v[180:183], v189 offset:34816
	ds_read_b128 v[190:193], v189 offset:35840
	ds_read_b128 v[194:197], v189 offset:36864
	ds_read_b128 v[198:201], v189 offset:37888
	ds_read_b128 v[208:211], v189 offset:38912
	ds_read_b128 v[212:215], v189 offset:39936
	global_load_lds_dwordx4 v166, s[0:1]
	s_mov_b32 m0, s36
	s_nop 0
	global_load_lds_dwordx4 v164, s[0:1]
	s_waitcnt vmcnt(8)
	s_waitcnt lgkmcnt(0)
	s_setprio 1
	s_barrier
	v_mfma_f32_16x16x32_bf16 v[130:133], v[126:129], v[172:175], v[130:133]
	v_mfma_f32_16x16x32_bf16 v[118:121], v[138:141], v[172:175], v[118:121]
	v_mfma_f32_16x16x32_bf16 v[110:113], v[126:129], v[180:183], v[110:113]
	v_mfma_f32_16x16x32_bf16 v[102:105], v[138:141], v[180:183], v[102:105]
	v_mfma_f32_16x16x32_bf16 v[94:97], v[126:129], v[194:197], v[94:97]
	v_mfma_f32_16x16x32_bf16 v[86:89], v[138:141], v[194:197], v[86:89]
	v_mfma_f32_16x16x32_bf16 v[78:81], v[126:129], v[208:211], v[78:81]
	v_mfma_f32_16x16x32_bf16 v[70:73], v[138:141], v[208:211], v[70:73]
	v_mfma_f32_16x16x32_bf16 v[130:133], v[134:137], v[176:179], v[130:133]
	v_mfma_f32_16x16x32_bf16 v[118:121], v[142:145], v[176:179], v[118:121]
	v_mfma_f32_16x16x32_bf16 v[110:113], v[134:137], v[190:193], v[110:113]
	v_mfma_f32_16x16x32_bf16 v[102:105], v[142:145], v[190:193], v[102:105]
	v_mfma_f32_16x16x32_bf16 v[94:97], v[134:137], v[198:201], v[94:97]
	v_mfma_f32_16x16x32_bf16 v[86:89], v[142:145], v[198:201], v[86:89]
	v_mfma_f32_16x16x32_bf16 v[78:81], v[134:137], v[212:215], v[78:81]
	v_mfma_f32_16x16x32_bf16 v[70:73], v[142:145], v[212:215], v[70:73]
	s_setprio 0
	s_setprio 1
	v_mfma_f32_16x16x32_bf16 v[122:125], v[146:149], v[172:175], v[122:125]
	v_mfma_f32_16x16x32_bf16 v[114:117], v[154:157], v[172:175], v[114:117]
	v_mfma_f32_16x16x32_bf16 v[106:109], v[146:149], v[180:183], v[106:109]
	v_mfma_f32_16x16x32_bf16 v[98:101], v[154:157], v[180:183], v[98:101]
	v_mfma_f32_16x16x32_bf16 v[90:93], v[146:149], v[194:197], v[90:93]
	v_mfma_f32_16x16x32_bf16 v[82:85], v[154:157], v[194:197], v[82:85]
	v_mfma_f32_16x16x32_bf16 v[74:77], v[146:149], v[208:211], v[74:77]
	v_mfma_f32_16x16x32_bf16 v[66:69], v[154:157], v[208:211], v[66:69]
	v_mfma_f32_16x16x32_bf16 v[122:125], v[150:153], v[176:179], v[122:125]
	v_mfma_f32_16x16x32_bf16 v[114:117], v[158:161], v[176:179], v[114:117]
	v_mfma_f32_16x16x32_bf16 v[106:109], v[150:153], v[190:193], v[106:109]
	v_mfma_f32_16x16x32_bf16 v[98:101], v[158:161], v[190:193], v[98:101]
	v_mfma_f32_16x16x32_bf16 v[90:93], v[150:153], v[198:201], v[90:93]
	v_mfma_f32_16x16x32_bf16 v[82:85], v[158:161], v[198:201], v[82:85]
	v_mfma_f32_16x16x32_bf16 v[74:77], v[150:153], v[212:215], v[74:77]
	v_mfma_f32_16x16x32_bf16 v[66:69], v[158:161], v[212:215], v[66:69]
	s_barrier
	s_setprio 0
	s_add_i32 s0, s33, s34
	s_add_u32 s100, s2, 0x80
	s_addc_u32 s101, s3, 0
	s_mov_b32 m0, s0
	ds_read_b128 v[172:175], v189 offset:49152
	ds_read_b128 v[176:179], v189 offset:50176
	ds_read_b128 v[180:183], v189 offset:51200
	ds_read_b128 v[190:193], v189 offset:52224
	ds_read_b128 v[194:197], v189 offset:53248
	ds_read_b128 v[198:201], v189 offset:54272
	ds_read_b128 v[208:211], v189 offset:55296
	ds_read_b128 v[212:215], v189 offset:56320
	global_load_lds_dwordx4 v202, s[100:101]
	s_add_i32 m0, s0, 0x2000
	s_add_u32 s100, s2, 0x80
	s_addc_u32 s101, s3, 0
	s_add_u32 s0, s2, 0x80080
	s_addc_u32 s1, s3, 0
	s_add_i32 s2, s55, s34
	global_load_lds_dwordx4 v162, s[100:101]
	s_mov_b32 m0, s2
	s_nop 0
	global_load_lds_dwordx4 v202, s[0:1]
	s_add_i32 m0, s2, 0x2000
	s_nop 0
	global_load_lds_dwordx4 v162, s[0:1]
	s_add_u32 s100, s4, 0x80
	s_addc_u32 s101, s5, 0
	s_mov_b32 m0, s39
	s_nop 0
	global_load_lds_dwordx4 v166, s[100:101]
	s_add_u32 s100, s4, 0x80
	s_addc_u32 s101, s5, 0
	s_mov_b32 m0, s40
	s_nop 0
	global_load_lds_dwordx4 v164, s[100:101]
	s_waitcnt vmcnt(8)
	s_waitcnt lgkmcnt(0)
	s_setprio 1
	s_barrier
	v_mfma_f32_16x16x32_bf16 v[62:65], v[126:129], v[172:175], v[62:65]
	v_mfma_f32_16x16x32_bf16 v[54:57], v[138:141], v[172:175], v[54:57]
	v_mfma_f32_16x16x32_bf16 v[46:49], v[126:129], v[180:183], v[46:49]
	v_mfma_f32_16x16x32_bf16 v[38:41], v[138:141], v[180:183], v[38:41]
	v_mfma_f32_16x16x32_bf16 v[30:33], v[126:129], v[194:197], v[30:33]
	v_mfma_f32_16x16x32_bf16 v[22:25], v[138:141], v[194:197], v[22:25]
	v_mfma_f32_16x16x32_bf16 v[14:17], v[126:129], v[208:211], v[14:17]
	v_mfma_f32_16x16x32_bf16 v[6:9], v[138:141], v[208:211], v[6:9]
	v_mfma_f32_16x16x32_bf16 v[62:65], v[134:137], v[176:179], v[62:65]
	v_mfma_f32_16x16x32_bf16 v[54:57], v[142:145], v[176:179], v[54:57]
	v_mfma_f32_16x16x32_bf16 v[46:49], v[134:137], v[190:193], v[46:49]
	v_mfma_f32_16x16x32_bf16 v[38:41], v[142:145], v[190:193], v[38:41]
	v_mfma_f32_16x16x32_bf16 v[30:33], v[134:137], v[198:201], v[30:33]
	v_mfma_f32_16x16x32_bf16 v[22:25], v[142:145], v[198:201], v[22:25]
	v_mfma_f32_16x16x32_bf16 v[14:17], v[134:137], v[212:215], v[14:17]
	v_mfma_f32_16x16x32_bf16 v[6:9], v[142:145], v[212:215], v[6:9]
	s_setprio 0
	s_setprio 1
	v_mfma_f32_16x16x32_bf16 v[58:61], v[146:149], v[172:175], v[58:61]
	v_mfma_f32_16x16x32_bf16 v[50:53], v[154:157], v[172:175], v[50:53]
	v_mfma_f32_16x16x32_bf16 v[42:45], v[146:149], v[180:183], v[42:45]
	v_mfma_f32_16x16x32_bf16 v[34:37], v[154:157], v[180:183], v[34:37]
	v_mfma_f32_16x16x32_bf16 v[26:29], v[146:149], v[194:197], v[26:29]
	v_mfma_f32_16x16x32_bf16 v[18:21], v[154:157], v[194:197], v[18:21]
	v_mfma_f32_16x16x32_bf16 v[10:13], v[146:149], v[208:211], v[10:13]
	v_mfma_f32_16x16x32_bf16 v[2:5], v[154:157], v[208:211], v[2:5]
	v_mfma_f32_16x16x32_bf16 v[58:61], v[150:153], v[176:179], v[58:61]
	v_mfma_f32_16x16x32_bf16 v[50:53], v[158:161], v[176:179], v[50:53]
	v_mfma_f32_16x16x32_bf16 v[42:45], v[150:153], v[190:193], v[42:45]
	v_mfma_f32_16x16x32_bf16 v[34:37], v[158:161], v[190:193], v[34:37]
	v_mfma_f32_16x16x32_bf16 v[26:29], v[150:153], v[198:201], v[26:29]
	v_mfma_f32_16x16x32_bf16 v[18:21], v[158:161], v[198:201], v[18:21]
	v_mfma_f32_16x16x32_bf16 v[10:13], v[150:153], v[212:215], v[10:13]
	v_mfma_f32_16x16x32_bf16 v[2:5], v[158:161], v[212:215], v[2:5]
	s_barrier
	s_setprio 0
	s_add_i32 s61, s61, 2
	s_add_u32 s26, s26, 0x100
	s_addc_u32 s27, s27, 0
	s_add_u32 s59, s59, 0x100
	s_addc_u32 s60, s60, 0
	s_cmp_gt_u32 s61, 29
	s_cbranch_scc0 .LBB0_1428
	s_and_b64 vcc, exec, s[10:11]
	s_cbranch_vccz .LBB0_1431
	s_barrier

.LBB0_1594:
	s_add_u32 s0, s28, 0xfff80080
	s_addc_u32 s1, s29, -1
	s_add_i32 s33, 0, 0x10000
	s_cmp_eq_u32 s61, 28
	s_cselect_b32 s5, s19, s1
	s_cselect_b32 s4, s49, s0
	v_add_u32_e32 v140, s33, v143
	s_cselect_b32 s3, s17, s60
	s_cselect_b32 s2, s58, s59
	s_add_i32 s55, 0, 0x14000
	ds_read_b128 v[146:149], v140
	ds_read_b128 v[150:153], v140 offset:1024
	ds_read_b128 v[154:157], v140 offset:2048
	ds_read_b128 v[158:161], v140 offset:3072
	v_add_u32_e32 v140, s55, v143
	ds_read_b128 v[162:165], v140
	ds_read_b128 v[166:169], v140 offset:1024
	ds_read_b128 v[170:173], v140 offset:2048
	ds_read_b128 v[174:177], v140 offset:3072
	s_add_i32 m0, s25, 0xc000
	ds_read_b128 v[178:181], v145
	ds_read_b128 v[182:185], v145 offset:1024
	ds_read_b128 v[186:189], v145 offset:2048
	ds_read_b128 v[190:193], v145 offset:3072
	ds_read_b128 v[194:197], v145 offset:4096
	ds_read_b128 v[198:201], v145 offset:5120
	ds_read_b128 v[208:211], v145 offset:6144
	ds_read_b128 v[212:215], v145 offset:7168
	global_load_lds_dwordx4 v136, s[28:29]
	s_add_i32 m0, s25, 0xe000
	s_nop 0
	global_load_lds_dwordx4 v138, s[28:29]
	s_waitcnt vmcnt(8)
	s_waitcnt lgkmcnt(0)
	s_setprio 1
	s_barrier
	v_mfma_f32_16x16x32_bf16 v[126:129], v[146:149], v[178:181], v[126:129]
	v_mfma_f32_16x16x32_bf16 v[118:121], v[154:157], v[178:181], v[118:121]
	v_mfma_f32_16x16x32_bf16 v[110:113], v[146:149], v[186:189], v[110:113]
	v_mfma_f32_16x16x32_bf16 v[102:105], v[154:157], v[186:189], v[102:105]
	v_mfma_f32_16x16x32_bf16 v[94:97], v[146:149], v[194:197], v[94:97]
	v_mfma_f32_16x16x32_bf16 v[86:89], v[154:157], v[194:197], v[86:89]
	v_mfma_f32_16x16x32_bf16 v[78:81], v[146:149], v[208:211], v[78:81]
	v_mfma_f32_16x16x32_bf16 v[70:73], v[154:157], v[208:211], v[70:73]
	v_mfma_f32_16x16x32_bf16 v[126:129], v[150:153], v[182:185], v[126:129]
	v_mfma_f32_16x16x32_bf16 v[118:121], v[158:161], v[182:185], v[118:121]
	v_mfma_f32_16x16x32_bf16 v[110:113], v[150:153], v[190:193], v[110:113]
	v_mfma_f32_16x16x32_bf16 v[102:105], v[158:161], v[190:193], v[102:105]
	v_mfma_f32_16x16x32_bf16 v[94:97], v[150:153], v[198:201], v[94:97]
	v_mfma_f32_16x16x32_bf16 v[86:89], v[158:161], v[198:201], v[86:89]
	v_mfma_f32_16x16x32_bf16 v[78:81], v[150:153], v[212:215], v[78:81]
	v_mfma_f32_16x16x32_bf16 v[70:73], v[158:161], v[212:215], v[70:73]
	s_setprio 0
	s_setprio 1
	v_mfma_f32_16x16x32_bf16 v[122:125], v[162:165], v[178:181], v[122:125]
	v_mfma_f32_16x16x32_bf16 v[114:117], v[170:173], v[178:181], v[114:117]
	v_mfma_f32_16x16x32_bf16 v[106:109], v[162:165], v[186:189], v[106:109]
	v_mfma_f32_16x16x32_bf16 v[98:101], v[170:173], v[186:189], v[98:101]
	v_mfma_f32_16x16x32_bf16 v[90:93], v[162:165], v[194:197], v[90:93]
	v_mfma_f32_16x16x32_bf16 v[82:85], v[170:173], v[194:197], v[82:85]
	v_mfma_f32_16x16x32_bf16 v[74:77], v[162:165], v[208:211], v[74:77]
	v_mfma_f32_16x16x32_bf16 v[66:69], v[170:173], v[208:211], v[66:69]
	v_mfma_f32_16x16x32_bf16 v[122:125], v[166:169], v[182:185], v[122:125]
	v_mfma_f32_16x16x32_bf16 v[114:117], v[174:177], v[182:185], v[114:117]
	v_mfma_f32_16x16x32_bf16 v[106:109], v[166:169], v[190:193], v[106:109]
	v_mfma_f32_16x16x32_bf16 v[98:101], v[174:177], v[190:193], v[98:101]
	v_mfma_f32_16x16x32_bf16 v[90:93], v[166:169], v[198:201], v[90:93]
	v_mfma_f32_16x16x32_bf16 v[82:85], v[174:177], v[198:201], v[82:85]
	v_mfma_f32_16x16x32_bf16 v[74:77], v[166:169], v[212:215], v[74:77]
	v_mfma_f32_16x16x32_bf16 v[66:69], v[174:177], v[212:215], v[66:69]
	s_barrier
	s_setprio 0
	s_add_i32 s0, s33, s36
	s_mov_b32 m0, s0
	ds_read_b128 v[178:181], v145 offset:16384
	ds_read_b128 v[182:185], v145 offset:17408
	ds_read_b128 v[186:189], v145 offset:18432
	ds_read_b128 v[190:193], v145 offset:19456
	ds_read_b128 v[194:197], v145 offset:20480
	ds_read_b128 v[198:201], v145 offset:21504
	ds_read_b128 v[208:211], v145 offset:22528
	ds_read_b128 v[212:215], v145 offset:23552
	global_load_lds_dwordx4 v202, s[2:3]
	s_add_i32 m0, s0, 0x2000
	s_add_u32 s0, s2, 0x80000
	s_addc_u32 s1, s3, 0
	s_add_i32 s33, s55, s36
	global_load_lds_dwordx4 v130, s[2:3]
	s_mov_b32 m0, s33
	s_nop 0
	global_load_lds_dwordx4 v202, s[0:1]
	s_add_i32 m0, s33, 0x2000
	s_nop 0
	global_load_lds_dwordx4 v130, s[0:1]
	s_mov_b32 m0, s25
	s_nop 0
	global_load_lds_dwordx4 v134, s[4:5]
	s_mov_b32 m0, s27
	s_nop 0
	global_load_lds_dwordx4 v132, s[4:5]
	s_waitcnt vmcnt(8)
	s_waitcnt lgkmcnt(0)
	s_setprio 1
	s_barrier
	v_mfma_f32_16x16x32_bf16 v[62:65], v[146:149], v[178:181], v[62:65]
	v_mfma_f32_16x16x32_bf16 v[54:57], v[154:157], v[178:181], v[54:57]
	v_mfma_f32_16x16x32_bf16 v[46:49], v[146:149], v[186:189], v[46:49]
	v_mfma_f32_16x16x32_bf16 v[38:41], v[154:157], v[186:189], v[38:41]
	v_mfma_f32_16x16x32_bf16 v[30:33], v[146:149], v[194:197], v[30:33]
	v_mfma_f32_16x16x32_bf16 v[22:25], v[154:157], v[194:197], v[22:25]
	v_mfma_f32_16x16x32_bf16 v[14:17], v[146:149], v[208:211], v[14:17]
	v_mfma_f32_16x16x32_bf16 v[6:9], v[154:157], v[208:211], v[6:9]
	v_mfma_f32_16x16x32_bf16 v[62:65], v[150:153], v[182:185], v[62:65]
	v_mfma_f32_16x16x32_bf16 v[54:57], v[158:161], v[182:185], v[54:57]
	v_mfma_f32_16x16x32_bf16 v[46:49], v[150:153], v[190:193], v[46:49]
	v_mfma_f32_16x16x32_bf16 v[38:41], v[158:161], v[190:193], v[38:41]
	v_mfma_f32_16x16x32_bf16 v[30:33], v[150:153], v[198:201], v[30:33]
	v_mfma_f32_16x16x32_bf16 v[22:25], v[158:161], v[198:201], v[22:25]
	v_mfma_f32_16x16x32_bf16 v[14:17], v[150:153], v[212:215], v[14:17]
	v_mfma_f32_16x16x32_bf16 v[6:9], v[158:161], v[212:215], v[6:9]
	s_setprio 0
	s_setprio 1
	v_mfma_f32_16x16x32_bf16 v[58:61], v[162:165], v[178:181], v[58:61]
	v_mfma_f32_16x16x32_bf16 v[50:53], v[170:173], v[178:181], v[50:53]
	v_mfma_f32_16x16x32_bf16 v[42:45], v[162:165], v[186:189], v[42:45]
	v_mfma_f32_16x16x32_bf16 v[34:37], v[170:173], v[186:189], v[34:37]
	v_mfma_f32_16x16x32_bf16 v[26:29], v[162:165], v[194:197], v[26:29]
	v_mfma_f32_16x16x32_bf16 v[18:21], v[170:173], v[194:197], v[18:21]
	v_mfma_f32_16x16x32_bf16 v[10:13], v[162:165], v[208:211], v[10:13]
	v_mfma_f32_16x16x32_bf16 v[2:5], v[170:173], v[208:211], v[2:5]
	v_mfma_f32_16x16x32_bf16 v[58:61], v[166:169], v[182:185], v[58:61]
	v_mfma_f32_16x16x32_bf16 v[50:53], v[174:177], v[182:185], v[50:53]
	v_mfma_f32_16x16x32_bf16 v[42:45], v[166:169], v[190:193], v[42:45]
	v_mfma_f32_16x16x32_bf16 v[34:37], v[174:177], v[190:193], v[34:37]
	v_mfma_f32_16x16x32_bf16 v[26:29], v[166:169], v[198:201], v[26:29]
	v_mfma_f32_16x16x32_bf16 v[18:21], v[174:177], v[198:201], v[18:21]
	v_mfma_f32_16x16x32_bf16 v[10:13], v[166:169], v[212:215], v[10:13]
	v_mfma_f32_16x16x32_bf16 v[2:5], v[174:177], v[212:215], v[2:5]
	s_barrier
	s_setprio 0
	s_add_i32 s33, 0, 0x18000
	s_add_i32 s55, 0, 0x1c000
	v_add_u32_e32 v158, s33, v143
	v_add_u32_e32 v174, s55, v143
	ds_read_b128 v[146:149], v158
	ds_read_b128 v[150:153], v158 offset:1024
	ds_read_b128 v[154:157], v158 offset:2048
	ds_read_b128 v[158:161], v158 offset:3072
	ds_read_b128 v[162:165], v174
	ds_read_b128 v[166:169], v174 offset:1024
	ds_read_b128 v[170:173], v174 offset:2048
	ds_read_b128 v[174:177], v174 offset:3072
	s_add_u32 s0, s4, 0x80000
	s_addc_u32 s1, s5, 0
	s_mov_b32 m0, s37
	ds_read_b128 v[178:181], v145 offset:32768
	ds_read_b128 v[182:185], v145 offset:33792
	ds_read_b128 v[186:189], v145 offset:34816
	ds_read_b128 v[190:193], v145 offset:35840
	ds_read_b128 v[194:197], v145 offset:36864
	ds_read_b128 v[198:201], v145 offset:37888
	ds_read_b128 v[208:211], v145 offset:38912
	ds_read_b128 v[212:215], v145 offset:39936
	global_load_lds_dwordx4 v134, s[0:1]
	s_mov_b32 m0, s38
	s_nop 0
	global_load_lds_dwordx4 v132, s[0:1]
	s_waitcnt vmcnt(8)
	s_waitcnt lgkmcnt(0)
	s_setprio 1
	s_barrier
	v_mfma_f32_16x16x32_bf16 v[126:129], v[146:149], v[178:181], v[126:129]
	v_mfma_f32_16x16x32_bf16 v[118:121], v[154:157], v[178:181], v[118:121]
	v_mfma_f32_16x16x32_bf16 v[110:113], v[146:149], v[186:189], v[110:113]
	v_mfma_f32_16x16x32_bf16 v[102:105], v[154:157], v[186:189], v[102:105]
	v_mfma_f32_16x16x32_bf16 v[94:97], v[146:149], v[194:197], v[94:97]
	v_mfma_f32_16x16x32_bf16 v[86:89], v[154:157], v[194:197], v[86:89]
	v_mfma_f32_16x16x32_bf16 v[78:81], v[146:149], v[208:211], v[78:81]
	v_mfma_f32_16x16x32_bf16 v[70:73], v[154:157], v[208:211], v[70:73]
	v_mfma_f32_16x16x32_bf16 v[126:129], v[150:153], v[182:185], v[126:129]
	v_mfma_f32_16x16x32_bf16 v[118:121], v[158:161], v[182:185], v[118:121]
	v_mfma_f32_16x16x32_bf16 v[110:113], v[150:153], v[190:193], v[110:113]
	v_mfma_f32_16x16x32_bf16 v[102:105], v[158:161], v[190:193], v[102:105]
	v_mfma_f32_16x16x32_bf16 v[94:97], v[150:153], v[198:201], v[94:97]
	v_mfma_f32_16x16x32_bf16 v[86:89], v[158:161], v[198:201], v[86:89]
	v_mfma_f32_16x16x32_bf16 v[78:81], v[150:153], v[212:215], v[78:81]
	v_mfma_f32_16x16x32_bf16 v[70:73], v[158:161], v[212:215], v[70:73]
	s_setprio 0
	s_setprio 1
	v_mfma_f32_16x16x32_bf16 v[122:125], v[162:165], v[178:181], v[122:125]
	v_mfma_f32_16x16x32_bf16 v[114:117], v[170:173], v[178:181], v[114:117]
	v_mfma_f32_16x16x32_bf16 v[106:109], v[162:165], v[186:189], v[106:109]
	v_mfma_f32_16x16x32_bf16 v[98:101], v[170:173], v[186:189], v[98:101]
	v_mfma_f32_16x16x32_bf16 v[90:93], v[162:165], v[194:197], v[90:93]
	v_mfma_f32_16x16x32_bf16 v[82:85], v[170:173], v[194:197], v[82:85]
	v_mfma_f32_16x16x32_bf16 v[74:77], v[162:165], v[208:211], v[74:77]
	v_mfma_f32_16x16x32_bf16 v[66:69], v[170:173], v[208:211], v[66:69]
	v_mfma_f32_16x16x32_bf16 v[122:125], v[166:169], v[182:185], v[122:125]
	v_mfma_f32_16x16x32_bf16 v[114:117], v[174:177], v[182:185], v[114:117]
	v_mfma_f32_16x16x32_bf16 v[106:109], v[166:169], v[190:193], v[106:109]
	v_mfma_f32_16x16x32_bf16 v[98:101], v[174:177], v[190:193], v[98:101]
	v_mfma_f32_16x16x32_bf16 v[90:93], v[166:169], v[198:201], v[90:93]
	v_mfma_f32_16x16x32_bf16 v[82:85], v[174:177], v[198:201], v[82:85]
	v_mfma_f32_16x16x32_bf16 v[74:77], v[166:169], v[212:215], v[74:77]
	v_mfma_f32_16x16x32_bf16 v[66:69], v[174:177], v[212:215], v[66:69]
	s_barrier
	s_setprio 0
	s_add_i32 s0, s33, s36
	s_add_u32 s100, s2, 0x80
	s_addc_u32 s101, s3, 0
	s_mov_b32 m0, s0
	ds_read_b128 v[178:181], v145 offset:49152
	ds_read_b128 v[182:185], v145 offset:50176
	ds_read_b128 v[186:189], v145 offset:51200
	ds_read_b128 v[190:193], v145 offset:52224
	ds_read_b128 v[194:197], v145 offset:53248
	ds_read_b128 v[198:201], v145 offset:54272
	ds_read_b128 v[208:211], v145 offset:55296
	ds_read_b128 v[212:215], v145 offset:56320
	global_load_lds_dwordx4 v202, s[100:101]
	s_add_i32 m0, s0, 0x2000
	s_add_u32 s100, s2, 0x80
	s_addc_u32 s101, s3, 0
	s_add_u32 s0, s2, 0x80080
	s_addc_u32 s1, s3, 0
	s_add_i32 s2, s55, s36
	global_load_lds_dwordx4 v130, s[100:101]
	s_mov_b32 m0, s2
	s_nop 0
	global_load_lds_dwordx4 v202, s[0:1]
	s_add_i32 m0, s2, 0x2000
	s_nop 0
	global_load_lds_dwordx4 v130, s[0:1]
	s_add_u32 s100, s4, 0x80
	s_addc_u32 s101, s5, 0
	s_mov_b32 m0, s39
	s_nop 0
	global_load_lds_dwordx4 v134, s[100:101]
	s_add_u32 s100, s4, 0x80
	s_addc_u32 s101, s5, 0
	s_mov_b32 m0, s40
	s_nop 0
	global_load_lds_dwordx4 v132, s[100:101]
	s_waitcnt vmcnt(8)
	s_waitcnt lgkmcnt(0)
	s_setprio 1
	s_barrier
	v_mfma_f32_16x16x32_bf16 v[62:65], v[146:149], v[178:181], v[62:65]
	v_mfma_f32_16x16x32_bf16 v[54:57], v[154:157], v[178:181], v[54:57]
	v_mfma_f32_16x16x32_bf16 v[46:49], v[146:149], v[186:189], v[46:49]
	v_mfma_f32_16x16x32_bf16 v[38:41], v[154:157], v[186:189], v[38:41]
	v_mfma_f32_16x16x32_bf16 v[30:33], v[146:149], v[194:197], v[30:33]
	v_mfma_f32_16x16x32_bf16 v[22:25], v[154:157], v[194:197], v[22:25]
	v_mfma_f32_16x16x32_bf16 v[14:17], v[146:149], v[208:211], v[14:17]
	v_mfma_f32_16x16x32_bf16 v[6:9], v[154:157], v[208:211], v[6:9]
	v_mfma_f32_16x16x32_bf16 v[62:65], v[150:153], v[182:185], v[62:65]
	v_mfma_f32_16x16x32_bf16 v[54:57], v[158:161], v[182:185], v[54:57]
	v_mfma_f32_16x16x32_bf16 v[46:49], v[150:153], v[190:193], v[46:49]
	v_mfma_f32_16x16x32_bf16 v[38:41], v[158:161], v[190:193], v[38:41]
	v_mfma_f32_16x16x32_bf16 v[30:33], v[150:153], v[198:201], v[30:33]
	v_mfma_f32_16x16x32_bf16 v[22:25], v[158:161], v[198:201], v[22:25]
	v_mfma_f32_16x16x32_bf16 v[14:17], v[150:153], v[212:215], v[14:17]
	v_mfma_f32_16x16x32_bf16 v[6:9], v[158:161], v[212:215], v[6:9]
	s_setprio 0
	s_setprio 1
	v_mfma_f32_16x16x32_bf16 v[58:61], v[162:165], v[178:181], v[58:61]
	v_mfma_f32_16x16x32_bf16 v[50:53], v[170:173], v[178:181], v[50:53]
	v_mfma_f32_16x16x32_bf16 v[42:45], v[162:165], v[186:189], v[42:45]
	v_mfma_f32_16x16x32_bf16 v[34:37], v[170:173], v[186:189], v[34:37]
	v_mfma_f32_16x16x32_bf16 v[26:29], v[162:165], v[194:197], v[26:29]
	v_mfma_f32_16x16x32_bf16 v[18:21], v[170:173], v[194:197], v[18:21]
	v_mfma_f32_16x16x32_bf16 v[10:13], v[162:165], v[208:211], v[10:13]
	v_mfma_f32_16x16x32_bf16 v[2:5], v[170:173], v[208:211], v[2:5]
	v_mfma_f32_16x16x32_bf16 v[58:61], v[166:169], v[182:185], v[58:61]
	v_mfma_f32_16x16x32_bf16 v[50:53], v[174:177], v[182:185], v[50:53]
	v_mfma_f32_16x16x32_bf16 v[42:45], v[166:169], v[190:193], v[42:45]
	v_mfma_f32_16x16x32_bf16 v[34:37], v[174:177], v[190:193], v[34:37]
	v_mfma_f32_16x16x32_bf16 v[26:29], v[166:169], v[198:201], v[26:29]
	v_mfma_f32_16x16x32_bf16 v[18:21], v[174:177], v[198:201], v[18:21]
	v_mfma_f32_16x16x32_bf16 v[10:13], v[166:169], v[212:215], v[10:13]
	v_mfma_f32_16x16x32_bf16 v[2:5], v[174:177], v[212:215], v[2:5]
	s_barrier
	s_setprio 0
	s_add_i32 s61, s61, 2
	s_add_u32 s28, s28, 0x100
	s_addc_u32 s29, s29, 0
	s_add_u32 s59, s59, 0x100
	s_addc_u32 s60, s60, 0
	s_cmp_gt_u32 s61, 29
	s_cbranch_scc0 .LBB0_1594
	s_and_b64 vcc, exec, s[14:15]
	s_cbranch_vccz .LBB0_1597
	s_barrier

.LBB0_1718:
	s_add_u32 s18, s4, 0x100
	s_addc_u32 s19, s5, 0
	s_add_i32 s0, 0, 0x10000
	s_cmpk_eq_i32 s59, 0x54
	s_cselect_b32 s23, s9, s19
	s_cselect_b32 s22, s8, s18
	s_cselect_b32 s21, s17, s58
	s_cselect_b32 s20, s16, s49
	s_add_i32 s33, 0, 0x14000
	v_add_u32_e32 v98, s0, v205
	v_add_u32_e32 v134, s33, v205
	ds_read_b128 v[78:81], v98
	ds_read_b128 v[82:85], v98 offset:1024
	ds_read_b128 v[94:97], v98 offset:2048
	ds_read_b128 v[98:101], v98 offset:3072
	ds_read_b128 v[106:109], v134
	ds_read_b128 v[110:113], v134 offset:1024
	ds_read_b128 v[126:129], v134 offset:2048
	ds_read_b128 v[134:137], v134 offset:3072
	s_add_i32 m0, s27, 0xc000
	ds_read_b128 v[146:149], v239
	ds_read_b128 v[158:161], v239 offset:1024
	ds_read_b128 v[166:169], v239 offset:2048
	ds_read_b128 v[174:177], v239 offset:3072
	ds_read_b128 v[178:181], v239 offset:4096
	ds_read_b128 v[182:185], v239 offset:5120
	ds_read_b128 v[186:189], v239 offset:6144
	ds_read_b128 v[190:193], v239 offset:7168
	global_load_lds_dwordx4 v214, s[4:5]
	s_add_i32 m0, s27, 0xe000
	s_nop 0
	global_load_lds_dwordx4 v216, s[4:5]
	s_waitcnt vmcnt(8)
	s_waitcnt lgkmcnt(0)
	s_setprio 1
	s_barrier
	v_mfma_f32_16x16x32_bf16 v[170:173], v[78:81], v[146:149], v[170:173]
	v_mfma_f32_16x16x32_bf16 v[162:165], v[94:97], v[146:149], v[162:165]
	v_mfma_f32_16x16x32_bf16 v[142:145], v[78:81], v[166:169], v[142:145]
	v_mfma_f32_16x16x32_bf16 v[138:141], v[94:97], v[166:169], v[138:141]
	v_mfma_f32_16x16x32_bf16 v[118:121], v[78:81], v[178:181], v[118:121]
	v_mfma_f32_16x16x32_bf16 v[114:117], v[94:97], v[178:181], v[114:117]
	v_mfma_f32_16x16x32_bf16 v[86:89], v[78:81], v[186:189], v[86:89]
	v_mfma_f32_16x16x32_bf16 v[74:77], v[94:97], v[186:189], v[74:77]
	v_mfma_f32_16x16x32_bf16 v[170:173], v[82:85], v[158:161], v[170:173]
	v_mfma_f32_16x16x32_bf16 v[162:165], v[98:101], v[158:161], v[162:165]
	v_mfma_f32_16x16x32_bf16 v[142:145], v[82:85], v[174:177], v[142:145]
	v_mfma_f32_16x16x32_bf16 v[138:141], v[98:101], v[174:177], v[138:141]
	v_mfma_f32_16x16x32_bf16 v[118:121], v[82:85], v[182:185], v[118:121]
	v_mfma_f32_16x16x32_bf16 v[114:117], v[98:101], v[182:185], v[114:117]
	v_mfma_f32_16x16x32_bf16 v[86:89], v[82:85], v[190:193], v[86:89]
	v_mfma_f32_16x16x32_bf16 v[74:77], v[98:101], v[190:193], v[74:77]
	s_setprio 0
	s_setprio 1
	v_mfma_f32_16x16x32_bf16 v[154:157], v[106:109], v[146:149], v[154:157]
	v_mfma_f32_16x16x32_bf16 v[130:133], v[106:109], v[166:169], v[130:133]
	v_mfma_f32_16x16x32_bf16 v[122:125], v[126:129], v[166:169], v[122:125]
	v_mfma_f32_16x16x32_bf16 v[102:105], v[106:109], v[178:181], v[102:105]
	v_mfma_f32_16x16x32_bf16 v[90:93], v[126:129], v[178:181], v[90:93]
	v_mfma_f32_16x16x32_bf16 v[70:73], v[106:109], v[186:189], v[70:73]
	v_mfma_f32_16x16x32_bf16 v[66:69], v[126:129], v[186:189], v[66:69]
	v_mfma_f32_16x16x32_bf16 v[154:157], v[110:113], v[158:161], v[154:157]
	v_mfma_f32_16x16x32_bf16 v[146:149], v[126:129], v[146:149], v[150:153]
	v_mfma_f32_16x16x32_bf16 v[130:133], v[110:113], v[174:177], v[130:133]
	v_mfma_f32_16x16x32_bf16 v[122:125], v[134:137], v[174:177], v[122:125]
	v_mfma_f32_16x16x32_bf16 v[102:105], v[110:113], v[182:185], v[102:105]
	v_mfma_f32_16x16x32_bf16 v[90:93], v[134:137], v[182:185], v[90:93]
	v_mfma_f32_16x16x32_bf16 v[70:73], v[110:113], v[190:193], v[70:73]
	v_mfma_f32_16x16x32_bf16 v[66:69], v[134:137], v[190:193], v[66:69]
	v_mfma_f32_16x16x32_bf16 v[146:149], v[134:137], v[158:161], v[146:149]
	s_barrier
	s_setprio 0
	s_add_i32 s0, s0, s26
	s_mov_b32 m0, s0
	ds_read_b128 v[150:153], v239 offset:16384
	ds_read_b128 v[158:161], v239 offset:17408
	ds_read_b128 v[166:169], v239 offset:18432
	ds_read_b128 v[174:177], v239 offset:19456
	ds_read_b128 v[178:181], v239 offset:20480
	ds_read_b128 v[182:185], v239 offset:21504
	ds_read_b128 v[186:189], v239 offset:22528
	ds_read_b128 v[190:193], v239 offset:23552
	global_load_lds_dwordx4 v202, s[20:21]
	s_add_i32 m0, s0, 0x2000
	s_add_u32 s0, s20, 0x160000
	s_addc_u32 s1, s21, 0
	s_add_i32 s4, s33, s26
	global_load_lds_dwordx4 v208, s[20:21]
	s_mov_b32 m0, s4
	s_nop 0
	global_load_lds_dwordx4 v202, s[0:1]
	s_add_i32 m0, s4, 0x2000
	s_nop 0
	global_load_lds_dwordx4 v208, s[0:1]
	s_mov_b32 m0, s27
	s_nop 0
	global_load_lds_dwordx4 v212, s[22:23]
	s_mov_b32 m0, s28
	s_nop 0
	global_load_lds_dwordx4 v210, s[22:23]
	s_waitcnt vmcnt(8)
	s_waitcnt lgkmcnt(0)
	s_setprio 1
	s_barrier
	v_mfma_f32_16x16x32_bf16 v[62:65], v[78:81], v[150:153], v[62:65]
	v_mfma_f32_16x16x32_bf16 v[58:61], v[94:97], v[150:153], v[58:61]
	v_mfma_f32_16x16x32_bf16 v[46:49], v[78:81], v[166:169], v[46:49]
	v_mfma_f32_16x16x32_bf16 v[42:45], v[94:97], v[166:169], v[42:45]
	v_mfma_f32_16x16x32_bf16 v[30:33], v[78:81], v[178:181], v[30:33]
	v_mfma_f32_16x16x32_bf16 v[26:29], v[94:97], v[178:181], v[26:29]
	v_mfma_f32_16x16x32_bf16 v[14:17], v[78:81], v[186:189], v[14:17]
	v_mfma_f32_16x16x32_bf16 v[10:13], v[94:97], v[186:189], v[10:13]
	v_mfma_f32_16x16x32_bf16 v[62:65], v[82:85], v[158:161], v[62:65]
	v_mfma_f32_16x16x32_bf16 v[58:61], v[98:101], v[158:161], v[58:61]
	v_mfma_f32_16x16x32_bf16 v[46:49], v[82:85], v[174:177], v[46:49]
	v_mfma_f32_16x16x32_bf16 v[42:45], v[98:101], v[174:177], v[42:45]
	v_mfma_f32_16x16x32_bf16 v[30:33], v[82:85], v[182:185], v[30:33]
	v_mfma_f32_16x16x32_bf16 v[26:29], v[98:101], v[182:185], v[26:29]
	v_mfma_f32_16x16x32_bf16 v[14:17], v[82:85], v[190:193], v[14:17]
	v_mfma_f32_16x16x32_bf16 v[10:13], v[98:101], v[190:193], v[10:13]
	s_setprio 0
	s_setprio 1
	v_mfma_f32_16x16x32_bf16 v[54:57], v[106:109], v[150:153], v[54:57]
	v_mfma_f32_16x16x32_bf16 v[50:53], v[126:129], v[150:153], v[50:53]
	v_mfma_f32_16x16x32_bf16 v[38:41], v[106:109], v[166:169], v[38:41]
	v_mfma_f32_16x16x32_bf16 v[34:37], v[126:129], v[166:169], v[34:37]
	v_mfma_f32_16x16x32_bf16 v[22:25], v[106:109], v[178:181], v[22:25]
	v_mfma_f32_16x16x32_bf16 v[18:21], v[126:129], v[178:181], v[18:21]
	v_mfma_f32_16x16x32_bf16 v[6:9], v[106:109], v[186:189], v[6:9]
	v_mfma_f32_16x16x32_bf16 v[2:5], v[126:129], v[186:189], v[2:5]
	v_mfma_f32_16x16x32_bf16 v[54:57], v[110:113], v[158:161], v[54:57]
	v_mfma_f32_16x16x32_bf16 v[50:53], v[134:137], v[158:161], v[50:53]
	v_mfma_f32_16x16x32_bf16 v[38:41], v[110:113], v[174:177], v[38:41]
	v_mfma_f32_16x16x32_bf16 v[34:37], v[134:137], v[174:177], v[34:37]
	v_mfma_f32_16x16x32_bf16 v[22:25], v[110:113], v[182:185], v[22:25]
	v_mfma_f32_16x16x32_bf16 v[18:21], v[134:137], v[182:185], v[18:21]
	v_mfma_f32_16x16x32_bf16 v[6:9], v[110:113], v[190:193], v[6:9]
	v_mfma_f32_16x16x32_bf16 v[2:5], v[134:137], v[190:193], v[2:5]
	s_barrier
	s_setprio 0
	s_add_i32 s4, 0, 0x18000
	s_add_i32 s5, 0, 0x1c000
	v_add_u32_e32 v98, s4, v205
	v_add_u32_e32 v134, s5, v205
	ds_read_b128 v[78:81], v98
	ds_read_b128 v[82:85], v98 offset:1024
	ds_read_b128 v[94:97], v98 offset:2048
	ds_read_b128 v[98:101], v98 offset:3072
	ds_read_b128 v[106:109], v134
	ds_read_b128 v[110:113], v134 offset:1024
	ds_read_b128 v[126:129], v134 offset:2048
	ds_read_b128 v[134:137], v134 offset:3072
	s_add_u32 s0, s22, 0x160000
	s_addc_u32 s1, s23, 0
	s_mov_b32 m0, s29
	ds_read_b128 v[150:153], v239 offset:32768
	ds_read_b128 v[158:161], v239 offset:33792
	ds_read_b128 v[166:169], v239 offset:34816
	ds_read_b128 v[174:177], v239 offset:35840
	ds_read_b128 v[178:181], v239 offset:36864
	ds_read_b128 v[182:185], v239 offset:37888
	ds_read_b128 v[186:189], v239 offset:38912
	ds_read_b128 v[190:193], v239 offset:39936
	global_load_lds_dwordx4 v212, s[0:1]
	s_mov_b32 m0, s30
	s_nop 0
	global_load_lds_dwordx4 v210, s[0:1]
	s_waitcnt vmcnt(8)
	s_waitcnt lgkmcnt(0)
	s_setprio 1
	s_barrier
	v_mfma_f32_16x16x32_bf16 v[170:173], v[78:81], v[150:153], v[170:173]
	v_mfma_f32_16x16x32_bf16 v[162:165], v[94:97], v[150:153], v[162:165]
	v_mfma_f32_16x16x32_bf16 v[142:145], v[78:81], v[166:169], v[142:145]
	v_mfma_f32_16x16x32_bf16 v[138:141], v[94:97], v[166:169], v[138:141]
	v_mfma_f32_16x16x32_bf16 v[118:121], v[78:81], v[178:181], v[118:121]
	v_mfma_f32_16x16x32_bf16 v[114:117], v[94:97], v[178:181], v[114:117]
	v_mfma_f32_16x16x32_bf16 v[86:89], v[78:81], v[186:189], v[86:89]
	v_mfma_f32_16x16x32_bf16 v[74:77], v[94:97], v[186:189], v[74:77]
	v_mfma_f32_16x16x32_bf16 v[170:173], v[82:85], v[158:161], v[170:173]
	v_mfma_f32_16x16x32_bf16 v[162:165], v[98:101], v[158:161], v[162:165]
	v_mfma_f32_16x16x32_bf16 v[142:145], v[82:85], v[174:177], v[142:145]
	v_mfma_f32_16x16x32_bf16 v[138:141], v[98:101], v[174:177], v[138:141]
	v_mfma_f32_16x16x32_bf16 v[118:121], v[82:85], v[182:185], v[118:121]
	v_mfma_f32_16x16x32_bf16 v[114:117], v[98:101], v[182:185], v[114:117]
	v_mfma_f32_16x16x32_bf16 v[86:89], v[82:85], v[190:193], v[86:89]
	v_mfma_f32_16x16x32_bf16 v[74:77], v[98:101], v[190:193], v[74:77]
	s_setprio 0
	s_setprio 1
	v_mfma_f32_16x16x32_bf16 v[154:157], v[106:109], v[150:153], v[154:157]
	v_mfma_f32_16x16x32_bf16 v[146:149], v[126:129], v[150:153], v[146:149]
	v_mfma_f32_16x16x32_bf16 v[130:133], v[106:109], v[166:169], v[130:133]
	v_mfma_f32_16x16x32_bf16 v[122:125], v[126:129], v[166:169], v[122:125]
	v_mfma_f32_16x16x32_bf16 v[102:105], v[106:109], v[178:181], v[102:105]
	v_mfma_f32_16x16x32_bf16 v[90:93], v[126:129], v[178:181], v[90:93]
	v_mfma_f32_16x16x32_bf16 v[70:73], v[106:109], v[186:189], v[70:73]
	v_mfma_f32_16x16x32_bf16 v[66:69], v[126:129], v[186:189], v[66:69]
	v_mfma_f32_16x16x32_bf16 v[154:157], v[110:113], v[158:161], v[154:157]
	v_mfma_f32_16x16x32_bf16 v[150:153], v[134:137], v[158:161], v[146:149]
	v_mfma_f32_16x16x32_bf16 v[130:133], v[110:113], v[174:177], v[130:133]
	v_mfma_f32_16x16x32_bf16 v[122:125], v[134:137], v[174:177], v[122:125]
	v_mfma_f32_16x16x32_bf16 v[102:105], v[110:113], v[182:185], v[102:105]
	v_mfma_f32_16x16x32_bf16 v[90:93], v[134:137], v[182:185], v[90:93]
	v_mfma_f32_16x16x32_bf16 v[70:73], v[110:113], v[190:193], v[70:73]
	v_mfma_f32_16x16x32_bf16 v[66:69], v[134:137], v[190:193], v[66:69]
	s_barrier
	s_setprio 0
	s_add_i32 s0, s4, s26
	s_add_u32 s100, s20, 0x80
	s_addc_u32 s101, s21, 0
	s_mov_b32 m0, s0
	ds_read_b128 v[146:149], v239 offset:49152
	ds_read_b128 v[158:161], v239 offset:50176
	ds_read_b128 v[166:169], v239 offset:51200
	ds_read_b128 v[174:177], v239 offset:52224
	ds_read_b128 v[178:181], v239 offset:53248
	ds_read_b128 v[182:185], v239 offset:54272
	ds_read_b128 v[186:189], v239 offset:55296
	ds_read_b128 v[190:193], v239 offset:56320
	global_load_lds_dwordx4 v202, s[100:101]
	s_add_i32 m0, s0, 0x2000
	s_add_u32 s100, s20, 0x80
	s_addc_u32 s101, s21, 0
	s_add_u32 s0, s20, 0x160080
	s_addc_u32 s1, s21, 0
	s_add_i32 s4, s5, s26
	global_load_lds_dwordx4 v208, s[100:101]
	s_mov_b32 m0, s4
	s_nop 0
	global_load_lds_dwordx4 v202, s[0:1]
	s_add_i32 m0, s4, 0x2000
	s_nop 0
	global_load_lds_dwordx4 v208, s[0:1]
	s_add_u32 s100, s22, 0x80
	s_addc_u32 s101, s23, 0
	s_mov_b32 m0, s35
	s_nop 0
	global_load_lds_dwordx4 v212, s[100:101]
	s_add_u32 s100, s22, 0x80
	s_addc_u32 s101, s23, 0
	s_mov_b32 m0, s36
	s_nop 0
	global_load_lds_dwordx4 v210, s[100:101]
	s_waitcnt vmcnt(8)
	s_waitcnt lgkmcnt(0)
	s_setprio 1
	s_barrier
	v_mfma_f32_16x16x32_bf16 v[62:65], v[78:81], v[146:149], v[62:65]
	v_mfma_f32_16x16x32_bf16 v[58:61], v[94:97], v[146:149], v[58:61]
	v_mfma_f32_16x16x32_bf16 v[46:49], v[78:81], v[166:169], v[46:49]
	v_mfma_f32_16x16x32_bf16 v[42:45], v[94:97], v[166:169], v[42:45]
	v_mfma_f32_16x16x32_bf16 v[30:33], v[78:81], v[178:181], v[30:33]
	v_mfma_f32_16x16x32_bf16 v[26:29], v[94:97], v[178:181], v[26:29]
	v_mfma_f32_16x16x32_bf16 v[14:17], v[78:81], v[186:189], v[14:17]
	v_mfma_f32_16x16x32_bf16 v[10:13], v[94:97], v[186:189], v[10:13]
	v_mfma_f32_16x16x32_bf16 v[62:65], v[82:85], v[158:161], v[62:65]
	v_mfma_f32_16x16x32_bf16 v[58:61], v[98:101], v[158:161], v[58:61]
	v_mfma_f32_16x16x32_bf16 v[46:49], v[82:85], v[174:177], v[46:49]
	v_mfma_f32_16x16x32_bf16 v[42:45], v[98:101], v[174:177], v[42:45]
	v_mfma_f32_16x16x32_bf16 v[30:33], v[82:85], v[182:185], v[30:33]
	v_mfma_f32_16x16x32_bf16 v[26:29], v[98:101], v[182:185], v[26:29]
	v_mfma_f32_16x16x32_bf16 v[14:17], v[82:85], v[190:193], v[14:17]
	v_mfma_f32_16x16x32_bf16 v[10:13], v[98:101], v[190:193], v[10:13]
	s_setprio 0
	s_setprio 1
	v_mfma_f32_16x16x32_bf16 v[54:57], v[106:109], v[146:149], v[54:57]
	v_mfma_f32_16x16x32_bf16 v[50:53], v[126:129], v[146:149], v[50:53]
	v_mfma_f32_16x16x32_bf16 v[38:41], v[106:109], v[166:169], v[38:41]
	v_mfma_f32_16x16x32_bf16 v[34:37], v[126:129], v[166:169], v[34:37]
	v_mfma_f32_16x16x32_bf16 v[22:25], v[106:109], v[178:181], v[22:25]
	v_mfma_f32_16x16x32_bf16 v[18:21], v[126:129], v[178:181], v[18:21]
	v_mfma_f32_16x16x32_bf16 v[6:9], v[106:109], v[186:189], v[6:9]
	v_mfma_f32_16x16x32_bf16 v[2:5], v[126:129], v[186:189], v[2:5]
	v_mfma_f32_16x16x32_bf16 v[54:57], v[110:113], v[158:161], v[54:57]
	v_mfma_f32_16x16x32_bf16 v[50:53], v[134:137], v[158:161], v[50:53]
	v_mfma_f32_16x16x32_bf16 v[38:41], v[110:113], v[174:177], v[38:41]
	v_mfma_f32_16x16x32_bf16 v[34:37], v[134:137], v[174:177], v[34:37]
	v_mfma_f32_16x16x32_bf16 v[22:25], v[110:113], v[182:185], v[22:25]
	v_mfma_f32_16x16x32_bf16 v[18:21], v[134:137], v[182:185], v[18:21]
	v_mfma_f32_16x16x32_bf16 v[6:9], v[110:113], v[190:193], v[6:9]
	v_mfma_f32_16x16x32_bf16 v[2:5], v[134:137], v[190:193], v[2:5]
	s_barrier
	s_setprio 0
	s_add_i32 s59, s59, 2
	s_add_u32 s49, s49, 0x100
	s_addc_u32 s58, s58, 0
	s_cmpk_gt_u32 s59, 0x55
	s_mov_b64 s[4:5], s[18:19]
	s_cbranch_scc0 .LBB0_1718
	s_and_b64 vcc, exec, s[14:15]
	s_cbranch_vccz .LBB0_1721
	s_barrier

.LBB0_1739:
	s_add_u32 s16, s14, 0x100
	s_addc_u32 s17, s15, 0
	s_add_i32 s0, 0, 0x10000
	s_cmp_eq_u32 s49, 4
	s_cselect_b32 s21, s9, s17
	s_cselect_b32 s20, s8, s16
	s_cselect_b32 s19, s11, s41
	s_cselect_b32 s18, s10, s40
	s_add_i32 s33, 0, 0x14000
	v_add_u32_e32 v152, s0, v136
	v_add_u32_e32 v168, s33, v136
	ds_read_b128 v[140:143], v152
	ds_read_b128 v[144:147], v152 offset:1024
	ds_read_b128 v[148:151], v152 offset:2048
	ds_read_b128 v[152:155], v152 offset:3072
	ds_read_b128 v[156:159], v168
	ds_read_b128 v[160:163], v168 offset:1024
	ds_read_b128 v[164:167], v168 offset:2048
	ds_read_b128 v[168:171], v168 offset:3072
	s_add_i32 m0, s23, 0xc000
	ds_read_b128 v[172:175], v139
	ds_read_b128 v[176:179], v139 offset:1024
	ds_read_b128 v[180:183], v139 offset:2048
	ds_read_b128 v[184:187], v139 offset:3072
	ds_read_b128 v[188:191], v139 offset:4096
	ds_read_b128 v[192:195], v139 offset:5120
	ds_read_b128 v[196:199], v139 offset:6144
	ds_read_b128 v[208:211], v139 offset:7168
	global_load_lds_dwordx4 v132, s[14:15]
	s_add_i32 m0, s23, 0xe000
	s_nop 0
	global_load_lds_dwordx4 v134, s[14:15]
	s_waitcnt vmcnt(8)
	s_waitcnt lgkmcnt(0)
	s_setprio 1
	s_barrier
	v_mfma_f32_16x16x32_bf16 v[126:129], v[140:143], v[172:175], v[126:129]
	v_mfma_f32_16x16x32_bf16 v[122:125], v[148:151], v[172:175], v[122:125]
	v_mfma_f32_16x16x32_bf16 v[118:121], v[140:143], v[180:183], v[118:121]
	v_mfma_f32_16x16x32_bf16 v[114:117], v[148:151], v[180:183], v[114:117]
	v_mfma_f32_16x16x32_bf16 v[106:109], v[140:143], v[188:191], v[106:109]
	v_mfma_f32_16x16x32_bf16 v[98:101], v[148:151], v[188:191], v[98:101]
	v_mfma_f32_16x16x32_bf16 v[90:93], v[140:143], v[196:199], v[90:93]
	v_mfma_f32_16x16x32_bf16 v[82:85], v[148:151], v[196:199], v[82:85]
	v_mfma_f32_16x16x32_bf16 v[126:129], v[144:147], v[176:179], v[126:129]
	v_mfma_f32_16x16x32_bf16 v[122:125], v[152:155], v[176:179], v[122:125]
	v_mfma_f32_16x16x32_bf16 v[118:121], v[144:147], v[184:187], v[118:121]
	v_mfma_f32_16x16x32_bf16 v[114:117], v[152:155], v[184:187], v[114:117]
	v_mfma_f32_16x16x32_bf16 v[106:109], v[144:147], v[192:195], v[106:109]
	v_mfma_f32_16x16x32_bf16 v[98:101], v[152:155], v[192:195], v[98:101]
	v_mfma_f32_16x16x32_bf16 v[90:93], v[144:147], v[208:211], v[90:93]
	v_mfma_f32_16x16x32_bf16 v[82:85], v[152:155], v[208:211], v[82:85]
	s_setprio 0
	s_setprio 1
	v_mfma_f32_16x16x32_bf16 v[110:113], v[156:159], v[172:175], v[110:113]
	v_mfma_f32_16x16x32_bf16 v[102:105], v[164:167], v[172:175], v[102:105]
	v_mfma_f32_16x16x32_bf16 v[94:97], v[156:159], v[180:183], v[94:97]
	v_mfma_f32_16x16x32_bf16 v[86:89], v[164:167], v[180:183], v[86:89]
	v_mfma_f32_16x16x32_bf16 v[78:81], v[156:159], v[188:191], v[78:81]
	v_mfma_f32_16x16x32_bf16 v[74:77], v[164:167], v[188:191], v[74:77]
	v_mfma_f32_16x16x32_bf16 v[70:73], v[156:159], v[196:199], v[70:73]
	v_mfma_f32_16x16x32_bf16 v[66:69], v[164:167], v[196:199], v[66:69]
	v_mfma_f32_16x16x32_bf16 v[110:113], v[160:163], v[176:179], v[110:113]
	v_mfma_f32_16x16x32_bf16 v[102:105], v[168:171], v[176:179], v[102:105]
	v_mfma_f32_16x16x32_bf16 v[94:97], v[160:163], v[184:187], v[94:97]
	v_mfma_f32_16x16x32_bf16 v[86:89], v[168:171], v[184:187], v[86:89]
	v_mfma_f32_16x16x32_bf16 v[78:81], v[160:163], v[192:195], v[78:81]
	v_mfma_f32_16x16x32_bf16 v[74:77], v[168:171], v[192:195], v[74:77]
	v_mfma_f32_16x16x32_bf16 v[70:73], v[160:163], v[208:211], v[70:73]
	v_mfma_f32_16x16x32_bf16 v[66:69], v[168:171], v[208:211], v[66:69]
	s_barrier
	s_setprio 0
	s_add_i32 s0, s0, s22
	s_mov_b32 m0, s0
	ds_read_b128 v[172:175], v139 offset:16384
	ds_read_b128 v[176:179], v139 offset:17408
	ds_read_b128 v[180:183], v139 offset:18432
	ds_read_b128 v[184:187], v139 offset:19456
	ds_read_b128 v[188:191], v139 offset:20480
	ds_read_b128 v[192:195], v139 offset:21504
	ds_read_b128 v[196:199], v139 offset:22528
	ds_read_b128 v[208:211], v139 offset:23552
	global_load_lds_dwordx4 v202, s[18:19]
	s_add_i32 m0, s0, 0x2000
	s_add_u32 s0, s18, 0x160000
	s_addc_u32 s1, s19, 0
	s_add_i32 s14, s33, s22
	global_load_lds_dwordx4 v130, s[18:19]
	s_mov_b32 m0, s14
	s_nop 0
	global_load_lds_dwordx4 v202, s[0:1]
	s_add_i32 m0, s14, 0x2000
	s_nop 0
	global_load_lds_dwordx4 v130, s[0:1]
	s_mov_b32 m0, s23
	s_nop 0
	global_load_lds_dwordx4 v202, s[20:21]
	s_mov_b32 m0, s26
	s_nop 0
	global_load_lds_dwordx4 v130, s[20:21]
	s_waitcnt vmcnt(8)
	s_waitcnt lgkmcnt(0)
	s_setprio 1
	s_barrier
	v_mfma_f32_16x16x32_bf16 v[62:65], v[140:143], v[172:175], v[62:65]
	v_mfma_f32_16x16x32_bf16 v[58:61], v[148:151], v[172:175], v[58:61]
	v_mfma_f32_16x16x32_bf16 v[54:57], v[140:143], v[180:183], v[54:57]
	v_mfma_f32_16x16x32_bf16 v[50:53], v[148:151], v[180:183], v[50:53]
	v_mfma_f32_16x16x32_bf16 v[38:41], v[140:143], v[188:191], v[38:41]
	v_mfma_f32_16x16x32_bf16 v[34:37], v[148:151], v[188:191], v[34:37]
	v_mfma_f32_16x16x32_bf16 v[22:25], v[140:143], v[196:199], v[22:25]
	v_mfma_f32_16x16x32_bf16 v[18:21], v[148:151], v[196:199], v[18:21]
	v_mfma_f32_16x16x32_bf16 v[62:65], v[144:147], v[176:179], v[62:65]
	v_mfma_f32_16x16x32_bf16 v[58:61], v[152:155], v[176:179], v[58:61]
	v_mfma_f32_16x16x32_bf16 v[54:57], v[144:147], v[184:187], v[54:57]
	v_mfma_f32_16x16x32_bf16 v[50:53], v[152:155], v[184:187], v[50:53]
	v_mfma_f32_16x16x32_bf16 v[38:41], v[144:147], v[192:195], v[38:41]
	v_mfma_f32_16x16x32_bf16 v[34:37], v[152:155], v[192:195], v[34:37]
	v_mfma_f32_16x16x32_bf16 v[22:25], v[144:147], v[208:211], v[22:25]
	v_mfma_f32_16x16x32_bf16 v[18:21], v[152:155], v[208:211], v[18:21]
	s_setprio 0
	s_setprio 1
	v_mfma_f32_16x16x32_bf16 v[46:49], v[156:159], v[172:175], v[46:49]
	v_mfma_f32_16x16x32_bf16 v[42:45], v[164:167], v[172:175], v[42:45]
	v_mfma_f32_16x16x32_bf16 v[30:33], v[156:159], v[180:183], v[30:33]
	v_mfma_f32_16x16x32_bf16 v[26:29], v[164:167], v[180:183], v[26:29]
	v_mfma_f32_16x16x32_bf16 v[14:17], v[156:159], v[188:191], v[14:17]
	v_mfma_f32_16x16x32_bf16 v[10:13], v[164:167], v[188:191], v[10:13]
	v_mfma_f32_16x16x32_bf16 v[6:9], v[156:159], v[196:199], v[6:9]
	v_mfma_f32_16x16x32_bf16 v[2:5], v[164:167], v[196:199], v[2:5]
	v_mfma_f32_16x16x32_bf16 v[46:49], v[160:163], v[176:179], v[46:49]
	v_mfma_f32_16x16x32_bf16 v[42:45], v[168:171], v[176:179], v[42:45]
	v_mfma_f32_16x16x32_bf16 v[30:33], v[160:163], v[184:187], v[30:33]
	v_mfma_f32_16x16x32_bf16 v[26:29], v[168:171], v[184:187], v[26:29]
	v_mfma_f32_16x16x32_bf16 v[14:17], v[160:163], v[192:195], v[14:17]
	v_mfma_f32_16x16x32_bf16 v[10:13], v[168:171], v[192:195], v[10:13]
	v_mfma_f32_16x16x32_bf16 v[6:9], v[160:163], v[208:211], v[6:9]
	v_mfma_f32_16x16x32_bf16 v[2:5], v[168:171], v[208:211], v[2:5]
	s_barrier
	s_setprio 0
	s_add_i32 s14, 0, 0x18000
	s_add_i32 s15, 0, 0x1c000
	v_add_u32_e32 v152, s14, v136
	v_add_u32_e32 v168, s15, v136
	ds_read_b128 v[140:143], v152
	ds_read_b128 v[144:147], v152 offset:1024
	ds_read_b128 v[148:151], v152 offset:2048
	ds_read_b128 v[152:155], v152 offset:3072
	ds_read_b128 v[156:159], v168
	ds_read_b128 v[160:163], v168 offset:1024
	ds_read_b128 v[164:167], v168 offset:2048
	ds_read_b128 v[168:171], v168 offset:3072
	s_add_u32 s0, s20, 0x160000
	s_addc_u32 s1, s21, 0
	s_mov_b32 m0, s27
	ds_read_b128 v[172:175], v139 offset:32768
	ds_read_b128 v[176:179], v139 offset:33792
	ds_read_b128 v[180:183], v139 offset:34816
	ds_read_b128 v[184:187], v139 offset:35840
	ds_read_b128 v[188:191], v139 offset:36864
	ds_read_b128 v[192:195], v139 offset:37888
	ds_read_b128 v[196:199], v139 offset:38912
	ds_read_b128 v[208:211], v139 offset:39936
	global_load_lds_dwordx4 v202, s[0:1]
	s_mov_b32 m0, s28
	s_nop 0
	global_load_lds_dwordx4 v130, s[0:1]
	s_waitcnt vmcnt(8)
	s_waitcnt lgkmcnt(0)
	s_setprio 1
	s_barrier
	v_mfma_f32_16x16x32_bf16 v[126:129], v[140:143], v[172:175], v[126:129]
	v_mfma_f32_16x16x32_bf16 v[122:125], v[148:151], v[172:175], v[122:125]
	v_mfma_f32_16x16x32_bf16 v[118:121], v[140:143], v[180:183], v[118:121]
	v_mfma_f32_16x16x32_bf16 v[114:117], v[148:151], v[180:183], v[114:117]
	v_mfma_f32_16x16x32_bf16 v[106:109], v[140:143], v[188:191], v[106:109]
	v_mfma_f32_16x16x32_bf16 v[98:101], v[148:151], v[188:191], v[98:101]
	v_mfma_f32_16x16x32_bf16 v[90:93], v[140:143], v[196:199], v[90:93]
	v_mfma_f32_16x16x32_bf16 v[82:85], v[148:151], v[196:199], v[82:85]
	v_mfma_f32_16x16x32_bf16 v[126:129], v[144:147], v[176:179], v[126:129]
	v_mfma_f32_16x16x32_bf16 v[122:125], v[152:155], v[176:179], v[122:125]
	v_mfma_f32_16x16x32_bf16 v[118:121], v[144:147], v[184:187], v[118:121]
	v_mfma_f32_16x16x32_bf16 v[114:117], v[152:155], v[184:187], v[114:117]
	v_mfma_f32_16x16x32_bf16 v[106:109], v[144:147], v[192:195], v[106:109]
	v_mfma_f32_16x16x32_bf16 v[98:101], v[152:155], v[192:195], v[98:101]
	v_mfma_f32_16x16x32_bf16 v[90:93], v[144:147], v[208:211], v[90:93]
	v_mfma_f32_16x16x32_bf16 v[82:85], v[152:155], v[208:211], v[82:85]
	s_setprio 0
	s_setprio 1
	v_mfma_f32_16x16x32_bf16 v[110:113], v[156:159], v[172:175], v[110:113]
	v_mfma_f32_16x16x32_bf16 v[102:105], v[164:167], v[172:175], v[102:105]
	v_mfma_f32_16x16x32_bf16 v[94:97], v[156:159], v[180:183], v[94:97]
	v_mfma_f32_16x16x32_bf16 v[86:89], v[164:167], v[180:183], v[86:89]
	v_mfma_f32_16x16x32_bf16 v[78:81], v[156:159], v[188:191], v[78:81]
	v_mfma_f32_16x16x32_bf16 v[74:77], v[164:167], v[188:191], v[74:77]
	v_mfma_f32_16x16x32_bf16 v[70:73], v[156:159], v[196:199], v[70:73]
	v_mfma_f32_16x16x32_bf16 v[66:69], v[164:167], v[196:199], v[66:69]
	v_mfma_f32_16x16x32_bf16 v[110:113], v[160:163], v[176:179], v[110:113]
	v_mfma_f32_16x16x32_bf16 v[102:105], v[168:171], v[176:179], v[102:105]
	v_mfma_f32_16x16x32_bf16 v[94:97], v[160:163], v[184:187], v[94:97]
	v_mfma_f32_16x16x32_bf16 v[86:89], v[168:171], v[184:187], v[86:89]
	v_mfma_f32_16x16x32_bf16 v[78:81], v[160:163], v[192:195], v[78:81]
	v_mfma_f32_16x16x32_bf16 v[74:77], v[168:171], v[192:195], v[74:77]
	v_mfma_f32_16x16x32_bf16 v[70:73], v[160:163], v[208:211], v[70:73]
	v_mfma_f32_16x16x32_bf16 v[66:69], v[168:171], v[208:211], v[66:69]
	s_barrier
	s_setprio 0
	s_add_i32 s0, s14, s22
	s_add_u32 s100, s18, 0x80
	s_addc_u32 s101, s19, 0
	s_mov_b32 m0, s0
	ds_read_b128 v[172:175], v139 offset:49152
	ds_read_b128 v[176:179], v139 offset:50176
	ds_read_b128 v[180:183], v139 offset:51200
	ds_read_b128 v[184:187], v139 offset:52224
	ds_read_b128 v[188:191], v139 offset:53248
	ds_read_b128 v[192:195], v139 offset:54272
	ds_read_b128 v[196:199], v139 offset:55296
	ds_read_b128 v[208:211], v139 offset:56320
	global_load_lds_dwordx4 v202, s[100:101]
	s_add_i32 m0, s0, 0x2000
	s_add_u32 s100, s18, 0x80
	s_addc_u32 s101, s19, 0
	s_add_u32 s0, s18, 0x160080
	s_addc_u32 s1, s19, 0
	s_add_i32 s14, s15, s22
	global_load_lds_dwordx4 v130, s[100:101]
	s_mov_b32 m0, s14
	s_nop 0
	global_load_lds_dwordx4 v202, s[0:1]
	s_add_i32 m0, s14, 0x2000
	s_nop 0
	global_load_lds_dwordx4 v130, s[0:1]
	s_add_u32 s100, s20, 0x80
	s_addc_u32 s101, s21, 0
	s_mov_b32 m0, s29
	s_nop 0
	global_load_lds_dwordx4 v202, s[100:101]
	s_add_u32 s100, s20, 0x80
	s_addc_u32 s101, s21, 0
	s_mov_b32 m0, s30
	s_nop 0
	global_load_lds_dwordx4 v130, s[100:101]
	s_waitcnt vmcnt(8)
	s_waitcnt lgkmcnt(0)
	s_setprio 1
	s_barrier
	v_mfma_f32_16x16x32_bf16 v[62:65], v[140:143], v[172:175], v[62:65]
	v_mfma_f32_16x16x32_bf16 v[58:61], v[148:151], v[172:175], v[58:61]
	v_mfma_f32_16x16x32_bf16 v[54:57], v[140:143], v[180:183], v[54:57]
	v_mfma_f32_16x16x32_bf16 v[50:53], v[148:151], v[180:183], v[50:53]
	v_mfma_f32_16x16x32_bf16 v[38:41], v[140:143], v[188:191], v[38:41]
	v_mfma_f32_16x16x32_bf16 v[34:37], v[148:151], v[188:191], v[34:37]
	v_mfma_f32_16x16x32_bf16 v[22:25], v[140:143], v[196:199], v[22:25]
	v_mfma_f32_16x16x32_bf16 v[18:21], v[148:151], v[196:199], v[18:21]
	v_mfma_f32_16x16x32_bf16 v[62:65], v[144:147], v[176:179], v[62:65]
	v_mfma_f32_16x16x32_bf16 v[58:61], v[152:155], v[176:179], v[58:61]
	v_mfma_f32_16x16x32_bf16 v[54:57], v[144:147], v[184:187], v[54:57]
	v_mfma_f32_16x16x32_bf16 v[50:53], v[152:155], v[184:187], v[50:53]
	v_mfma_f32_16x16x32_bf16 v[38:41], v[144:147], v[192:195], v[38:41]
	v_mfma_f32_16x16x32_bf16 v[34:37], v[152:155], v[192:195], v[34:37]
	v_mfma_f32_16x16x32_bf16 v[22:25], v[144:147], v[208:211], v[22:25]
	v_mfma_f32_16x16x32_bf16 v[18:21], v[152:155], v[208:211], v[18:21]
	s_setprio 0
	s_setprio 1
	v_mfma_f32_16x16x32_bf16 v[46:49], v[156:159], v[172:175], v[46:49]
	v_mfma_f32_16x16x32_bf16 v[42:45], v[164:167], v[172:175], v[42:45]
	v_mfma_f32_16x16x32_bf16 v[30:33], v[156:159], v[180:183], v[30:33]
	v_mfma_f32_16x16x32_bf16 v[26:29], v[164:167], v[180:183], v[26:29]
	v_mfma_f32_16x16x32_bf16 v[14:17], v[156:159], v[188:191], v[14:17]
	v_mfma_f32_16x16x32_bf16 v[10:13], v[164:167], v[188:191], v[10:13]
	v_mfma_f32_16x16x32_bf16 v[6:9], v[156:159], v[196:199], v[6:9]
	v_mfma_f32_16x16x32_bf16 v[2:5], v[164:167], v[196:199], v[2:5]
	v_mfma_f32_16x16x32_bf16 v[46:49], v[160:163], v[176:179], v[46:49]
	v_mfma_f32_16x16x32_bf16 v[42:45], v[168:171], v[176:179], v[42:45]
	v_mfma_f32_16x16x32_bf16 v[30:33], v[160:163], v[184:187], v[30:33]
	v_mfma_f32_16x16x32_bf16 v[26:29], v[168:171], v[184:187], v[26:29]
	v_mfma_f32_16x16x32_bf16 v[14:17], v[160:163], v[192:195], v[14:17]
	v_mfma_f32_16x16x32_bf16 v[10:13], v[168:171], v[192:195], v[10:13]
	v_mfma_f32_16x16x32_bf16 v[6:9], v[160:163], v[208:211], v[6:9]
	v_mfma_f32_16x16x32_bf16 v[2:5], v[168:171], v[208:211], v[2:5]
	s_barrier
	s_setprio 0
	s_add_i32 s49, s49, 2
	s_add_u32 s40, s40, 0x100
	s_addc_u32 s41, s41, 0
	s_cmp_gt_u32 s49, 5
	s_mov_b64 s[14:15], s[16:17]
	s_cbranch_scc0 .LBB0_1739
	s_and_b64 vcc, exec, s[6:7]
	s_cbranch_vccz .LBB0_1742
	s_barrier

	.amdhsa_kernel _Z10fwd_kernel4Args
		.amdhsa_group_segment_fixed_size 0
		.amdhsa_private_segment_fixed_size 0
		.amdhsa_kernarg_size 504
		.amdhsa_user_sgpr_count 2
		.amdhsa_user_sgpr_dispatch_ptr 0
		.amdhsa_user_sgpr_queue_ptr 0
		.amdhsa_user_sgpr_kernarg_segment_ptr 1
		.amdhsa_user_sgpr_dispatch_id 0
		.amdhsa_user_sgpr_kernarg_preload_length 0
		.amdhsa_user_sgpr_kernarg_preload_offset 0
		.amdhsa_user_sgpr_private_segment_size 0
		.amdhsa_uses_dynamic_stack 0
		.amdhsa_enable_private_segment 0
		.amdhsa_system_sgpr_workgroup_id_x 1
		.amdhsa_system_sgpr_workgroup_id_y 0
		.amdhsa_system_sgpr_workgroup_id_z 0
		.amdhsa_system_sgpr_workgroup_info 0
		.amdhsa_system_vgpr_workitem_id 0
		.amdhsa_next_free_vgpr 256
		.amdhsa_next_free_sgpr 102
		.amdhsa_accum_offset 256
		.amdhsa_reserve_vcc 1
		.amdhsa_float_round_mode_32 0
		.amdhsa_float_round_mode_16_64 0
		.amdhsa_float_denorm_mode_32 3
		.amdhsa_float_denorm_mode_16_64 3
		.amdhsa_dx10_clamp 1
		.amdhsa_ieee_mode 1
		.amdhsa_fp16_overflow 0
		.amdhsa_tg_split 0
		.amdhsa_exception_fp_ieee_invalid_op 0
		.amdhsa_exception_fp_denorm_src 0
		.amdhsa_exception_fp_ieee_div_zero 0
		.amdhsa_exception_fp_ieee_overflow 0
		.amdhsa_exception_fp_ieee_underflow 0
		.amdhsa_exception_fp_ieee_inexact 0
		.amdhsa_exception_int_div_zero 0
	.end_amdhsa_kernel

amdhsa.kernels:
  - .agpr_count:     0
    .args:
      - .offset:         0
        .size:           248
        .value_kind:     by_value
      - .offset:         248
        .size:           4
        .value_kind:     hidden_block_count_x
      - .offset:         252
        .size:           4
        .value_kind:     hidden_block_count_y
      - .offset:         256
        .size:           4
        .value_kind:     hidden_block_count_z
      - .offset:         260
        .size:           2
        .value_kind:     hidden_group_size_x
      - .offset:         262
        .size:           2
        .value_kind:     hidden_group_size_y
      - .offset:         264
        .size:           2
        .value_kind:     hidden_group_size_z
      - .offset:         266
        .size:           2
        .value_kind:     hidden_remainder_x
      - .offset:         268
        .size:           2
        .value_kind:     hidden_remainder_y
      - .offset:         270
        .size:           2
        .value_kind:     hidden_remainder_z
      - .offset:         288
        .size:           8
        .value_kind:     hidden_global_offset_x
      - .offset:         296
        .size:           8
        .value_kind:     hidden_global_offset_y
      - .offset:         304
        .size:           8
        .value_kind:     hidden_global_offset_z
      - .offset:         312
        .size:           2
        .value_kind:     hidden_grid_dims
      - .offset:         368
        .size:           4
        .value_kind:     hidden_dynamic_lds_size
    .group_segment_fixed_size: 0
    .kernarg_segment_align: 8
    .kernarg_segment_size: 504
    .language:       OpenCL C
    .language_version:
      - 2
      - 0
    .max_flat_workgroup_size: 512
    .name:           _Z10fwd_kernel4Args
    .private_segment_fixed_size: 0
    .sgpr_count:     108
    .sgpr_spill_count: 284
    .symbol:         _Z10fwd_kernel4Args.kd
    .uniform_work_group_size: 1
    .uses_dynamic_stack: false
    .vgpr_count:     256
    .vgpr_spill_count: 0
    .wavefront_size: 64
